# packed fp32 op split extended to the scan and the E1/E5/E5B GEMM phases
# baseline (speedup 1.0000x reference)
; DI bf16_t f2bf(float x) { return (bf16_t)(cvt_pk(x, 0.f) & 0xffffu); }
;     ...
;         } else {
;             const int oc = (seg == 0 ? 0 : seg == 1 ? 512 : seg == 3 ? 1024 : 1536) + cs;
;             bf16_t* d = (bf16_t*)(p.ws + OFF_PQK) + (size_t)row0 * 2048 + oc;
; #pragma unroll
;             for (int e = 0; e < 4; ++e) d[(size_t)e * 2048] = f2bf(v[e]);
;         }
; template <int EPI, int K, int LNI>
; DI void gemm_tail_unit(const Params& p, const bf16_t* __restrict__ A, const bf16_t* __restrict__ Bt, const int un, float* s_aux) {
;     ...
;     {
;         const int tile = w >> 1, i = tile >> 1, j = tile & 1;
; #pragma unroll
;         for (int gg = 0; gg < 2; ++gg) {
;             const int g = 2 * (w & 1) + gg;
;             float v[4];
; #pragma unroll
;             for (int e = 0; e < 4; ++e) {
;                 float sacc = 0.f;
; #pragma unroll
;                 for (int wv = 0; wv < 8; ++wv) sacc += red[((wv * 4 + tile) * 16 + 4 * g + e) * 64 + lane];
;                 v[e] = sacc;
;             }
.LBB0_406:
	s_waitcnt lgkmcnt(14)
	v_pk_add_f32 v[28:29], v[28:29], 0 op_sel_hi:[1,0]
	v_ashrrev_i32_e32 v37, 3, v67
	v_add_f32_e64 v24, v28, v24
	v_add_f32_e64 v25, v29, v25
	v_lshlrev_b32_e32 v40, 2, v68
	s_waitcnt lgkmcnt(11)
	v_add_f32_e64 v24, v24, v30
	v_add_f32_e64 v25, v25, v31
	v_lshlrev_b32_e32 v36, 5, v36
	s_waitcnt lgkmcnt(10)
	v_add_f32_e64 v24, v24, v26
	v_add_f32_e64 v25, v25, v27
	v_and_or_b32 v37, v37, s14, v40
	v_add_f32_e64 v8, v24, v8
	v_add_f32_e64 v9, v25, v9
	v_and_b32_e32 v36, 32, v36
	v_add_f32_e64 v4, v8, v4
	v_add_f32_e64 v5, v9, v5
	s_and_b32 s8, s3, 0x1c0
	v_add_f32_e64 v2, v4, v2
	v_add_f32_e64 v3, v5, v3
	v_add_u32_e32 v37, 0x8000, v37
	v_add_f32_e64 v0, v2, v0
	v_add_f32_e64 v1, v3, v1
	v_pk_add_f32 v[2:3], v[12:13], 0 op_sel_hi:[1,0]
	v_or3_b32 v40, s8, v36, v66
	v_add_f32_e64 v2, v2, v6
	v_add_f32_e64 v3, v3, v7
	v_or_b32_e32 v36, s21, v40
	s_waitcnt lgkmcnt(8)
	v_add_f32_e64 v2, v2, v14
	v_add_f32_e64 v3, v3, v15
	s_andn2_b64 vcc, exec, s[6:7]
	v_add_f32_e64 v2, v2, v10
	v_add_f32_e64 v3, v3, v11
	v_lshl_or_b32 v4, v38, 3, v37
	s_waitcnt lgkmcnt(3)
	v_add_f32_e64 v2, v2, v22
	v_add_f32_e64 v3, v3, v23
	s_waitcnt lgkmcnt(2)
	v_add_f32_e64 v2, v2, v20
	v_add_f32_e64 v3, v3, v21
	s_waitcnt lgkmcnt(1)
	v_add_f32_e64 v2, v2, v18
	v_add_f32_e64 v3, v3, v19
	s_waitcnt lgkmcnt(0)
	v_add_f32_e64 v2, v2, v16
	v_add_f32_e64 v3, v3, v17
	s_cbranch_vccnz .LBB0_408
	v_ashrrev_i32_e32 v5, 31, v4
	v_lshlrev_b64 v[6:7], 12, v[4:5]
	v_lshl_add_u64 v[6:7], s[36:37], 0, v[6:7]
	v_lshlrev_b32_e32 v64, 1, v36
	v_lshl_add_u64 v[6:7], v[6:7], 0, v[64:65]
	v_cvt_pk_bf16_f32 v5, v0, s0
	v_add_co_u32_e32 v8, vcc, 0x1000, v6
	global_store_short v[6:7], v5, off
	v_cvt_pk_bf16_f32 v5, v1, s0
	v_addc_co_u32_e32 v9, vcc, 0, v7, vcc
	global_store_short v[8:9], v5, off
	v_add_co_u32_e32 v8, vcc, 0x2000, v6
	v_cvt_pk_bf16_f32 v5, v2, s0
	s_nop 0
	v_addc_co_u32_e32 v9, vcc, 0, v7, vcc
	v_add_co_u32_e32 v6, vcc, 0x3000, v6
	global_store_short v[8:9], v5, off
	v_cvt_pk_bf16_f32 v5, v3, s0
	v_addc_co_u32_e32 v7, vcc, 0, v7, vcc
	global_store_short v[6:7], v5, off
	s_mov_b64 s[4:5], 0

; DI bf16_t f2bf(float x) { return (bf16_t)(cvt_pk(x, 0.f) & 0xffffu); }
;     ...
;         } else {
;             const int oc = (seg == 0 ? 0 : seg == 1 ? 512 : seg == 3 ? 1024 : 1536) + cs;
;             bf16_t* d = (bf16_t*)(p.ws + OFF_PQK) + (size_t)row0 * 2048 + oc;
; #pragma unroll
;             for (int e = 0; e < 4; ++e) d[(size_t)e * 2048] = f2bf(v[e]);
;         }
; template <int EPI, int K, int LNI>
; DI void gemm_tail_unit(const Params& p, const bf16_t* __restrict__ A, const bf16_t* __restrict__ Bt, const int un, float* s_aux) {
;     ...
; #pragma unroll
;             for (int e = 0; e < 4; ++e) {
;                 float sacc = 0.f;
; #pragma unroll
;                 for (int wv = 0; wv < 8; ++wv) sacc += red[((wv * 4 + tile) * 16 + 4 * g + e) * 64 + lane];
;                 v[e] = sacc;
;             }
.LBB0_414:
	s_waitcnt lgkmcnt(14)
	v_pk_add_f32 v[28:29], v[28:29], 0 op_sel_hi:[1,0]
	s_andn2_b64 vcc, exec, s[6:7]
	v_add_f32_e64 v24, v28, v24
	v_add_f32_e64 v25, v29, v25
	s_waitcnt lgkmcnt(11)
	v_add_f32_e64 v24, v24, v30
	v_add_f32_e64 v25, v25, v31
	s_waitcnt lgkmcnt(10)
	v_add_f32_e64 v24, v24, v26
	v_add_f32_e64 v25, v25, v27
	s_nop 0
	v_add_f32_e64 v8, v24, v8
	v_add_f32_e64 v9, v25, v9
	s_nop 0
	v_add_f32_e64 v4, v8, v4
	v_add_f32_e64 v5, v9, v5
	s_nop 0
	v_add_f32_e64 v2, v4, v2
	v_add_f32_e64 v3, v5, v3
	v_lshl_or_b32 v4, v38, 3, v37
	v_add_f32_e64 v0, v2, v0
	v_add_f32_e64 v1, v3, v1
	v_pk_add_f32 v[2:3], v[12:13], 0 op_sel_hi:[1,0]
	s_nop 0
	v_add_f32_e64 v2, v2, v6
	v_add_f32_e64 v3, v3, v7
	s_waitcnt lgkmcnt(8)
	v_add_f32_e64 v2, v2, v14
	v_add_f32_e64 v3, v3, v15
	s_nop 0
	v_add_f32_e64 v2, v2, v10
	v_add_f32_e64 v3, v3, v11
	s_waitcnt lgkmcnt(3)
	v_add_f32_e64 v2, v2, v22
	v_add_f32_e64 v3, v3, v23
	s_waitcnt lgkmcnt(2)
	v_add_f32_e64 v2, v2, v20
	v_add_f32_e64 v3, v3, v21
	s_waitcnt lgkmcnt(1)
	v_add_f32_e64 v2, v2, v18
	v_add_f32_e64 v3, v3, v19
	s_waitcnt lgkmcnt(0)
	v_add_f32_e64 v2, v2, v16
	v_add_f32_e64 v3, v3, v17
	s_cbranch_vccnz .LBB0_416
	v_ashrrev_i32_e32 v5, 31, v4
	v_lshlrev_b64 v[6:7], 12, v[4:5]
	v_lshl_add_u64 v[6:7], s[36:37], 0, v[6:7]
	v_lshlrev_b32_e32 v8, 1, v36
	v_mov_b32_e32 v9, v65
	v_lshl_add_u64 v[6:7], v[6:7], 0, v[8:9]
	v_cvt_pk_bf16_f32 v5, v0, s0
	v_add_co_u32_e32 v8, vcc, 0x1000, v6
	global_store_short v[6:7], v5, off
	v_cvt_pk_bf16_f32 v5, v1, s0
	v_addc_co_u32_e32 v9, vcc, 0, v7, vcc
	global_store_short v[8:9], v5, off
	v_add_co_u32_e32 v8, vcc, 0x2000, v6
	v_cvt_pk_bf16_f32 v5, v2, s0
	s_nop 0
	v_addc_co_u32_e32 v9, vcc, 0, v7, vcc
	v_add_co_u32_e32 v6, vcc, 0x3000, v6
	global_store_short v[8:9], v5, off
	v_cvt_pk_bf16_f32 v5, v3, s0
	v_addc_co_u32_e32 v7, vcc, 0, v7, vcc
	global_store_short v[6:7], v5, off
	s_mov_b64 s[4:5], 0

; DI unsigned cvt_pk(float lo, float hi) { f32x2 v = {lo, hi}; bf16x2v b = __builtin_convertvector(v, bf16x2v); return __builtin_bit_cast(unsigned, b); }
; DI bf16_t f2bf(float x) { return (bf16_t)(cvt_pk(x, 0.f) & 0xffffu); }
; DI float ex2(float x) { return __builtin_amdgcn_exp2f(x); }
; DI size_t qf_off(int item, int i, int dk) { return ((size_t)(((item * 8 + (dk >> 5)) * 2 + ((dk >> 4) & 1)) * 2 + (i >> 5)) * 64 + ((dk >> 3) & 1) * 32 + (i & 31)) * 8 + (dk & 7); }
; DI size_t kf_off(int item, int dk, int j) { return ((size_t)((item * 8 + (dk >> 5)) * 4 + (j >> 4)) * 64 + ((j >> 3) & 1) * 32 + perm23(dk & 31)) * 8 + (j & 7); }
;     ...
;     } else if (EPI == EPI_E5) {
;         const int idx = (pos + 48) & 63, ch = (pos + 48) >> 6;
;         if (col < 1024) {
;             const int hd = col >> 8, item = (ch * 4 + b) * 4 + hd;
;             bf16_t* d = (bf16_t*)((unsigned char*)p.out + OFFO_QHAT) + qf_off(item, idx, col & 255);
; #pragma unroll
;             for (int e = 0; e < 4; ++e) d[e * 8] = f2bf(v[e] * rs[e][0]);
;         } else if (col < 2048) {
;             const int c = col - 1024, hd = c >> 8, item = (ch * 4 + b) * 4 + hd;
;             bf16_t* d = (bf16_t*)(p.ws + OFF_KHAT) + (size_t)row0 * 1024 + c;
; #pragma unroll
;             for (int e = 0; e < 4; ++e) { v[e] *= rs[e][1]; d[(size_t)e * 1024] = f2bf(v[e]); }
;             u32x2 wv; wv[0] = cvt_pk(v[0], v[1]); wv[1] = cvt_pk(v[2], v[3]);
;             *(u32x2*)((bf16_t*)(p.ws + OFF_KHATT) + kf_off(item, c & 255, idx)) = wv;
;         } else {
;             const int c = col - 2048, hd = c >> 9, item = (ch * 4 + b) * 4 + hd;
;             u32x2 wv; wv[0] = cvt_pk(v[0], v[1]); wv[1] = cvt_pk(v[2], v[3]);
;             *(u32x2*)((bf16_t*)(p.ws + OFF_VT1) + vf_off(item, c & 511, idx)) = wv;
;         }
; template <int EPI, int K, int LNI = -1>
; DI void ph_gemm(const Params& p, const bf16_t* __restrict__ A, const bf16_t* __restrict__ Bt, int N, float* s_aux) {
;     ...
;                     if (EPI == EPI_E5) {
;                         const int idx_ = ((row0 % LT) + 48) & 63; const float lgh = lg_[0][0];
; #pragma unroll
;                         for (int e = 0; e < 4; ++e) rs[e] = (f32x2){ex2(lgh * (float)(idx_ + e + 1)), 0.0625f * ex2(lgh * (float)(63 - idx_ - e))};
;                     }
.LBB0_1147:
	s_or_b64 exec, exec, s[12:13]
	s_and_b32 s9, s8, 3
	v_cvt_f32_ubyte0_e32 v132, s9
	v_sub_f32_e32 v132, 0xc0a00000, v132
	v_exp_f32_e32 v132, v132
	v_lshl_add_u32 v138, s10, 8, v163
	v_mov_b32_e32 v139, 0
	v_sub_f32_e32 v132, 1.0, v132
	v_cmp_gt_f32_e32 vcc, s72, v132
	s_and_b64 s[10:11], vcc, exec
	s_cselect_b32 s9, 32, 0
	v_ldexp_f32 v132, v132, s9
	v_log_f32_e32 v132, v132
	v_cndmask_b32_e32 v140, 0, v175, vcc
	v_add_u32_e32 v138, v138, v139
	v_lshl_or_b32 v141, s8, 8, v164
	v_sub_f32_e32 v179, v132, v140
	v_mul_hi_i32 v132, v138, s73
	v_lshrrev_b32_e32 v140, 31, v132
	v_ashrrev_i32_e32 v132, 12, v132
	v_add_u32_e32 v132, v132, v140
	v_mul_i32_i24_e32 v140, 0x2010, v132
	v_sub_u32_e32 v140, v138, v140
	v_add_u32_e32 v140, 48, v140
	v_and_b32_e32 v180, 63, v140
	v_add_u32_e32 v176, v141, v139
	v_sub_u32_e32 v141, 62, v180
	v_cvt_f32_i32_e32 v141, v141
	v_bitop3_b32 v140, v140, 63, v140 bitop3:0xc
	v_cvt_f32_ubyte0_e32 v140, v140
	v_mul_f32_e32 v140, v179, v140
	v_mul_f32_e32 v141, v179, v141
	v_exp_f32_e32 v140, v140
	v_exp_f32_e32 v141, v141
	v_sub_u32_e32 v142, 61, v180
	v_sub_u32_e32 v143, 60, v180
	v_cvt_f32_i32_e32 v142, v142
	v_cvt_f32_i32_e32 v143, v143
	v_mul_f32_e64 v144, v140, s44
	v_mul_f32_e64 v145, v141, s44
	v_add_u32_e32 v140, 48, v138
	v_add_u32_e32 v139, v139, v162
	v_mad_i32_i24 v181, v132, s74, v140
	v_mul_f32_e32 v142, v179, v142
	v_mul_f32_e32 v143, v179, v143
	v_and_b32_e32 v178, 31, v139
	v_ashrrev_i32_e32 v182, 6, v181
	v_lshlrev_b32_e32 v139, 8, v132
	v_exp_f32_e32 v142, v142
	v_exp_f32_e32 v143, v143
	v_lshl_add_u32 v139, v182, 10, v139
	v_bfe_u32 v184, v181, 4, 2
	v_or_b32_e32 v183, v139, v184
	v_lshlrev_b32_e32 v139, 2, v181
	v_and_b32_e32 v141, 32, v139
	v_ashrrev_i32_e32 v139, 31, v138
	v_lshlrev_b32_e32 v132, 7, v132
	v_lshlrev_b64 v[146:147], 11, v[138:139]
	v_lshl_add_u32 v139, v182, 9, v132
	v_mul_f32_e64 v142, v142, s44
	v_mul_f32_e64 v143, v143, s44
	v_and_b32_e32 v177, 7, v138
	v_or_b32_e32 v182, v139, v184
	v_cmp_lt_i32_e64 s[12:13], s75, v176
	s_and_saveexec_b64 s[8:9], s[12:13]
	s_xor_b64 s[8:9], exec, s[8:9]
	s_cbranch_execz .LBB0_1153
	v_cmp_lt_u32_e32 vcc, s71, v176
	s_and_saveexec_b64 s[10:11], vcc
	s_xor_b64 s[10:11], exec, s[10:11]
	s_cbranch_execz .LBB0_1150
	v_add_u32_e32 v132, 0xfffff800, v176
	v_lshrrev_b32_e32 v186, 3, v176
	v_lshrrev_b32_e32 v132, 3, v132
	v_and_b32_e32 v186, 60, v186
	v_and_or_b32 v132, v132, s76, v186
	v_add_u32_e32 v186, v132, v183
	v_ashrrev_i32_e32 v187, 31, v186
	v_lshlrev_b64 v[186:187], 6, v[186:187]
	v_or_b32_e32 v132, v186, v178
	v_or_b32_e32 v186, v132, v141
	v_lshl_add_u64 v[186:187], v[186:187], 4, s[20:21]
	v_lshlrev_b32_e32 v132, 1, v177
	v_cvt_pk_bf16_f32 v184, v124, v125
	v_cvt_pk_bf16_f32 v185, v126, v127
	v_lshl_add_u64 v[186:187], v[186:187], 0, v[132:133]
	global_store_dwordx2 v[186:187], v[184:185], off
.LBB0_1150:
	s_andn2_saveexec_b64 s[10:11], s[10:11]
	s_cbranch_execz .LBB0_1152
	v_add_u32_e32 v132, 0xfffffc00, v176
	v_lshl_add_u64 v[184:185], s[36:37], 0, v[146:147]
	v_mul_f32_e64 v186, v124, v144
	v_mul_f32_e64 v187, v125, v145
	v_lshl_add_u64 v[184:185], v[132:133], 1, v[184:185]
	v_cvt_pk_bf16_f32 v188, v186, s0
	global_store_short v[184:185], v188, off
	v_cvt_pk_bf16_f32 v188, v187, s0
	global_store_short v[184:185], v188, off offset:2048
	v_mul_f32_e64 v188, v126, v142
	v_mul_f32_e64 v189, v127, v143
	v_add_co_u32_e32 v184, vcc, s35, v184
	v_cvt_pk_bf16_f32 v190, v188, s0
	s_nop 0
	v_addc_co_u32_e32 v185, vcc, 0, v185, vcc
	global_store_short v[184:185], v190, off
	v_cvt_pk_bf16_f32 v190, v189, s0
	global_store_short v[184:185], v190, off offset:2048
	v_cvt_pk_bf16_f32 v184, v186, v187
	v_lshrrev_b32_e32 v186, 3, v176
	v_lshrrev_b32_e32 v132, 3, v132
	v_and_b32_e32 v186, 28, v186
	v_and_or_b32 v132, v132, s77, v186
	v_cvt_pk_bf16_f32 v185, v188, v189
	v_add_u32_e32 v186, v132, v182
	v_and_b32_e32 v132, 19, v176
	v_lshlrev_b32_e32 v188, 1, v176
	v_ashrrev_i32_e32 v187, 31, v186
	v_and_or_b32 v132, v188, 8, v132
	v_lshrrev_b32_e32 v188, 1, v176
	v_lshlrev_b64 v[186:187], 6, v[186:187]
	v_and_b32_e32 v188, 4, v188
	v_or3_b32 v132, v132, v188, v186
	v_or_b32_e32 v186, v132, v141
	v_lshl_add_u64 v[186:187], v[186:187], 4, s[24:25]
	v_lshlrev_b32_e32 v132, 1, v177
	v_lshl_add_u64 v[186:187], v[186:187], 0, v[132:133]
	global_store_dwordx2 v[186:187], v[184:185], off

; DI unsigned cvt_pk(float lo, float hi) { f32x2 v = {lo, hi}; bf16x2v b = __builtin_convertvector(v, bf16x2v); return __builtin_bit_cast(unsigned, b); }
; DI bf16_t f2bf(float x) { return (bf16_t)(cvt_pk(x, 0.f) & 0xffffu); }
; DI size_t kf_off(int item, int dk, int j) { return ((size_t)((item * 8 + (dk >> 5)) * 4 + (j >> 4)) * 64 + ((j >> 3) & 1) * 32 + perm23(dk & 31)) * 8 + (j & 7); }
;     ...
;         } else if (col < 2048) {
;             const int c = col - 1024, hd = c >> 8, item = (ch * 4 + b) * 4 + hd;
;             bf16_t* d = (bf16_t*)(p.ws + OFF_KHAT) + (size_t)row0 * 1024 + c;
; #pragma unroll
;             for (int e = 0; e < 4; ++e) { v[e] *= rs[e][1]; d[(size_t)e * 1024] = f2bf(v[e]); }
;             u32x2 wv; wv[0] = cvt_pk(v[0], v[1]); wv[1] = cvt_pk(v[2], v[3]);
;             *(u32x2*)((bf16_t*)(p.ws + OFF_KHATT) + kf_off(item, c & 255, idx)) = wv;
.LBB0_1158:
	s_andn2_saveexec_b64 s[10:11], s[10:11]
	s_cbranch_execz .LBB0_1160
	v_add_u32_e32 v126, 0xfffffc10, v176
	v_lshl_add_u64 v[190:191], s[36:37], 0, v[146:147]
	v_mov_b32_e32 v127, v133
	v_mul_f32_e64 v192, v120, v144
	v_mul_f32_e64 v193, v121, v145
	v_lshl_add_u64 v[190:191], v[126:127], 1, v[190:191]
	v_cvt_pk_bf16_f32 v125, v192, s0
	global_store_short v[190:191], v125, off
	v_cvt_pk_bf16_f32 v125, v193, s0
	global_store_short v[190:191], v125, off offset:2048
	v_mul_f32_e64 v194, v122, v142
	v_mul_f32_e64 v195, v123, v143
	v_add_co_u32_e32 v190, vcc, s35, v190
	v_cvt_pk_bf16_f32 v125, v194, s0
	s_nop 0
	v_addc_co_u32_e32 v191, vcc, 0, v191, vcc
	global_store_short v[190:191], v125, off
	v_cvt_pk_bf16_f32 v125, v195, s0
	global_store_short v[190:191], v125, off offset:2048
	v_lshrrev_b32_e32 v125, 3, v126
	v_lshrrev_b32_e32 v126, 3, v124
	v_and_b32_e32 v126, 28, v126
	v_and_or_b32 v125, v125, s77, v126
	v_add_u32_e32 v126, v125, v182
	v_cvt_pk_bf16_f32 v190, v192, v193
	v_ashrrev_i32_e32 v127, 31, v126
	v_and_b32_e32 v125, 19, v124
	v_lshlrev_b32_e32 v192, 1, v124
	v_lshrrev_b32_e32 v193, 1, v176
	v_lshlrev_b64 v[126:127], 6, v[126:127]
	v_and_b32_e32 v192, 8, v192
	v_and_or_b32 v125, v193, 4, v125
	v_or3_b32 v125, v125, v192, v126
	v_or_b32_e32 v126, v125, v141
	v_lshl_add_u64 v[126:127], v[126:127], 4, s[24:25]
	v_lshlrev_b32_e32 v192, 1, v177
	v_mov_b32_e32 v193, v133
	v_cvt_pk_bf16_f32 v191, v194, v195
	v_lshl_add_u64 v[126:127], v[126:127], 0, v[192:193]
	global_store_dwordx2 v[126:127], v[190:191], off

; DI unsigned cvt_pk(float lo, float hi) { f32x2 v = {lo, hi}; bf16x2v b = __builtin_convertvector(v, bf16x2v); return __builtin_bit_cast(unsigned, b); }
; DI bf16_t f2bf(float x) { return (bf16_t)(cvt_pk(x, 0.f) & 0xffffu); }
; DI size_t kf_off(int item, int dk, int j) { return ((size_t)((item * 8 + (dk >> 5)) * 4 + (j >> 4)) * 64 + ((j >> 3) & 1) * 32 + perm23(dk & 31)) * 8 + (j & 7); }
;     ...
;         } else if (col < 2048) {
;             const int c = col - 1024, hd = c >> 8, item = (ch * 4 + b) * 4 + hd;
;             bf16_t* d = (bf16_t*)(p.ws + OFF_KHAT) + (size_t)row0 * 1024 + c;
; #pragma unroll
;             for (int e = 0; e < 4; ++e) { v[e] *= rs[e][1]; d[(size_t)e * 1024] = f2bf(v[e]); }
;             u32x2 wv; wv[0] = cvt_pk(v[0], v[1]); wv[1] = cvt_pk(v[2], v[3]);
;             *(u32x2*)((bf16_t*)(p.ws + OFF_KHATT) + kf_off(item, c & 255, idx)) = wv;
.LBB0_1166:
	s_andn2_saveexec_b64 s[66:67], s[66:67]
	s_cbranch_execz .LBB0_1168
	v_add_u32_e32 v122, 0xfffffc80, v176
	v_lshl_add_u64 v[190:191], s[36:37], 0, v[146:147]
	v_mov_b32_e32 v123, v133
	v_mul_f32_e64 v192, v116, v144
	v_mul_f32_e64 v193, v117, v145
	v_lshl_add_u64 v[190:191], v[122:123], 1, v[190:191]
	v_cvt_pk_bf16_f32 v121, v192, s0
	global_store_short v[190:191], v121, off
	v_cvt_pk_bf16_f32 v121, v193, s0
	global_store_short v[190:191], v121, off offset:2048
	v_mul_f32_e64 v194, v118, v142
	v_mul_f32_e64 v195, v119, v143
	v_add_co_u32_e32 v190, vcc, s35, v190
	v_cvt_pk_bf16_f32 v121, v194, s0
	s_nop 0
	v_addc_co_u32_e32 v191, vcc, 0, v191, vcc
	global_store_short v[190:191], v121, off
	v_cvt_pk_bf16_f32 v121, v195, s0
	global_store_short v[190:191], v121, off offset:2048
	v_lshrrev_b32_e32 v121, 3, v122
	v_lshrrev_b32_e32 v122, 3, v120
	v_and_b32_e32 v122, 28, v122
	v_and_or_b32 v121, v121, s77, v122
	v_add_u32_e32 v122, v121, v182
	v_cvt_pk_bf16_f32 v190, v192, v193
	v_ashrrev_i32_e32 v123, 31, v122
	v_and_b32_e32 v121, 19, v176
	v_lshlrev_b32_e32 v127, 1, v120
	v_lshrrev_b32_e32 v192, 1, v176
	v_lshlrev_b64 v[122:123], 6, v[122:123]
	v_and_b32_e32 v127, 8, v127
	v_and_or_b32 v121, v192, 4, v121
	v_or3_b32 v121, v121, v127, v122
	v_or_b32_e32 v122, v121, v141
	v_lshl_add_u64 v[122:123], v[122:123], 4, s[24:25]
	v_lshlrev_b32_e32 v192, 1, v177
	v_mov_b32_e32 v193, v133
	v_cvt_pk_bf16_f32 v191, v194, v195
	v_lshl_add_u64 v[122:123], v[122:123], 0, v[192:193]
	global_store_dwordx2 v[122:123], v[190:191], off

; DI unsigned cvt_pk(float lo, float hi) { f32x2 v = {lo, hi}; bf16x2v b = __builtin_convertvector(v, bf16x2v); return __builtin_bit_cast(unsigned, b); }
; DI bf16_t f2bf(float x) { return (bf16_t)(cvt_pk(x, 0.f) & 0xffffu); }
; DI size_t kf_off(int item, int dk, int j) { return ((size_t)((item * 8 + (dk >> 5)) * 4 + (j >> 4)) * 64 + ((j >> 3) & 1) * 32 + perm23(dk & 31)) * 8 + (j & 7); }
;     ...
;         } else if (col < 2048) {
;             const int c = col - 1024, hd = c >> 8, item = (ch * 4 + b) * 4 + hd;
;             bf16_t* d = (bf16_t*)(p.ws + OFF_KHAT) + (size_t)row0 * 1024 + c;
; #pragma unroll
;             for (int e = 0; e < 4; ++e) { v[e] *= rs[e][1]; d[(size_t)e * 1024] = f2bf(v[e]); }
;             u32x2 wv; wv[0] = cvt_pk(v[0], v[1]); wv[1] = cvt_pk(v[2], v[3]);
;             *(u32x2*)((bf16_t*)(p.ws + OFF_KHATT) + kf_off(item, c & 255, idx)) = wv;
.LBB0_1174:
	s_andn2_saveexec_b64 s[68:69], s[68:69]
	s_cbranch_execz .LBB0_1176
	v_add_u32_e32 v116, 0xfffffc90, v176
	v_lshl_add_u64 v[146:147], s[36:37], 0, v[146:147]
	v_mov_b32_e32 v117, v133
	v_mul_f32_e64 v144, v112, v144
	v_mul_f32_e64 v145, v113, v145
	v_lshl_add_u64 v[146:147], v[116:117], 1, v[146:147]
	v_cvt_pk_bf16_f32 v117, v144, s0
	global_store_short v[146:147], v117, off
	v_cvt_pk_bf16_f32 v117, v145, s0
	global_store_short v[146:147], v117, off offset:2048
	v_mul_f32_e64 v142, v114, v142
	v_mul_f32_e64 v143, v115, v143
	v_add_co_u32_e32 v146, vcc, s35, v146
	v_cvt_pk_bf16_f32 v117, v142, s0
	s_nop 0
	v_addc_co_u32_e32 v147, vcc, 0, v147, vcc
	global_store_short v[146:147], v117, off
	v_cvt_pk_bf16_f32 v117, v143, s0
	global_store_short v[146:147], v117, off offset:2048
	v_lshrrev_b32_e32 v117, 3, v118
	v_lshrrev_b32_e32 v116, 3, v116
	v_and_b32_e32 v117, 28, v117
	v_and_or_b32 v116, v116, s77, v117
	v_add_u32_e32 v116, v116, v182
	v_ashrrev_i32_e32 v117, 31, v116
	v_and_b32_e32 v119, 19, v118
	v_lshlrev_b32_e32 v123, 1, v118
	v_lshrrev_b32_e32 v127, 1, v176
	v_lshlrev_b64 v[116:117], 6, v[116:117]
	v_and_b32_e32 v123, 8, v123
	v_and_or_b32 v119, v127, 4, v119
	v_or3_b32 v116, v119, v123, v116
	v_or_b32_e32 v116, v116, v141
	v_cvt_pk_bf16_f32 v144, v144, v145
	v_cvt_pk_bf16_f32 v145, v142, v143
	v_lshl_add_u64 v[116:117], v[116:117], 4, s[24:25]
	v_lshlrev_b32_e32 v142, 1, v177
	v_mov_b32_e32 v143, v133
	v_lshl_add_u64 v[116:117], v[116:117], 0, v[142:143]
	global_store_dwordx2 v[116:117], v[144:145], off

; DI unsigned cvt_pk(float lo, float hi) { f32x2 v = {lo, hi}; bf16x2v b = __builtin_convertvector(v, bf16x2v); return __builtin_bit_cast(unsigned, b); }
; DI bf16_t f2bf(float x) { return (bf16_t)(cvt_pk(x, 0.f) & 0xffffu); }
; DI float ex2(float x) { return __builtin_amdgcn_exp2f(x); }
; DI size_t qf_off(int item, int i, int dk) { return ((size_t)(((item * 8 + (dk >> 5)) * 2 + ((dk >> 4) & 1)) * 2 + (i >> 5)) * 64 + ((dk >> 3) & 1) * 32 + (i & 31)) * 8 + (dk & 7); }
; DI size_t kf_off(int item, int dk, int j) { return ((size_t)((item * 8 + (dk >> 5)) * 4 + (j >> 4)) * 64 + ((j >> 3) & 1) * 32 + perm23(dk & 31)) * 8 + (j & 7); }
;     ...
;     } else if (EPI == EPI_E5) {
;         const int idx = (pos + 48) & 63, ch = (pos + 48) >> 6;
;         if (col < 1024) {
;             const int hd = col >> 8, item = (ch * 4 + b) * 4 + hd;
;             bf16_t* d = (bf16_t*)((unsigned char*)p.out + OFFO_QHAT) + qf_off(item, idx, col & 255);
; #pragma unroll
;             for (int e = 0; e < 4; ++e) d[e * 8] = f2bf(v[e] * rs[e][0]);
;         } else if (col < 2048) {
;             const int c = col - 1024, hd = c >> 8, item = (ch * 4 + b) * 4 + hd;
;             bf16_t* d = (bf16_t*)(p.ws + OFF_KHAT) + (size_t)row0 * 1024 + c;
; #pragma unroll
;             for (int e = 0; e < 4; ++e) { v[e] *= rs[e][1]; d[(size_t)e * 1024] = f2bf(v[e]); }
;             u32x2 wv; wv[0] = cvt_pk(v[0], v[1]); wv[1] = cvt_pk(v[2], v[3]);
;             *(u32x2*)((bf16_t*)(p.ws + OFF_KHATT) + kf_off(item, c & 255, idx)) = wv;
;         } else {
;             const int c = col - 2048, hd = c >> 9, item = (ch * 4 + b) * 4 + hd;
;             u32x2 wv; wv[0] = cvt_pk(v[0], v[1]); wv[1] = cvt_pk(v[2], v[3]);
;             *(u32x2*)((bf16_t*)(p.ws + OFF_VT1) + vf_off(item, c & 511, idx)) = wv;
;         }
; template <int EPI, int K, int LNI = -1>
; DI void ph_gemm(const Params& p, const bf16_t* __restrict__ A, const bf16_t* __restrict__ Bt, int N, float* s_aux) {
;     ...
;                     if (EPI == EPI_E5) {
;                         const int idx_ = ((row0 % LT) + 48) & 63; const float lgh = lg_[0][0];
; #pragma unroll
;                         for (int e = 0; e < 4; ++e) rs[e] = (f32x2){ex2(lgh * (float)(idx_ + e + 1)), 0.0625f * ex2(lgh * (float)(63 - idx_ - e))};
;                     }
.LBB0_1179:
	s_or_b64 exec, exec, s[66:67]
	v_add_u32_e32 v116, 16, v138
	v_mul_hi_i32 v112, v116, s73
	v_lshrrev_b32_e32 v113, 31, v112
	v_ashrrev_i32_e32 v112, 12, v112
	v_add_u32_e32 v141, v112, v113
	v_mul_i32_i24_e32 v112, 0x2010, v141
	v_sub_u32_e32 v112, v116, v112
	v_add_u32_e32 v112, 48, v112
	v_and_b32_e32 v146, 63, v112
	v_sub_u32_e32 v114, 61, v146
	v_sub_u32_e32 v113, 62, v146
	v_cvt_f32_i32_e32 v114, v114
	v_sub_u32_e32 v115, 60, v146
	v_cvt_f32_i32_e32 v113, v113
	v_cvt_f32_i32_e32 v115, v115
	v_bitop3_b32 v112, v112, 63, v112 bitop3:0xc
	v_cvt_f32_ubyte0_e32 v112, v112
	v_mul_f32_e32 v114, v179, v114
	v_mul_f32_e32 v112, v179, v112
	v_mul_f32_e32 v113, v179, v113
	v_exp_f32_e32 v142, v114
	v_mul_f32_e32 v114, v179, v115
	v_exp_f32_e32 v112, v112
	v_exp_f32_e32 v113, v113
	v_exp_f32_e32 v143, v114
	v_mul_i32_i24_e32 v117, 0xffffdff0, v141
	v_add3_u32 v147, v138, v117, 64
	v_mul_f32_e64 v114, v112, s44
	v_mul_f32_e64 v115, v113, s44
	v_mul_f32_e64 v112, v142, s44
	v_mul_f32_e64 v113, v143, s44
	v_ashrrev_i32_e32 v143, 6, v147
	v_lshlrev_b32_e32 v117, 8, v141
	v_lshl_add_u32 v117, v143, 10, v117
	v_bfe_u32 v144, v147, 4, 2
	v_or_b32_e32 v142, v117, v144
	v_lshlrev_b32_e32 v117, 2, v147
	v_lshlrev_b32_e32 v141, 7, v141
	v_and_b32_e32 v127, 32, v117
	v_ashrrev_i32_e32 v117, 31, v116
	v_lshl_add_u32 v182, v143, 9, v141
	v_lshlrev_b64 v[116:117], 11, v[116:117]
	v_or_b32_e32 v141, v182, v144
	s_and_saveexec_b64 s[42:43], s[12:13]
	s_xor_b64 s[66:67], exec, s[42:43]
	s_cbranch_execz .LBB0_1185
	v_cmp_lt_u32_e32 vcc, s71, v176
	s_and_saveexec_b64 s[42:43], vcc
	s_xor_b64 s[68:69], exec, s[42:43]
	s_cbranch_execz .LBB0_1182
	v_add_u32_e32 v143, 0xfffff800, v176
	v_lshrrev_b32_e32 v143, 3, v143
	v_and_b32_e32 v183, 60, v180
	v_and_or_b32 v143, v143, s76, v183
	v_add_u32_e32 v184, v143, v142
	v_ashrrev_i32_e32 v185, 31, v184
	v_lshlrev_b64 v[184:185], 6, v[184:185]
	v_or_b32_e32 v143, v184, v178
	v_or_b32_e32 v184, v143, v127
	v_lshl_add_u64 v[184:185], v[184:185], 4, s[20:21]
	v_lshlrev_b32_e32 v186, 1, v177
	v_mov_b32_e32 v187, v133
	v_cvt_pk_bf16_f32 v144, v108, v109
	v_cvt_pk_bf16_f32 v145, v110, v111
	v_lshl_add_u64 v[184:185], v[184:185], 0, v[186:187]
	global_store_dwordx2 v[184:185], v[144:145], off
.LBB0_1182:
	s_andn2_saveexec_b64 s[68:69], s[68:69]
	s_cbranch_execz .LBB0_1184
	v_add_u32_e32 v144, 0xfffffc00, v176
	v_lshl_add_u64 v[184:185], s[36:37], 0, v[116:117]
	v_mov_b32_e32 v145, v133
	v_mul_f32_e64 v186, v108, v114
	v_mul_f32_e64 v187, v109, v115
	v_lshl_add_u64 v[184:185], v[144:145], 1, v[184:185]
	v_cvt_pk_bf16_f32 v143, v186, s0
	global_store_short v[184:185], v143, off
	v_cvt_pk_bf16_f32 v143, v187, s0
	global_store_short v[184:185], v143, off offset:2048
	v_mul_f32_e64 v188, v110, v112
	v_mul_f32_e64 v189, v111, v113
	v_add_co_u32_e32 v184, vcc, s35, v184
	v_cvt_pk_bf16_f32 v143, v188, s0
	s_nop 0
	v_addc_co_u32_e32 v185, vcc, 0, v185, vcc
	global_store_short v[184:185], v143, off
	v_cvt_pk_bf16_f32 v143, v189, s0
	global_store_short v[184:185], v143, off offset:2048
	v_lshrrev_b32_e32 v143, 3, v144
	v_and_b32_e32 v144, 28, v180
	v_and_or_b32 v143, v143, s77, v144
	v_add_u32_e32 v144, v143, v141
	v_and_b32_e32 v143, 19, v176
	v_lshlrev_b32_e32 v183, 1, v176
	v_ashrrev_i32_e32 v145, 31, v144
	v_and_or_b32 v143, v183, 8, v143
	v_lshrrev_b32_e32 v183, 1, v176
	v_lshlrev_b64 v[144:145], 6, v[144:145]
	v_and_b32_e32 v183, 4, v183
	v_or3_b32 v143, v143, v183, v144
	v_or_b32_e32 v144, v143, v127
	v_cvt_pk_bf16_f32 v184, v186, v187
	v_lshl_add_u64 v[144:145], v[144:145], 4, s[24:25]
	v_lshlrev_b32_e32 v186, 1, v177
	v_mov_b32_e32 v187, v133
	v_cvt_pk_bf16_f32 v185, v188, v189
	v_lshl_add_u64 v[144:145], v[144:145], 0, v[186:187]
	global_store_dwordx2 v[144:145], v[184:185], off

; DI unsigned cvt_pk(float lo, float hi) { f32x2 v = {lo, hi}; bf16x2v b = __builtin_convertvector(v, bf16x2v); return __builtin_bit_cast(unsigned, b); }
; DI bf16_t f2bf(float x) { return (bf16_t)(cvt_pk(x, 0.f) & 0xffffu); }
; DI float ex2(float x) { return __builtin_amdgcn_exp2f(x); }
; DI size_t qf_off(int item, int i, int dk) { return ((size_t)(((item * 8 + (dk >> 5)) * 2 + ((dk >> 4) & 1)) * 2 + (i >> 5)) * 64 + ((dk >> 3) & 1) * 32 + (i & 31)) * 8 + (dk & 7); }
; DI size_t kf_off(int item, int dk, int j) { return ((size_t)((item * 8 + (dk >> 5)) * 4 + (j >> 4)) * 64 + ((j >> 3) & 1) * 32 + perm23(dk & 31)) * 8 + (j & 7); }
;     ...
;     } else if (EPI == EPI_E5) {
;         const int idx = (pos + 48) & 63, ch = (pos + 48) >> 6;
;         if (col < 1024) {
;             const int hd = col >> 8, item = (ch * 4 + b) * 4 + hd;
;             bf16_t* d = (bf16_t*)((unsigned char*)p.out + OFFO_QHAT) + qf_off(item, idx, col & 255);
; #pragma unroll
;             for (int e = 0; e < 4; ++e) d[e * 8] = f2bf(v[e] * rs[e][0]);
;         } else if (col < 2048) {
;             const int c = col - 1024, hd = c >> 8, item = (ch * 4 + b) * 4 + hd;
;             bf16_t* d = (bf16_t*)(p.ws + OFF_KHAT) + (size_t)row0 * 1024 + c;
; #pragma unroll
;             for (int e = 0; e < 4; ++e) { v[e] *= rs[e][1]; d[(size_t)e * 1024] = f2bf(v[e]); }
;             u32x2 wv; wv[0] = cvt_pk(v[0], v[1]); wv[1] = cvt_pk(v[2], v[3]);
;             *(u32x2*)((bf16_t*)(p.ws + OFF_KHATT) + kf_off(item, c & 255, idx)) = wv;
;         } else {
;             const int c = col - 2048, hd = c >> 9, item = (ch * 4 + b) * 4 + hd;
;             u32x2 wv; wv[0] = cvt_pk(v[0], v[1]); wv[1] = cvt_pk(v[2], v[3]);
;             *(u32x2*)((bf16_t*)(p.ws + OFF_VT1) + vf_off(item, c & 511, idx)) = wv;
;         }
; template <int EPI, int K, int LNI = -1>
; DI void ph_gemm(const Params& p, const bf16_t* __restrict__ A, const bf16_t* __restrict__ Bt, int N, float* s_aux) {
;     ...
;                     if (EPI == EPI_E5) {
;                         const int idx_ = ((row0 % LT) + 48) & 63; const float lgh = lg_[0][0];
; #pragma unroll
;                         for (int e = 0; e < 4; ++e) rs[e] = (f32x2){ex2(lgh * (float)(idx_ + e + 1)), 0.0625f * ex2(lgh * (float)(63 - idx_ - e))};
;                     }
.LBB0_1193:
	s_or_b64 exec, exec, s[66:67]
	v_add_u32_e32 v100, 32, v138
	v_mul_hi_i32 v96, v100, s73
	v_lshrrev_b32_e32 v97, 31, v96
	v_ashrrev_i32_e32 v96, 12, v96
	v_add_u32_e32 v105, v96, v97
	v_mul_i32_i24_e32 v96, 0x2010, v105
	v_sub_u32_e32 v96, v100, v96
	v_add_u32_e32 v96, 48, v96
	v_and_b32_e32 v108, 63, v96
	v_sub_u32_e32 v98, 61, v108
	v_sub_u32_e32 v97, 62, v108
	v_cvt_f32_i32_e32 v98, v98
	v_sub_u32_e32 v99, 60, v108
	v_cvt_f32_i32_e32 v97, v97
	v_cvt_f32_i32_e32 v99, v99
	v_bitop3_b32 v96, v96, 63, v96 bitop3:0xc
	v_cvt_f32_ubyte0_e32 v96, v96
	v_mul_f32_e32 v98, v179, v98
	v_mul_f32_e32 v96, v179, v96
	v_mul_f32_e32 v97, v179, v97
	v_exp_f32_e32 v102, v98
	v_mul_f32_e32 v98, v179, v99
	v_exp_f32_e32 v96, v96
	v_exp_f32_e32 v97, v97
	v_exp_f32_e32 v103, v98
	v_mul_i32_i24_e32 v101, 0xffffdff0, v105
	v_add3_u32 v109, v138, v101, s78
	v_mul_f32_e64 v98, v96, s44
	v_mul_f32_e64 v99, v97, s44
	v_mul_f32_e64 v96, v102, s44
	v_mul_f32_e64 v97, v103, s44
	v_ashrrev_i32_e32 v103, 6, v109
	v_lshlrev_b32_e32 v101, 8, v105
	v_lshl_add_u32 v101, v103, 10, v101
	v_bfe_u32 v106, v109, 4, 2
	v_or_b32_e32 v104, v101, v106
	v_lshlrev_b32_e32 v101, 2, v109
	v_lshlrev_b32_e32 v105, 7, v105
	v_and_b32_e32 v102, 32, v101
	v_ashrrev_i32_e32 v101, 31, v100
	v_lshl_add_u32 v110, v103, 9, v105
	v_lshlrev_b64 v[100:101], 11, v[100:101]
	v_or_b32_e32 v103, v110, v106
	s_and_saveexec_b64 s[42:43], s[12:13]
	s_xor_b64 s[66:67], exec, s[42:43]
	s_cbranch_execz .LBB0_1199
	v_cmp_lt_u32_e32 vcc, s71, v176
	s_and_saveexec_b64 s[42:43], vcc
	s_xor_b64 s[68:69], exec, s[42:43]
	s_cbranch_execz .LBB0_1196
	v_add_u32_e32 v105, 0xfffff800, v176
	v_lshrrev_b32_e32 v105, 3, v105
	v_and_b32_e32 v111, 60, v180
	v_and_or_b32 v105, v105, s76, v111
	v_add_u32_e32 v112, v105, v104
	v_ashrrev_i32_e32 v113, 31, v112
	v_lshlrev_b64 v[112:113], 6, v[112:113]
	v_or_b32_e32 v105, v112, v178
	v_or_b32_e32 v112, v105, v102
	v_lshl_add_u64 v[112:113], v[112:113], 4, s[20:21]
	v_lshlrev_b32_e32 v114, 1, v177
	v_mov_b32_e32 v115, v133
	v_cvt_pk_bf16_f32 v106, v92, v93
	v_cvt_pk_bf16_f32 v107, v94, v95
	v_lshl_add_u64 v[112:113], v[112:113], 0, v[114:115]
	global_store_dwordx2 v[112:113], v[106:107], off
.LBB0_1196:
	s_andn2_saveexec_b64 s[68:69], s[68:69]
	s_cbranch_execz .LBB0_1198
	v_add_u32_e32 v106, 0xfffffc00, v176
	v_lshl_add_u64 v[112:113], s[36:37], 0, v[100:101]
	v_mov_b32_e32 v107, v133
	v_mul_f32_e64 v114, v92, v98
	v_mul_f32_e64 v115, v93, v99
	v_lshl_add_u64 v[112:113], v[106:107], 1, v[112:113]
	v_cvt_pk_bf16_f32 v105, v114, s0
	global_store_short v[112:113], v105, off
	v_cvt_pk_bf16_f32 v105, v115, s0
	global_store_short v[112:113], v105, off offset:2048
	v_mul_f32_e64 v116, v94, v96
	v_mul_f32_e64 v117, v95, v97
	v_add_co_u32_e32 v112, vcc, s35, v112
	v_cvt_pk_bf16_f32 v105, v116, s0
	s_nop 0
	v_addc_co_u32_e32 v113, vcc, 0, v113, vcc
	global_store_short v[112:113], v105, off
	v_cvt_pk_bf16_f32 v105, v117, s0
	global_store_short v[112:113], v105, off offset:2048
	v_lshrrev_b32_e32 v105, 3, v106
	v_and_b32_e32 v106, 28, v180
	v_and_or_b32 v105, v105, s77, v106
	v_add_u32_e32 v106, v105, v103
	v_and_b32_e32 v105, 19, v176
	v_lshlrev_b32_e32 v111, 1, v176
	v_ashrrev_i32_e32 v107, 31, v106
	v_and_or_b32 v105, v111, 8, v105
	v_lshrrev_b32_e32 v111, 1, v176
	v_lshlrev_b64 v[106:107], 6, v[106:107]
	v_and_b32_e32 v111, 4, v111
	v_or3_b32 v105, v105, v111, v106
	v_or_b32_e32 v106, v105, v102
	v_cvt_pk_bf16_f32 v112, v114, v115
	v_lshl_add_u64 v[106:107], v[106:107], 4, s[24:25]
	v_lshlrev_b32_e32 v114, 1, v177
	v_mov_b32_e32 v115, v133
	v_cvt_pk_bf16_f32 v113, v116, v117
	v_lshl_add_u64 v[106:107], v[106:107], 0, v[114:115]
	global_store_dwordx2 v[106:107], v[112:113], off

; DI unsigned cvt_pk(float lo, float hi) { f32x2 v = {lo, hi}; bf16x2v b = __builtin_convertvector(v, bf16x2v); return __builtin_bit_cast(unsigned, b); }
; DI bf16_t f2bf(float x) { return (bf16_t)(cvt_pk(x, 0.f) & 0xffffu); }
; DI float ex2(float x) { return __builtin_amdgcn_exp2f(x); }
; DI size_t qf_off(int item, int i, int dk) { return ((size_t)(((item * 8 + (dk >> 5)) * 2 + ((dk >> 4) & 1)) * 2 + (i >> 5)) * 64 + ((dk >> 3) & 1) * 32 + (i & 31)) * 8 + (dk & 7); }
; DI size_t kf_off(int item, int dk, int j) { return ((size_t)((item * 8 + (dk >> 5)) * 4 + (j >> 4)) * 64 + ((j >> 3) & 1) * 32 + perm23(dk & 31)) * 8 + (j & 7); }
;     ...
;     } else if (EPI == EPI_E5) {
;         const int idx = (pos + 48) & 63, ch = (pos + 48) >> 6;
;         if (col < 1024) {
;             const int hd = col >> 8, item = (ch * 4 + b) * 4 + hd;
;             bf16_t* d = (bf16_t*)((unsigned char*)p.out + OFFO_QHAT) + qf_off(item, idx, col & 255);
; #pragma unroll
;             for (int e = 0; e < 4; ++e) d[e * 8] = f2bf(v[e] * rs[e][0]);
;         } else if (col < 2048) {
;             const int c = col - 1024, hd = c >> 8, item = (ch * 4 + b) * 4 + hd;
;             bf16_t* d = (bf16_t*)(p.ws + OFF_KHAT) + (size_t)row0 * 1024 + c;
; #pragma unroll
;             for (int e = 0; e < 4; ++e) { v[e] *= rs[e][1]; d[(size_t)e * 1024] = f2bf(v[e]); }
;             u32x2 wv; wv[0] = cvt_pk(v[0], v[1]); wv[1] = cvt_pk(v[2], v[3]);
;             *(u32x2*)((bf16_t*)(p.ws + OFF_KHATT) + kf_off(item, c & 255, idx)) = wv;
;         } else {
;             const int c = col - 2048, hd = c >> 9, item = (ch * 4 + b) * 4 + hd;
;             u32x2 wv; wv[0] = cvt_pk(v[0], v[1]); wv[1] = cvt_pk(v[2], v[3]);
;             *(u32x2*)((bf16_t*)(p.ws + OFF_VT1) + vf_off(item, c & 511, idx)) = wv;
;         }
; template <int EPI, int K, int LNI = -1>
; DI void ph_gemm(const Params& p, const bf16_t* __restrict__ A, const bf16_t* __restrict__ Bt, int N, float* s_aux) {
;     ...
;                     if (EPI == EPI_E5) {
;                         const int idx_ = ((row0 % LT) + 48) & 63; const float lgh = lg_[0][0];
; #pragma unroll
;                         for (int e = 0; e < 4; ++e) rs[e] = (f32x2){ex2(lgh * (float)(idx_ + e + 1)), 0.0625f * ex2(lgh * (float)(63 - idx_ - e))};
;                     }
.LBB0_1207:
	s_or_b64 exec, exec, s[66:67]
	v_mul_hi_i32 v80, v140, s73
	v_lshrrev_b32_e32 v81, 31, v80
	v_ashrrev_i32_e32 v80, 12, v80
	v_add_u32_e32 v87, v80, v81
	v_mul_i32_i24_e32 v80, 0x2010, v87
	v_sub_u32_e32 v80, v140, v80
	v_add_u32_e32 v80, 48, v80
	v_and_b32_e32 v92, 63, v80
	v_sub_u32_e32 v82, 61, v92
	v_sub_u32_e32 v81, 62, v92
	v_cvt_f32_i32_e32 v82, v82
	v_sub_u32_e32 v83, 60, v92
	v_cvt_f32_i32_e32 v81, v81
	v_cvt_f32_i32_e32 v83, v83
	v_bitop3_b32 v80, v80, 63, v80 bitop3:0xc
	v_cvt_f32_ubyte0_e32 v80, v80
	v_mul_f32_e32 v82, v179, v82
	v_mul_f32_e32 v80, v179, v80
	v_mul_f32_e32 v81, v179, v81
	v_exp_f32_e32 v84, v82
	v_mul_f32_e32 v82, v179, v83
	v_exp_f32_e32 v80, v80
	v_exp_f32_e32 v81, v81
	v_exp_f32_e32 v85, v82
	v_ashrrev_i32_e32 v141, 31, v140
	v_mul_f32_e64 v82, v80, s44
	v_mul_f32_e64 v83, v81, s44
	v_mul_f32_e64 v80, v84, s44
	v_mul_f32_e64 v81, v85, s44
	v_mul_i32_i24_e32 v84, 0xffffdff0, v87
	v_add3_u32 v93, v138, v84, s79
	v_ashrrev_i32_e32 v89, 6, v93
	v_lshlrev_b32_e32 v84, 8, v87
	v_lshl_add_u32 v84, v89, 10, v84
	v_bfe_u32 v90, v93, 4, 2
	v_lshlrev_b32_e32 v87, 7, v87
	v_or_b32_e32 v88, v84, v90
	v_lshlrev_b32_e32 v84, 2, v93
	v_lshl_add_u32 v94, v89, 9, v87
	v_and_b32_e32 v86, 32, v84
	v_lshlrev_b64 v[84:85], 11, v[140:141]
	v_or_b32_e32 v87, v94, v90
	s_and_saveexec_b64 s[42:43], s[12:13]
	s_xor_b64 s[66:67], exec, s[42:43]
	s_cbranch_execz .LBB0_1213
	v_cmp_lt_u32_e32 vcc, s71, v176
	s_and_saveexec_b64 s[42:43], vcc
	s_xor_b64 s[68:69], exec, s[42:43]
	s_cbranch_execz .LBB0_1210
	v_add_u32_e32 v89, 0xfffff800, v176
	v_lshrrev_b32_e32 v89, 3, v89
	v_and_b32_e32 v95, 60, v180
	v_and_or_b32 v89, v89, s76, v95
	v_add_u32_e32 v96, v89, v88
	v_ashrrev_i32_e32 v97, 31, v96
	v_lshlrev_b64 v[96:97], 6, v[96:97]
	v_or_b32_e32 v89, v96, v178
	v_or_b32_e32 v96, v89, v86
	v_lshl_add_u64 v[96:97], v[96:97], 4, s[20:21]
	v_lshlrev_b32_e32 v98, 1, v177
	v_mov_b32_e32 v99, v133
	v_cvt_pk_bf16_f32 v90, v76, v77
	v_cvt_pk_bf16_f32 v91, v78, v79
	v_lshl_add_u64 v[96:97], v[96:97], 0, v[98:99]
	global_store_dwordx2 v[96:97], v[90:91], off
.LBB0_1210:
	s_andn2_saveexec_b64 s[68:69], s[68:69]
	s_cbranch_execz .LBB0_1212
	v_add_u32_e32 v90, 0xfffffc00, v176
	v_lshl_add_u64 v[96:97], s[36:37], 0, v[84:85]
	v_mov_b32_e32 v91, v133
	v_mul_f32_e64 v98, v76, v82
	v_mul_f32_e64 v99, v77, v83
	v_lshl_add_u64 v[96:97], v[90:91], 1, v[96:97]
	v_cvt_pk_bf16_f32 v89, v98, s0
	global_store_short v[96:97], v89, off
	v_cvt_pk_bf16_f32 v89, v99, s0
	global_store_short v[96:97], v89, off offset:2048
	v_mul_f32_e64 v100, v78, v80
	v_mul_f32_e64 v101, v79, v81
	v_add_co_u32_e32 v96, vcc, s35, v96
	v_cvt_pk_bf16_f32 v89, v100, s0
	s_nop 0
	v_addc_co_u32_e32 v97, vcc, 0, v97, vcc
	global_store_short v[96:97], v89, off
	v_cvt_pk_bf16_f32 v89, v101, s0
	global_store_short v[96:97], v89, off offset:2048
	v_lshrrev_b32_e32 v89, 3, v90
	v_and_b32_e32 v90, 28, v180
	v_and_or_b32 v89, v89, s77, v90
	v_add_u32_e32 v90, v89, v87
	v_and_b32_e32 v89, 19, v176
	v_lshlrev_b32_e32 v95, 1, v176
	v_ashrrev_i32_e32 v91, 31, v90
	v_and_or_b32 v89, v95, 8, v89
	v_lshrrev_b32_e32 v95, 1, v176
	v_lshlrev_b64 v[90:91], 6, v[90:91]
	v_and_b32_e32 v95, 4, v95
	v_or3_b32 v89, v89, v95, v90
	v_or_b32_e32 v90, v89, v86
	v_cvt_pk_bf16_f32 v96, v98, v99
	v_lshl_add_u64 v[90:91], v[90:91], 4, s[24:25]
	v_lshlrev_b32_e32 v98, 1, v177
	v_mov_b32_e32 v99, v133
	v_cvt_pk_bf16_f32 v97, v100, v101
	v_lshl_add_u64 v[90:91], v[90:91], 0, v[98:99]
	global_store_dwordx2 v[90:91], v[96:97], off

; DI unsigned cvt_pk(float lo, float hi) { f32x2 v = {lo, hi}; bf16x2v b = __builtin_convertvector(v, bf16x2v); return __builtin_bit_cast(unsigned, b); }
; DI bf16_t f2bf(float x) { return (bf16_t)(cvt_pk(x, 0.f) & 0xffffu); }
; DI float ex2(float x) { return __builtin_amdgcn_exp2f(x); }
; DI size_t qf_off(int item, int i, int dk) { return ((size_t)(((item * 8 + (dk >> 5)) * 2 + ((dk >> 4) & 1)) * 2 + (i >> 5)) * 64 + ((dk >> 3) & 1) * 32 + (i & 31)) * 8 + (dk & 7); }
; DI size_t kf_off(int item, int dk, int j) { return ((size_t)((item * 8 + (dk >> 5)) * 4 + (j >> 4)) * 64 + ((j >> 3) & 1) * 32 + perm23(dk & 31)) * 8 + (j & 7); }
;     ...
;     } else if (EPI == EPI_E5) {
;         const int idx = (pos + 48) & 63, ch = (pos + 48) >> 6;
;         if (col < 1024) {
;             const int hd = col >> 8, item = (ch * 4 + b) * 4 + hd;
;             bf16_t* d = (bf16_t*)((unsigned char*)p.out + OFFO_QHAT) + qf_off(item, idx, col & 255);
; #pragma unroll
;             for (int e = 0; e < 4; ++e) d[e * 8] = f2bf(v[e] * rs[e][0]);
;         } else if (col < 2048) {
;             const int c = col - 1024, hd = c >> 8, item = (ch * 4 + b) * 4 + hd;
;             bf16_t* d = (bf16_t*)(p.ws + OFF_KHAT) + (size_t)row0 * 1024 + c;
; #pragma unroll
;             for (int e = 0; e < 4; ++e) { v[e] *= rs[e][1]; d[(size_t)e * 1024] = f2bf(v[e]); }
;             u32x2 wv; wv[0] = cvt_pk(v[0], v[1]); wv[1] = cvt_pk(v[2], v[3]);
;             *(u32x2*)((bf16_t*)(p.ws + OFF_KHATT) + kf_off(item, c & 255, idx)) = wv;
;         } else {
;             const int c = col - 2048, hd = c >> 9, item = (ch * 4 + b) * 4 + hd;
;             u32x2 wv; wv[0] = cvt_pk(v[0], v[1]); wv[1] = cvt_pk(v[2], v[3]);
;             *(u32x2*)((bf16_t*)(p.ws + OFF_VT1) + vf_off(item, c & 511, idx)) = wv;
;         }
; template <int EPI, int K, int LNI = -1>
; DI void ph_gemm(const Params& p, const bf16_t* __restrict__ A, const bf16_t* __restrict__ Bt, int N, float* s_aux) {
;     ...
;                     if (EPI == EPI_E5) {
;                         const int idx_ = ((row0 % LT) + 48) & 63; const float lgh = lg_[0][0];
; #pragma unroll
;                         for (int e = 0; e < 4; ++e) rs[e] = (f32x2){ex2(lgh * (float)(idx_ + e + 1)), 0.0625f * ex2(lgh * (float)(63 - idx_ - e))};
;                     }
.LBB0_1221:
	s_or_b64 exec, exec, s[66:67]
	v_add_u32_e32 v70, 0x80, v138
	v_mul_hi_i32 v64, v70, s73
	v_lshrrev_b32_e32 v65, 31, v64
	v_ashrrev_i32_e32 v64, 12, v64
	v_add_u32_e32 v72, v64, v65
	v_mul_i32_i24_e32 v64, 0x2010, v72
	v_sub_u32_e32 v64, v70, v64
	v_add_u32_e32 v64, 48, v64
	v_and_b32_e32 v77, 63, v64
	v_sub_u32_e32 v65, 62, v77
	v_cvt_f32_i32_e32 v65, v65
	v_bitop3_b32 v64, v64, 63, v64 bitop3:0xc
	v_cvt_f32_ubyte0_e32 v64, v64
	v_mul_f32_e32 v64, v179, v64
	v_mul_f32_e32 v65, v179, v65
	v_sub_u32_e32 v66, 61, v77
	v_sub_u32_e32 v67, 60, v77
	v_exp_f32_e32 v64, v64
	v_cvt_f32_i32_e32 v66, v66
	v_cvt_f32_i32_e32 v67, v67
	v_exp_f32_e32 v65, v65
	v_ashrrev_i32_e32 v71, 31, v70
	v_mul_f32_e32 v66, v179, v66
	v_mul_f32_e32 v67, v179, v67
	v_mul_f32_e64 v68, v64, s44
	v_mul_f32_e64 v69, v65, s44
	v_add_u32_e32 v64, 0xb0, v138
	v_exp_f32_e32 v66, v66
	v_exp_f32_e32 v67, v67
	v_mad_i32_i24 v78, v72, s74, v64
	v_ashrrev_i32_e32 v74, 6, v78
	v_lshlrev_b32_e32 v65, 8, v72
	v_lshl_add_u32 v65, v74, 10, v65
	v_bfe_u32 v75, v78, 4, 2
	v_lshlrev_b32_e32 v72, 7, v72
	v_or_b32_e32 v73, v65, v75
	v_lshlrev_b32_e32 v65, 2, v78
	v_lshl_add_u32 v79, v74, 9, v72
	v_mul_f32_e64 v66, v66, s44
	v_mul_f32_e64 v67, v67, s44
	v_and_b32_e32 v65, 32, v65
	v_lshlrev_b64 v[70:71], 11, v[70:71]
	v_or_b32_e32 v72, v79, v75
	s_and_saveexec_b64 s[42:43], s[12:13]
	s_xor_b64 s[66:67], exec, s[42:43]
	s_cbranch_execz .LBB0_1227
	v_cmp_lt_u32_e32 vcc, s71, v176
	s_and_saveexec_b64 s[42:43], vcc
	s_xor_b64 s[68:69], exec, s[42:43]
	s_cbranch_execz .LBB0_1224
	v_add_u32_e32 v76, 0xfffff800, v176
	v_lshrrev_b32_e32 v76, 3, v76
	v_and_b32_e32 v80, 60, v180
	v_and_or_b32 v76, v76, s76, v80
	v_add_u32_e32 v80, v76, v73
	v_ashrrev_i32_e32 v81, 31, v80
	v_lshlrev_b64 v[80:81], 6, v[80:81]
	v_or_b32_e32 v76, v80, v178
	v_or_b32_e32 v80, v76, v65
	v_lshl_add_u64 v[80:81], v[80:81], 4, s[20:21]
	v_lshlrev_b32_e32 v82, 1, v177
	v_mov_b32_e32 v83, v133
	v_cvt_pk_bf16_f32 v74, v60, v61
	v_cvt_pk_bf16_f32 v75, v62, v63
	v_lshl_add_u64 v[80:81], v[80:81], 0, v[82:83]
	global_store_dwordx2 v[80:81], v[74:75], off
.LBB0_1224:
	s_andn2_saveexec_b64 s[68:69], s[68:69]
	s_cbranch_execz .LBB0_1226
	v_add_u32_e32 v74, 0xfffffc00, v176
	v_lshl_add_u64 v[80:81], s[36:37], 0, v[70:71]
	v_mov_b32_e32 v75, v133
	v_mul_f32_e64 v82, v60, v68
	v_mul_f32_e64 v83, v61, v69
	v_lshl_add_u64 v[80:81], v[74:75], 1, v[80:81]
	v_cvt_pk_bf16_f32 v75, v82, s0
	global_store_short v[80:81], v75, off
	v_cvt_pk_bf16_f32 v75, v83, s0
	global_store_short v[80:81], v75, off offset:2048
	v_mul_f32_e64 v84, v62, v66
	v_mul_f32_e64 v85, v63, v67
	v_add_co_u32_e32 v80, vcc, s35, v80
	v_cvt_pk_bf16_f32 v75, v84, s0
	s_nop 0
	v_addc_co_u32_e32 v81, vcc, 0, v81, vcc
	global_store_short v[80:81], v75, off
	v_cvt_pk_bf16_f32 v75, v85, s0
	global_store_short v[80:81], v75, off offset:2048
	v_lshrrev_b32_e32 v74, 3, v74
	v_and_b32_e32 v75, 28, v180
	v_and_or_b32 v74, v74, s77, v75
	v_cvt_pk_bf16_f32 v80, v82, v83
	v_add_u32_e32 v74, v74, v72
	v_and_b32_e32 v76, 19, v176
	v_lshlrev_b32_e32 v82, 1, v176
	v_ashrrev_i32_e32 v75, 31, v74
	v_and_or_b32 v76, v82, 8, v76
	v_lshrrev_b32_e32 v82, 1, v176
	v_lshlrev_b64 v[74:75], 6, v[74:75]
	v_and_b32_e32 v82, 4, v82
	v_or3_b32 v74, v76, v82, v74
	v_or_b32_e32 v74, v74, v65
	v_lshl_add_u64 v[74:75], v[74:75], 4, s[24:25]
	v_lshlrev_b32_e32 v82, 1, v177
	v_mov_b32_e32 v83, v133
	v_cvt_pk_bf16_f32 v81, v84, v85
	v_lshl_add_u64 v[74:75], v[74:75], 0, v[82:83]
	global_store_dwordx2 v[74:75], v[80:81], off

; DI unsigned cvt_pk(float lo, float hi) { f32x2 v = {lo, hi}; bf16x2v b = __builtin_convertvector(v, bf16x2v); return __builtin_bit_cast(unsigned, b); }
; DI bf16_t f2bf(float x) { return (bf16_t)(cvt_pk(x, 0.f) & 0xffffu); }
; DI float ex2(float x) { return __builtin_amdgcn_exp2f(x); }
; DI size_t qf_off(int item, int i, int dk) { return ((size_t)(((item * 8 + (dk >> 5)) * 2 + ((dk >> 4) & 1)) * 2 + (i >> 5)) * 64 + ((dk >> 3) & 1) * 32 + (i & 31)) * 8 + (dk & 7); }
; DI size_t kf_off(int item, int dk, int j) { return ((size_t)((item * 8 + (dk >> 5)) * 4 + (j >> 4)) * 64 + ((j >> 3) & 1) * 32 + perm23(dk & 31)) * 8 + (j & 7); }
;     ...
;     } else if (EPI == EPI_E5) {
;         const int idx = (pos + 48) & 63, ch = (pos + 48) >> 6;
;         if (col < 1024) {
;             const int hd = col >> 8, item = (ch * 4 + b) * 4 + hd;
;             bf16_t* d = (bf16_t*)((unsigned char*)p.out + OFFO_QHAT) + qf_off(item, idx, col & 255);
; #pragma unroll
;             for (int e = 0; e < 4; ++e) d[e * 8] = f2bf(v[e] * rs[e][0]);
;         } else if (col < 2048) {
;             const int c = col - 1024, hd = c >> 8, item = (ch * 4 + b) * 4 + hd;
;             bf16_t* d = (bf16_t*)(p.ws + OFF_KHAT) + (size_t)row0 * 1024 + c;
; #pragma unroll
;             for (int e = 0; e < 4; ++e) { v[e] *= rs[e][1]; d[(size_t)e * 1024] = f2bf(v[e]); }
;             u32x2 wv; wv[0] = cvt_pk(v[0], v[1]); wv[1] = cvt_pk(v[2], v[3]);
;             *(u32x2*)((bf16_t*)(p.ws + OFF_KHATT) + kf_off(item, c & 255, idx)) = wv;
;         } else {
;             const int c = col - 2048, hd = c >> 9, item = (ch * 4 + b) * 4 + hd;
;             u32x2 wv; wv[0] = cvt_pk(v[0], v[1]); wv[1] = cvt_pk(v[2], v[3]);
;             *(u32x2*)((bf16_t*)(p.ws + OFF_VT1) + vf_off(item, c & 511, idx)) = wv;
;         }
; template <int EPI, int K, int LNI = -1>
; DI void ph_gemm(const Params& p, const bf16_t* __restrict__ A, const bf16_t* __restrict__ Bt, int N, float* s_aux) {
;     ...
;                     if (EPI == EPI_E5) {
;                         const int idx_ = ((row0 % LT) + 48) & 63; const float lgh = lg_[0][0];
; #pragma unroll
;                         for (int e = 0; e < 4; ++e) rs[e] = (f32x2){ex2(lgh * (float)(idx_ + e + 1)), 0.0625f * ex2(lgh * (float)(63 - idx_ - e))};
;                     }
.LBB0_1235:
	s_or_b64 exec, exec, s[66:67]
	v_add_u32_e32 v52, 0x90, v138
	v_mul_hi_i32 v48, v52, s73
	v_lshrrev_b32_e32 v49, 31, v48
	v_ashrrev_i32_e32 v48, 12, v48
	v_add_u32_e32 v57, v48, v49
	v_mul_i32_i24_e32 v48, 0x2010, v57
	v_sub_u32_e32 v48, v52, v48
	v_add_u32_e32 v48, 48, v48
	v_and_b32_e32 v60, 63, v48
	v_sub_u32_e32 v50, 61, v60
	v_sub_u32_e32 v49, 62, v60
	v_cvt_f32_i32_e32 v50, v50
	v_sub_u32_e32 v51, 60, v60
	v_cvt_f32_i32_e32 v49, v49
	v_cvt_f32_i32_e32 v51, v51
	v_bitop3_b32 v48, v48, 63, v48 bitop3:0xc
	v_cvt_f32_ubyte0_e32 v48, v48
	v_mul_f32_e32 v50, v179, v50
	v_mul_f32_e32 v48, v179, v48
	v_mul_f32_e32 v49, v179, v49
	v_exp_f32_e32 v54, v50
	v_mul_f32_e32 v50, v179, v51
	v_exp_f32_e32 v48, v48
	v_exp_f32_e32 v49, v49
	v_exp_f32_e32 v55, v50
	v_mul_i32_i24_e32 v53, 0xffffdff0, v57
	v_add3_u32 v61, v138, v53, s3
	v_mul_f32_e64 v50, v48, s44
	v_mul_f32_e64 v51, v49, s44
	v_mul_f32_e64 v48, v54, s44
	v_mul_f32_e64 v49, v55, s44
	v_ashrrev_i32_e32 v55, 6, v61
	v_lshlrev_b32_e32 v53, 8, v57
	v_lshl_add_u32 v53, v55, 10, v53
	v_bfe_u32 v58, v61, 4, 2
	v_or_b32_e32 v56, v53, v58
	v_lshlrev_b32_e32 v53, 2, v61
	v_lshlrev_b32_e32 v57, 7, v57
	v_and_b32_e32 v54, 32, v53
	v_ashrrev_i32_e32 v53, 31, v52
	v_lshl_add_u32 v62, v55, 9, v57
	v_lshlrev_b64 v[52:53], 11, v[52:53]
	v_or_b32_e32 v55, v62, v58
	s_and_saveexec_b64 s[42:43], s[12:13]
	s_xor_b64 s[66:67], exec, s[42:43]
	s_cbranch_execz .LBB0_1241
	v_cmp_lt_u32_e32 vcc, s71, v176
	s_and_saveexec_b64 s[42:43], vcc
	s_xor_b64 s[68:69], exec, s[42:43]
	s_cbranch_execz .LBB0_1238
	v_add_u32_e32 v57, 0xfffff800, v176
	v_lshrrev_b32_e32 v57, 3, v57
	v_and_b32_e32 v63, 60, v180
	v_and_or_b32 v57, v57, s76, v63
	v_add_u32_e32 v66, v57, v56
	v_ashrrev_i32_e32 v67, 31, v66
	v_lshlrev_b64 v[66:67], 6, v[66:67]
	v_or_b32_e32 v57, v66, v178
	v_or_b32_e32 v66, v57, v54
	v_lshl_add_u64 v[66:67], v[66:67], 4, s[20:21]
	v_lshlrev_b32_e32 v68, 1, v177
	v_mov_b32_e32 v69, v133
	v_cvt_pk_bf16_f32 v58, v44, v45
	v_cvt_pk_bf16_f32 v59, v46, v47
	v_lshl_add_u64 v[66:67], v[66:67], 0, v[68:69]
	global_store_dwordx2 v[66:67], v[58:59], off
.LBB0_1238:
	s_andn2_saveexec_b64 s[68:69], s[68:69]
	s_cbranch_execz .LBB0_1240
	v_add_u32_e32 v58, 0xfffffc00, v176
	v_lshl_add_u64 v[66:67], s[36:37], 0, v[52:53]
	v_mov_b32_e32 v59, v133
	v_mul_f32_e64 v68, v44, v50
	v_mul_f32_e64 v69, v45, v51
	v_lshl_add_u64 v[66:67], v[58:59], 1, v[66:67]
	v_cvt_pk_bf16_f32 v57, v68, s0
	global_store_short v[66:67], v57, off
	v_cvt_pk_bf16_f32 v57, v69, s0
	global_store_short v[66:67], v57, off offset:2048
	v_mul_f32_e64 v70, v46, v48
	v_mul_f32_e64 v71, v47, v49
	v_add_co_u32_e32 v66, vcc, s35, v66
	v_cvt_pk_bf16_f32 v57, v70, s0
	s_nop 0
	v_addc_co_u32_e32 v67, vcc, 0, v67, vcc
	global_store_short v[66:67], v57, off
	v_cvt_pk_bf16_f32 v57, v71, s0
	global_store_short v[66:67], v57, off offset:2048
	v_lshrrev_b32_e32 v57, 3, v58
	v_and_b32_e32 v58, 28, v180
	v_and_or_b32 v57, v57, s77, v58
	v_add_u32_e32 v58, v57, v55
	v_and_b32_e32 v57, 19, v176
	v_lshlrev_b32_e32 v63, 1, v176
	v_ashrrev_i32_e32 v59, 31, v58
	v_and_or_b32 v57, v63, 8, v57
	v_lshrrev_b32_e32 v63, 1, v176
	v_lshlrev_b64 v[58:59], 6, v[58:59]
	v_and_b32_e32 v63, 4, v63
	v_or3_b32 v57, v57, v63, v58
	v_or_b32_e32 v58, v57, v54
	v_cvt_pk_bf16_f32 v66, v68, v69
	v_lshl_add_u64 v[58:59], v[58:59], 4, s[24:25]
	v_lshlrev_b32_e32 v68, 1, v177
	v_mov_b32_e32 v69, v133
	v_cvt_pk_bf16_f32 v67, v70, v71
	v_lshl_add_u64 v[58:59], v[58:59], 0, v[68:69]
	global_store_dwordx2 v[58:59], v[66:67], off

; DI unsigned cvt_pk(float lo, float hi) { f32x2 v = {lo, hi}; bf16x2v b = __builtin_convertvector(v, bf16x2v); return __builtin_bit_cast(unsigned, b); }
; DI bf16_t f2bf(float x) { return (bf16_t)(cvt_pk(x, 0.f) & 0xffffu); }
; DI float ex2(float x) { return __builtin_amdgcn_exp2f(x); }
; DI size_t qf_off(int item, int i, int dk) { return ((size_t)(((item * 8 + (dk >> 5)) * 2 + ((dk >> 4) & 1)) * 2 + (i >> 5)) * 64 + ((dk >> 3) & 1) * 32 + (i & 31)) * 8 + (dk & 7); }
; DI size_t kf_off(int item, int dk, int j) { return ((size_t)((item * 8 + (dk >> 5)) * 4 + (j >> 4)) * 64 + ((j >> 3) & 1) * 32 + perm23(dk & 31)) * 8 + (j & 7); }
;     ...
;     } else if (EPI == EPI_E5) {
;         const int idx = (pos + 48) & 63, ch = (pos + 48) >> 6;
;         if (col < 1024) {
;             const int hd = col >> 8, item = (ch * 4 + b) * 4 + hd;
;             bf16_t* d = (bf16_t*)((unsigned char*)p.out + OFFO_QHAT) + qf_off(item, idx, col & 255);
; #pragma unroll
;             for (int e = 0; e < 4; ++e) d[e * 8] = f2bf(v[e] * rs[e][0]);
;         } else if (col < 2048) {
;             const int c = col - 1024, hd = c >> 8, item = (ch * 4 + b) * 4 + hd;
;             bf16_t* d = (bf16_t*)(p.ws + OFF_KHAT) + (size_t)row0 * 1024 + c;
; #pragma unroll
;             for (int e = 0; e < 4; ++e) { v[e] *= rs[e][1]; d[(size_t)e * 1024] = f2bf(v[e]); }
;             u32x2 wv; wv[0] = cvt_pk(v[0], v[1]); wv[1] = cvt_pk(v[2], v[3]);
;             *(u32x2*)((bf16_t*)(p.ws + OFF_KHATT) + kf_off(item, c & 255, idx)) = wv;
;         } else {
;             const int c = col - 2048, hd = c >> 9, item = (ch * 4 + b) * 4 + hd;
;             u32x2 wv; wv[0] = cvt_pk(v[0], v[1]); wv[1] = cvt_pk(v[2], v[3]);
;             *(u32x2*)((bf16_t*)(p.ws + OFF_VT1) + vf_off(item, c & 511, idx)) = wv;
;         }
; template <int EPI, int K, int LNI = -1>
; DI void ph_gemm(const Params& p, const bf16_t* __restrict__ A, const bf16_t* __restrict__ Bt, int N, float* s_aux) {
;     ...
;                     if (EPI == EPI_E5) {
;                         const int idx_ = ((row0 % LT) + 48) & 63; const float lgh = lg_[0][0];
; #pragma unroll
;                         for (int e = 0; e < 4; ++e) rs[e] = (f32x2){ex2(lgh * (float)(idx_ + e + 1)), 0.0625f * ex2(lgh * (float)(63 - idx_ - e))};
;                     }
.LBB0_1249:
	s_or_b64 exec, exec, s[66:67]
	v_add_u32_e32 v36, 0xa0, v138
	v_mul_hi_i32 v32, v36, s73
	v_lshrrev_b32_e32 v33, 31, v32
	v_ashrrev_i32_e32 v32, 12, v32
	v_add_u32_e32 v41, v32, v33
	v_mul_i32_i24_e32 v32, 0x2010, v41
	v_sub_u32_e32 v32, v36, v32
	v_add_u32_e32 v32, 48, v32
	v_and_b32_e32 v44, 63, v32
	v_sub_u32_e32 v34, 61, v44
	v_sub_u32_e32 v33, 62, v44
	v_cvt_f32_i32_e32 v34, v34
	v_sub_u32_e32 v35, 60, v44
	v_cvt_f32_i32_e32 v33, v33
	v_cvt_f32_i32_e32 v35, v35
	v_bitop3_b32 v32, v32, 63, v32 bitop3:0xc
	v_cvt_f32_ubyte0_e32 v32, v32
	v_mul_f32_e32 v34, v179, v34
	v_mul_f32_e32 v32, v179, v32
	v_mul_f32_e32 v33, v179, v33
	v_exp_f32_e32 v38, v34
	v_mul_f32_e32 v34, v179, v35
	v_exp_f32_e32 v32, v32
	v_exp_f32_e32 v33, v33
	v_exp_f32_e32 v39, v34
	v_mul_i32_i24_e32 v37, 0xffffdff0, v41
	v_add3_u32 v45, v138, v37, s88
	v_mul_f32_e64 v34, v32, s44
	v_mul_f32_e64 v35, v33, s44
	v_mul_f32_e64 v32, v38, s44
	v_mul_f32_e64 v33, v39, s44
	v_ashrrev_i32_e32 v39, 6, v45
	v_lshlrev_b32_e32 v37, 8, v41
	v_lshl_add_u32 v37, v39, 10, v37
	v_bfe_u32 v42, v45, 4, 2
	v_or_b32_e32 v40, v37, v42
	v_lshlrev_b32_e32 v37, 2, v45
	v_lshlrev_b32_e32 v41, 7, v41
	v_and_b32_e32 v38, 32, v37
	v_ashrrev_i32_e32 v37, 31, v36
	v_lshl_add_u32 v46, v39, 9, v41
	v_lshlrev_b64 v[36:37], 11, v[36:37]
	v_or_b32_e32 v39, v46, v42
	s_and_saveexec_b64 s[42:43], s[12:13]
	s_xor_b64 s[66:67], exec, s[42:43]
	s_cbranch_execz .LBB0_1255
	v_cmp_lt_u32_e32 vcc, s71, v176
	s_and_saveexec_b64 s[42:43], vcc
	s_xor_b64 s[68:69], exec, s[42:43]
	s_cbranch_execz .LBB0_1252
	v_add_u32_e32 v41, 0xfffff800, v176
	v_lshrrev_b32_e32 v41, 3, v41
	v_and_b32_e32 v47, 60, v180
	v_and_or_b32 v41, v41, s76, v47
	v_add_u32_e32 v48, v41, v40
	v_ashrrev_i32_e32 v49, 31, v48
	v_lshlrev_b64 v[48:49], 6, v[48:49]
	v_or_b32_e32 v41, v48, v178
	v_or_b32_e32 v48, v41, v38
	v_lshl_add_u64 v[48:49], v[48:49], 4, s[20:21]
	v_lshlrev_b32_e32 v50, 1, v177
	v_mov_b32_e32 v51, v133
	v_cvt_pk_bf16_f32 v42, v28, v29
	v_cvt_pk_bf16_f32 v43, v30, v31
	v_lshl_add_u64 v[48:49], v[48:49], 0, v[50:51]
	global_store_dwordx2 v[48:49], v[42:43], off
.LBB0_1252:
	s_andn2_saveexec_b64 s[68:69], s[68:69]
	s_cbranch_execz .LBB0_1254
	v_add_u32_e32 v42, 0xfffffc00, v176
	v_lshl_add_u64 v[48:49], s[36:37], 0, v[36:37]
	v_mov_b32_e32 v43, v133
	v_mul_f32_e64 v50, v28, v34
	v_mul_f32_e64 v51, v29, v35
	v_lshl_add_u64 v[48:49], v[42:43], 1, v[48:49]
	v_cvt_pk_bf16_f32 v41, v50, s0
	global_store_short v[48:49], v41, off
	v_cvt_pk_bf16_f32 v41, v51, s0
	global_store_short v[48:49], v41, off offset:2048
	v_mul_f32_e64 v52, v30, v32
	v_mul_f32_e64 v53, v31, v33
	v_add_co_u32_e32 v48, vcc, s35, v48
	v_cvt_pk_bf16_f32 v41, v52, s0
	s_nop 0
	v_addc_co_u32_e32 v49, vcc, 0, v49, vcc
	global_store_short v[48:49], v41, off
	v_cvt_pk_bf16_f32 v41, v53, s0
	global_store_short v[48:49], v41, off offset:2048
	v_lshrrev_b32_e32 v41, 3, v42
	v_and_b32_e32 v42, 28, v180
	v_and_or_b32 v41, v41, s77, v42
	v_add_u32_e32 v42, v41, v39
	v_and_b32_e32 v41, 19, v176
	v_lshlrev_b32_e32 v47, 1, v176
	v_ashrrev_i32_e32 v43, 31, v42
	v_and_or_b32 v41, v47, 8, v41
	v_lshrrev_b32_e32 v47, 1, v176
	v_lshlrev_b64 v[42:43], 6, v[42:43]
	v_and_b32_e32 v47, 4, v47
	v_or3_b32 v41, v41, v47, v42
	v_or_b32_e32 v42, v41, v38
	v_cvt_pk_bf16_f32 v48, v50, v51
	v_lshl_add_u64 v[42:43], v[42:43], 4, s[24:25]
	v_lshlrev_b32_e32 v50, 1, v177
	v_mov_b32_e32 v51, v133
	v_cvt_pk_bf16_f32 v49, v52, v53
	v_lshl_add_u64 v[42:43], v[42:43], 0, v[50:51]
	global_store_dwordx2 v[42:43], v[48:49], off

; DI unsigned cvt_pk(float lo, float hi) { f32x2 v = {lo, hi}; bf16x2v b = __builtin_convertvector(v, bf16x2v); return __builtin_bit_cast(unsigned, b); }
; DI bf16_t f2bf(float x) { return (bf16_t)(cvt_pk(x, 0.f) & 0xffffu); }
; DI float ex2(float x) { return __builtin_amdgcn_exp2f(x); }
; DI size_t qf_off(int item, int i, int dk) { return ((size_t)(((item * 8 + (dk >> 5)) * 2 + ((dk >> 4) & 1)) * 2 + (i >> 5)) * 64 + ((dk >> 3) & 1) * 32 + (i & 31)) * 8 + (dk & 7); }
; DI size_t kf_off(int item, int dk, int j) { return ((size_t)((item * 8 + (dk >> 5)) * 4 + (j >> 4)) * 64 + ((j >> 3) & 1) * 32 + perm23(dk & 31)) * 8 + (j & 7); }
;     ...
;     } else if (EPI == EPI_E5) {
;         const int idx = (pos + 48) & 63, ch = (pos + 48) >> 6;
;         if (col < 1024) {
;             const int hd = col >> 8, item = (ch * 4 + b) * 4 + hd;
;             bf16_t* d = (bf16_t*)((unsigned char*)p.out + OFFO_QHAT) + qf_off(item, idx, col & 255);
; #pragma unroll
;             for (int e = 0; e < 4; ++e) d[e * 8] = f2bf(v[e] * rs[e][0]);
;         } else if (col < 2048) {
;             const int c = col - 1024, hd = c >> 8, item = (ch * 4 + b) * 4 + hd;
;             bf16_t* d = (bf16_t*)(p.ws + OFF_KHAT) + (size_t)row0 * 1024 + c;
; #pragma unroll
;             for (int e = 0; e < 4; ++e) { v[e] *= rs[e][1]; d[(size_t)e * 1024] = f2bf(v[e]); }
;             u32x2 wv; wv[0] = cvt_pk(v[0], v[1]); wv[1] = cvt_pk(v[2], v[3]);
;             *(u32x2*)((bf16_t*)(p.ws + OFF_KHATT) + kf_off(item, c & 255, idx)) = wv;
;         } else {
;             const int c = col - 2048, hd = c >> 9, item = (ch * 4 + b) * 4 + hd;
;             u32x2 wv; wv[0] = cvt_pk(v[0], v[1]); wv[1] = cvt_pk(v[2], v[3]);
;             *(u32x2*)((bf16_t*)(p.ws + OFF_VT1) + vf_off(item, c & 511, idx)) = wv;
;         }
; template <int EPI, int K, int LNI = -1>
; DI void ph_gemm(const Params& p, const bf16_t* __restrict__ A, const bf16_t* __restrict__ Bt, int N, float* s_aux) {
;     ...
;                     if (EPI == EPI_E5) {
;                         const int idx_ = ((row0 % LT) + 48) & 63; const float lgh = lg_[0][0];
; #pragma unroll
;                         for (int e = 0; e < 4; ++e) rs[e] = (f32x2){ex2(lgh * (float)(idx_ + e + 1)), 0.0625f * ex2(lgh * (float)(63 - idx_ - e))};
;                     }
.LBB0_1263:
	s_or_b64 exec, exec, s[66:67]
	v_mul_hi_i32 v16, v64, s73
	v_lshrrev_b32_e32 v17, 31, v16
	v_ashrrev_i32_e32 v16, 12, v16
	v_add_u32_e32 v23, v16, v17
	v_mul_i32_i24_e32 v16, 0x2010, v23
	v_sub_u32_e32 v16, v64, v16
	v_add_u32_e32 v16, 48, v16
	v_and_b32_e32 v28, 63, v16
	v_sub_u32_e32 v18, 61, v28
	v_sub_u32_e32 v17, 62, v28
	v_cvt_f32_i32_e32 v18, v18
	v_sub_u32_e32 v19, 60, v28
	v_cvt_f32_i32_e32 v17, v17
	v_cvt_f32_i32_e32 v19, v19
	v_bitop3_b32 v16, v16, 63, v16 bitop3:0xc
	v_cvt_f32_ubyte0_e32 v16, v16
	v_mul_f32_e32 v18, v179, v18
	v_mul_f32_e32 v16, v179, v16
	v_mul_f32_e32 v17, v179, v17
	v_exp_f32_e32 v20, v18
	v_mul_f32_e32 v18, v179, v19
	v_exp_f32_e32 v16, v16
	v_exp_f32_e32 v17, v17
	v_exp_f32_e32 v21, v18
	v_ashrrev_i32_e32 v65, 31, v64
	v_mul_f32_e64 v18, v16, s44
	v_mul_f32_e64 v19, v17, s44
	v_mul_f32_e64 v16, v20, s44
	v_mul_f32_e64 v17, v21, s44
	v_mul_i32_i24_e32 v20, 0xffffdff0, v23
	v_add3_u32 v29, v138, v20, s89
	v_ashrrev_i32_e32 v25, 6, v29
	v_lshlrev_b32_e32 v20, 8, v23
	v_lshl_add_u32 v20, v25, 10, v20
	v_bfe_u32 v26, v29, 4, 2
	v_lshlrev_b32_e32 v23, 7, v23
	v_or_b32_e32 v24, v20, v26
	v_lshlrev_b32_e32 v20, 2, v29
	v_lshl_add_u32 v30, v25, 9, v23
	v_and_b32_e32 v22, 32, v20
	v_lshlrev_b64 v[20:21], 11, v[64:65]
	v_or_b32_e32 v23, v30, v26
	s_and_saveexec_b64 s[42:43], s[12:13]
	s_xor_b64 s[12:13], exec, s[42:43]
	s_cbranch_execz .LBB0_1269
	v_cmp_lt_u32_e32 vcc, s71, v176
	s_and_saveexec_b64 s[42:43], vcc
	s_xor_b64 s[66:67], exec, s[42:43]
	s_cbranch_execz .LBB0_1266
	v_add_u32_e32 v25, 0xfffff800, v176
	v_lshrrev_b32_e32 v25, 3, v25
	v_and_b32_e32 v31, 60, v180
	v_and_or_b32 v25, v25, s76, v31
	v_add_u32_e32 v32, v25, v24
	v_ashrrev_i32_e32 v33, 31, v32
	v_lshlrev_b64 v[32:33], 6, v[32:33]
	v_or_b32_e32 v25, v32, v178
	v_or_b32_e32 v32, v25, v22
	v_lshl_add_u64 v[32:33], v[32:33], 4, s[20:21]
	v_lshlrev_b32_e32 v34, 1, v177
	v_mov_b32_e32 v35, v133
	v_cvt_pk_bf16_f32 v26, v12, v13
	v_cvt_pk_bf16_f32 v27, v14, v15
	v_lshl_add_u64 v[32:33], v[32:33], 0, v[34:35]
	global_store_dwordx2 v[32:33], v[26:27], off
.LBB0_1266:
	s_andn2_saveexec_b64 s[66:67], s[66:67]
	s_cbranch_execz .LBB0_1268
	v_add_u32_e32 v26, 0xfffffc00, v176
	v_lshl_add_u64 v[32:33], s[36:37], 0, v[20:21]
	v_mov_b32_e32 v27, v133
	v_mul_f32_e64 v34, v12, v18
	v_mul_f32_e64 v35, v13, v19
	v_lshl_add_u64 v[32:33], v[26:27], 1, v[32:33]
	v_cvt_pk_bf16_f32 v25, v34, s0
	global_store_short v[32:33], v25, off
	v_cvt_pk_bf16_f32 v25, v35, s0
	global_store_short v[32:33], v25, off offset:2048
	v_mul_f32_e64 v36, v14, v16
	v_mul_f32_e64 v37, v15, v17
	v_add_co_u32_e32 v32, vcc, s35, v32
	v_cvt_pk_bf16_f32 v25, v36, s0
	s_nop 0
	v_addc_co_u32_e32 v33, vcc, 0, v33, vcc
	global_store_short v[32:33], v25, off
	v_cvt_pk_bf16_f32 v25, v37, s0
	global_store_short v[32:33], v25, off offset:2048
	v_lshrrev_b32_e32 v25, 3, v26
	v_and_b32_e32 v26, 28, v180
	v_and_or_b32 v25, v25, s77, v26
	v_add_u32_e32 v26, v25, v23
	v_and_b32_e32 v25, 19, v176
	v_lshlrev_b32_e32 v31, 1, v176
	v_ashrrev_i32_e32 v27, 31, v26
	v_and_or_b32 v25, v31, 8, v25
	v_lshrrev_b32_e32 v31, 1, v176
	v_lshlrev_b64 v[26:27], 6, v[26:27]
	v_and_b32_e32 v31, 4, v31
	v_or3_b32 v25, v25, v31, v26
	v_or_b32_e32 v26, v25, v22
	v_cvt_pk_bf16_f32 v32, v34, v35
	v_lshl_add_u64 v[26:27], v[26:27], 4, s[24:25]
	v_lshlrev_b32_e32 v34, 1, v177
	v_mov_b32_e32 v35, v133
	v_cvt_pk_bf16_f32 v33, v36, v37
	v_lshl_add_u64 v[26:27], v[26:27], 0, v[34:35]
	global_store_dwordx2 v[26:27], v[32:33], off

; DI unsigned cvt_pk(float lo, float hi) { f32x2 v = {lo, hi}; bf16x2v b = __builtin_convertvector(v, bf16x2v); return __builtin_bit_cast(unsigned, b); }
; DI bf16_t f2bf(float x) { return (bf16_t)(cvt_pk(x, 0.f) & 0xffffu); }
; DI size_t kf_off(int item, int dk, int j) { return ((size_t)((item * 8 + (dk >> 5)) * 4 + (j >> 4)) * 64 + ((j >> 3) & 1) * 32 + perm23(dk & 31)) * 8 + (j & 7); }
;     ...
;         } else if (col < 2048) {
;             const int c = col - 1024, hd = c >> 8, item = (ch * 4 + b) * 4 + hd;
;             bf16_t* d = (bf16_t*)(p.ws + OFF_KHAT) + (size_t)row0 * 1024 + c;
; #pragma unroll
;             for (int e = 0; e < 4; ++e) { v[e] *= rs[e][1]; d[(size_t)e * 1024] = f2bf(v[e]); }
;             u32x2 wv; wv[0] = cvt_pk(v[0], v[1]); wv[1] = cvt_pk(v[2], v[3]);
;             *(u32x2*)((bf16_t*)(p.ws + OFF_KHATT) + kf_off(item, c & 255, idx)) = wv;
.LBB0_1280:
	s_andn2_saveexec_b64 s[68:69], s[68:69]
	s_cbranch_execz .LBB0_1282
	v_add_u32_e32 v108, 0xfffffc10, v176
	v_lshl_add_u64 v[110:111], s[36:37], 0, v[116:117]
	v_mov_b32_e32 v109, v133
	v_mul_f32_e64 v184, v104, v114
	v_mul_f32_e64 v185, v105, v115
	v_lshl_add_u64 v[110:111], v[108:109], 1, v[110:111]
	v_cvt_pk_bf16_f32 v109, v184, s0
	global_store_short v[110:111], v109, off
	v_cvt_pk_bf16_f32 v109, v185, s0
	global_store_short v[110:111], v109, off offset:2048
	v_mul_f32_e64 v186, v106, v112
	v_mul_f32_e64 v187, v107, v113
	v_add_co_u32_e32 v110, vcc, s35, v110
	v_cvt_pk_bf16_f32 v109, v186, s0
	s_nop 0
	v_addc_co_u32_e32 v111, vcc, 0, v111, vcc
	global_store_short v[110:111], v109, off
	v_cvt_pk_bf16_f32 v109, v187, s0
	global_store_short v[110:111], v109, off offset:2048
	v_lshrrev_b32_e32 v108, 3, v108
	v_and_b32_e32 v109, 28, v125
	v_and_or_b32 v108, v108, s77, v109
	v_add_u32_e32 v108, v108, v141
	v_cvt_pk_bf16_f32 v110, v184, v185
	v_ashrrev_i32_e32 v109, 31, v108
	v_and_b32_e32 v183, 19, v124
	v_lshlrev_b32_e32 v184, 1, v124
	v_lshrrev_b32_e32 v185, 1, v176
	v_lshlrev_b64 v[108:109], 6, v[108:109]
	v_and_b32_e32 v184, 8, v184
	v_and_or_b32 v183, v185, 4, v183
	v_or3_b32 v108, v183, v184, v108
	v_or_b32_e32 v108, v108, v127
	v_lshl_add_u64 v[108:109], v[108:109], 4, s[24:25]
	v_lshlrev_b32_e32 v184, 1, v177
	v_mov_b32_e32 v185, v133
	v_cvt_pk_bf16_f32 v111, v186, v187
	v_lshl_add_u64 v[108:109], v[108:109], 0, v[184:185]
	global_store_dwordx2 v[108:109], v[110:111], off

; DI unsigned cvt_pk(float lo, float hi) { f32x2 v = {lo, hi}; bf16x2v b = __builtin_convertvector(v, bf16x2v); return __builtin_bit_cast(unsigned, b); }
; DI bf16_t f2bf(float x) { return (bf16_t)(cvt_pk(x, 0.f) & 0xffffu); }
; DI size_t kf_off(int item, int dk, int j) { return ((size_t)((item * 8 + (dk >> 5)) * 4 + (j >> 4)) * 64 + ((j >> 3) & 1) * 32 + perm23(dk & 31)) * 8 + (j & 7); }
;     ...
;         } else if (col < 2048) {
;             const int c = col - 1024, hd = c >> 8, item = (ch * 4 + b) * 4 + hd;
;             bf16_t* d = (bf16_t*)(p.ws + OFF_KHAT) + (size_t)row0 * 1024 + c;
; #pragma unroll
;             for (int e = 0; e < 4; ++e) { v[e] *= rs[e][1]; d[(size_t)e * 1024] = f2bf(v[e]); }
;             u32x2 wv; wv[0] = cvt_pk(v[0], v[1]); wv[1] = cvt_pk(v[2], v[3]);
;             *(u32x2*)((bf16_t*)(p.ws + OFF_KHATT) + kf_off(item, c & 255, idx)) = wv;
.LBB0_1286:
	s_andn2_saveexec_b64 s[68:69], s[68:69]
	s_cbranch_execz .LBB0_1288
	v_add_u32_e32 v104, 0xfffffc80, v176
	v_lshl_add_u64 v[106:107], s[36:37], 0, v[116:117]
	v_mov_b32_e32 v105, v133
	v_mul_f32_e64 v108, v100, v114
	v_mul_f32_e64 v109, v101, v115
	v_lshl_add_u64 v[106:107], v[104:105], 1, v[106:107]
	v_cvt_pk_bf16_f32 v105, v108, s0
	global_store_short v[106:107], v105, off
	v_cvt_pk_bf16_f32 v105, v109, s0
	global_store_short v[106:107], v105, off offset:2048
	v_mul_f32_e64 v110, v102, v112
	v_mul_f32_e64 v111, v103, v113
	v_add_co_u32_e32 v106, vcc, s35, v106
	v_cvt_pk_bf16_f32 v105, v110, s0
	s_nop 0
	v_addc_co_u32_e32 v107, vcc, 0, v107, vcc
	global_store_short v[106:107], v105, off
	v_cvt_pk_bf16_f32 v105, v111, s0
	global_store_short v[106:107], v105, off offset:2048
	v_lshrrev_b32_e32 v104, 3, v104
	v_and_b32_e32 v105, 28, v121
	v_and_or_b32 v104, v104, s77, v105
	v_add_u32_e32 v104, v104, v141
	v_cvt_pk_bf16_f32 v106, v108, v109
	v_cvt_pk_bf16_f32 v107, v110, v111
	v_ashrrev_i32_e32 v105, 31, v104
	v_and_b32_e32 v108, 19, v176
	v_lshlrev_b32_e32 v109, 1, v120
	v_lshrrev_b32_e32 v110, 1, v176
	v_lshlrev_b64 v[104:105], 6, v[104:105]
	v_and_b32_e32 v109, 8, v109
	v_and_or_b32 v108, v110, 4, v108
	v_or3_b32 v104, v108, v109, v104
	v_or_b32_e32 v104, v104, v127
	v_lshl_add_u64 v[104:105], v[104:105], 4, s[24:25]
	v_lshlrev_b32_e32 v108, 1, v177
	v_mov_b32_e32 v109, v133
	v_lshl_add_u64 v[104:105], v[104:105], 0, v[108:109]
	global_store_dwordx2 v[104:105], v[106:107], off

; DI unsigned cvt_pk(float lo, float hi) { f32x2 v = {lo, hi}; bf16x2v b = __builtin_convertvector(v, bf16x2v); return __builtin_bit_cast(unsigned, b); }
; DI bf16_t f2bf(float x) { return (bf16_t)(cvt_pk(x, 0.f) & 0xffffu); }
; DI size_t kf_off(int item, int dk, int j) { return ((size_t)((item * 8 + (dk >> 5)) * 4 + (j >> 4)) * 64 + ((j >> 3) & 1) * 32 + perm23(dk & 31)) * 8 + (j & 7); }
;     ...
;         } else if (col < 2048) {
;             const int c = col - 1024, hd = c >> 8, item = (ch * 4 + b) * 4 + hd;
;             bf16_t* d = (bf16_t*)(p.ws + OFF_KHAT) + (size_t)row0 * 1024 + c;
; #pragma unroll
;             for (int e = 0; e < 4; ++e) { v[e] *= rs[e][1]; d[(size_t)e * 1024] = f2bf(v[e]); }
;             u32x2 wv; wv[0] = cvt_pk(v[0], v[1]); wv[1] = cvt_pk(v[2], v[3]);
;             *(u32x2*)((bf16_t*)(p.ws + OFF_KHATT) + kf_off(item, c & 255, idx)) = wv;
.LBB0_1292:
	s_andn2_saveexec_b64 s[68:69], s[68:69]
	s_cbranch_execz .LBB0_1294
	v_add_u32_e32 v100, 0xfffffc90, v176
	v_lshl_add_u64 v[102:103], s[36:37], 0, v[116:117]
	v_mov_b32_e32 v101, v133
	v_mul_f32_e64 v104, v96, v114
	v_mul_f32_e64 v105, v97, v115
	v_lshl_add_u64 v[102:103], v[100:101], 1, v[102:103]
	v_cvt_pk_bf16_f32 v101, v104, s0
	global_store_short v[102:103], v101, off
	v_cvt_pk_bf16_f32 v101, v105, s0
	global_store_short v[102:103], v101, off offset:2048
	v_mul_f32_e64 v106, v98, v112
	v_mul_f32_e64 v107, v99, v113
	v_add_co_u32_e32 v102, vcc, s35, v102
	v_cvt_pk_bf16_f32 v101, v106, s0
	s_nop 0
	v_addc_co_u32_e32 v103, vcc, 0, v103, vcc
	global_store_short v[102:103], v101, off
	v_cvt_pk_bf16_f32 v101, v107, s0
	global_store_short v[102:103], v101, off offset:2048
	v_lshrrev_b32_e32 v100, 3, v100
	v_and_b32_e32 v101, 28, v119
	v_and_or_b32 v100, v100, s77, v101
	v_add_u32_e32 v100, v100, v141
	v_cvt_pk_bf16_f32 v102, v104, v105
	v_cvt_pk_bf16_f32 v103, v106, v107
	v_ashrrev_i32_e32 v101, 31, v100
	v_and_b32_e32 v104, 19, v118
	v_lshlrev_b32_e32 v105, 1, v118
	v_lshrrev_b32_e32 v106, 1, v176
	v_lshlrev_b64 v[100:101], 6, v[100:101]
	v_and_b32_e32 v105, 8, v105
	v_and_or_b32 v104, v106, 4, v104
	v_or3_b32 v100, v104, v105, v100
	v_or_b32_e32 v100, v100, v127
	v_lshl_add_u64 v[100:101], v[100:101], 4, s[24:25]
	v_lshlrev_b32_e32 v104, 1, v177
	v_mov_b32_e32 v105, v133
	v_lshl_add_u64 v[100:101], v[100:101], 0, v[104:105]
	global_store_dwordx2 v[100:101], v[102:103], off

; DI unsigned cvt_pk(float lo, float hi) { f32x2 v = {lo, hi}; bf16x2v b = __builtin_convertvector(v, bf16x2v); return __builtin_bit_cast(unsigned, b); }
; DI bf16_t f2bf(float x) { return (bf16_t)(cvt_pk(x, 0.f) & 0xffffu); }
; DI size_t kf_off(int item, int dk, int j) { return ((size_t)((item * 8 + (dk >> 5)) * 4 + (j >> 4)) * 64 + ((j >> 3) & 1) * 32 + perm23(dk & 31)) * 8 + (j & 7); }
;     ...
;         } else if (col < 2048) {
;             const int c = col - 1024, hd = c >> 8, item = (ch * 4 + b) * 4 + hd;
;             bf16_t* d = (bf16_t*)(p.ws + OFF_KHAT) + (size_t)row0 * 1024 + c;
; #pragma unroll
;             for (int e = 0; e < 4; ++e) { v[e] *= rs[e][1]; d[(size_t)e * 1024] = f2bf(v[e]); }
;             u32x2 wv; wv[0] = cvt_pk(v[0], v[1]); wv[1] = cvt_pk(v[2], v[3]);
;             *(u32x2*)((bf16_t*)(p.ws + OFF_KHATT) + kf_off(item, c & 255, idx)) = wv;
.LBB0_1298:
	s_andn2_saveexec_b64 s[68:69], s[68:69]
	s_cbranch_execz .LBB0_1300
	v_add_u32_e32 v92, 0xfffffc10, v176
	v_lshl_add_u64 v[94:95], s[36:37], 0, v[100:101]
	v_mov_b32_e32 v93, v133
	v_mul_f32_e64 v112, v88, v98
	v_mul_f32_e64 v113, v89, v99
	v_lshl_add_u64 v[94:95], v[92:93], 1, v[94:95]
	v_cvt_pk_bf16_f32 v93, v112, s0
	global_store_short v[94:95], v93, off
	v_cvt_pk_bf16_f32 v93, v113, s0
	global_store_short v[94:95], v93, off offset:2048
	v_mul_f32_e64 v114, v90, v96
	v_mul_f32_e64 v115, v91, v97
	v_add_co_u32_e32 v94, vcc, s35, v94
	v_cvt_pk_bf16_f32 v93, v114, s0
	s_nop 0
	v_addc_co_u32_e32 v95, vcc, 0, v95, vcc
	global_store_short v[94:95], v93, off
	v_cvt_pk_bf16_f32 v93, v115, s0
	global_store_short v[94:95], v93, off offset:2048
	v_lshrrev_b32_e32 v92, 3, v92
	v_and_b32_e32 v93, 28, v125
	v_and_or_b32 v92, v92, s77, v93
	v_add_u32_e32 v92, v92, v103
	v_cvt_pk_bf16_f32 v94, v112, v113
	v_ashrrev_i32_e32 v93, 31, v92
	v_and_b32_e32 v111, 19, v124
	v_lshlrev_b32_e32 v112, 1, v124
	v_lshrrev_b32_e32 v113, 1, v176
	v_lshlrev_b64 v[92:93], 6, v[92:93]
	v_and_b32_e32 v112, 8, v112
	v_and_or_b32 v111, v113, 4, v111
	v_or3_b32 v92, v111, v112, v92
	v_or_b32_e32 v92, v92, v102
	v_lshl_add_u64 v[92:93], v[92:93], 4, s[24:25]
	v_lshlrev_b32_e32 v112, 1, v177
	v_mov_b32_e32 v113, v133
	v_cvt_pk_bf16_f32 v95, v114, v115
	v_lshl_add_u64 v[92:93], v[92:93], 0, v[112:113]
	global_store_dwordx2 v[92:93], v[94:95], off

; DI unsigned cvt_pk(float lo, float hi) { f32x2 v = {lo, hi}; bf16x2v b = __builtin_convertvector(v, bf16x2v); return __builtin_bit_cast(unsigned, b); }
; DI bf16_t f2bf(float x) { return (bf16_t)(cvt_pk(x, 0.f) & 0xffffu); }
; DI size_t kf_off(int item, int dk, int j) { return ((size_t)((item * 8 + (dk >> 5)) * 4 + (j >> 4)) * 64 + ((j >> 3) & 1) * 32 + perm23(dk & 31)) * 8 + (j & 7); }
;     ...
;         } else if (col < 2048) {
;             const int c = col - 1024, hd = c >> 8, item = (ch * 4 + b) * 4 + hd;
;             bf16_t* d = (bf16_t*)(p.ws + OFF_KHAT) + (size_t)row0 * 1024 + c;
; #pragma unroll
;             for (int e = 0; e < 4; ++e) { v[e] *= rs[e][1]; d[(size_t)e * 1024] = f2bf(v[e]); }
;             u32x2 wv; wv[0] = cvt_pk(v[0], v[1]); wv[1] = cvt_pk(v[2], v[3]);
;             *(u32x2*)((bf16_t*)(p.ws + OFF_KHATT) + kf_off(item, c & 255, idx)) = wv;
.LBB0_1304:
	s_andn2_saveexec_b64 s[68:69], s[68:69]
	s_cbranch_execz .LBB0_1306
	v_add_u32_e32 v88, 0xfffffc80, v176
	v_lshl_add_u64 v[90:91], s[36:37], 0, v[100:101]
	v_mov_b32_e32 v89, v133
	v_mul_f32_e64 v92, v84, v98
	v_mul_f32_e64 v93, v85, v99
	v_lshl_add_u64 v[90:91], v[88:89], 1, v[90:91]
	v_cvt_pk_bf16_f32 v89, v92, s0
	global_store_short v[90:91], v89, off
	v_cvt_pk_bf16_f32 v89, v93, s0
	global_store_short v[90:91], v89, off offset:2048
	v_mul_f32_e64 v94, v86, v96
	v_mul_f32_e64 v95, v87, v97
	v_add_co_u32_e32 v90, vcc, s35, v90
	v_cvt_pk_bf16_f32 v89, v94, s0
	s_nop 0
	v_addc_co_u32_e32 v91, vcc, 0, v91, vcc
	global_store_short v[90:91], v89, off
	v_cvt_pk_bf16_f32 v89, v95, s0
	global_store_short v[90:91], v89, off offset:2048
	v_lshrrev_b32_e32 v88, 3, v88
	v_and_b32_e32 v89, 28, v121
	v_and_or_b32 v88, v88, s77, v89
	v_add_u32_e32 v88, v88, v103
	v_cvt_pk_bf16_f32 v90, v92, v93
	v_cvt_pk_bf16_f32 v91, v94, v95
	v_ashrrev_i32_e32 v89, 31, v88
	v_and_b32_e32 v92, 19, v176
	v_lshlrev_b32_e32 v93, 1, v120
	v_lshrrev_b32_e32 v94, 1, v176
	v_lshlrev_b64 v[88:89], 6, v[88:89]
	v_and_b32_e32 v93, 8, v93
	v_and_or_b32 v92, v94, 4, v92
	v_or3_b32 v88, v92, v93, v88
	v_or_b32_e32 v88, v88, v102
	v_lshl_add_u64 v[88:89], v[88:89], 4, s[24:25]
	v_lshlrev_b32_e32 v92, 1, v177
	v_mov_b32_e32 v93, v133
	v_lshl_add_u64 v[88:89], v[88:89], 0, v[92:93]
	global_store_dwordx2 v[88:89], v[90:91], off

; DI unsigned cvt_pk(float lo, float hi) { f32x2 v = {lo, hi}; bf16x2v b = __builtin_convertvector(v, bf16x2v); return __builtin_bit_cast(unsigned, b); }
; DI bf16_t f2bf(float x) { return (bf16_t)(cvt_pk(x, 0.f) & 0xffffu); }
; DI size_t kf_off(int item, int dk, int j) { return ((size_t)((item * 8 + (dk >> 5)) * 4 + (j >> 4)) * 64 + ((j >> 3) & 1) * 32 + perm23(dk & 31)) * 8 + (j & 7); }
;     ...
;         } else if (col < 2048) {
;             const int c = col - 1024, hd = c >> 8, item = (ch * 4 + b) * 4 + hd;
;             bf16_t* d = (bf16_t*)(p.ws + OFF_KHAT) + (size_t)row0 * 1024 + c;
; #pragma unroll
;             for (int e = 0; e < 4; ++e) { v[e] *= rs[e][1]; d[(size_t)e * 1024] = f2bf(v[e]); }
;             u32x2 wv; wv[0] = cvt_pk(v[0], v[1]); wv[1] = cvt_pk(v[2], v[3]);
;             *(u32x2*)((bf16_t*)(p.ws + OFF_KHATT) + kf_off(item, c & 255, idx)) = wv;
.LBB0_1310:
	s_andn2_saveexec_b64 s[68:69], s[68:69]
	s_cbranch_execz .LBB0_1312
	v_add_u32_e32 v84, 0xfffffc90, v176
	v_lshl_add_u64 v[86:87], s[36:37], 0, v[100:101]
	v_mov_b32_e32 v85, v133
	v_mul_f32_e64 v88, v80, v98
	v_mul_f32_e64 v89, v81, v99
	v_lshl_add_u64 v[86:87], v[84:85], 1, v[86:87]
	v_cvt_pk_bf16_f32 v85, v88, s0
	global_store_short v[86:87], v85, off
	v_cvt_pk_bf16_f32 v85, v89, s0
	global_store_short v[86:87], v85, off offset:2048
	v_mul_f32_e64 v90, v82, v96
	v_mul_f32_e64 v91, v83, v97
	v_add_co_u32_e32 v86, vcc, s35, v86
	v_cvt_pk_bf16_f32 v85, v90, s0
	s_nop 0
	v_addc_co_u32_e32 v87, vcc, 0, v87, vcc
	global_store_short v[86:87], v85, off
	v_cvt_pk_bf16_f32 v85, v91, s0
	global_store_short v[86:87], v85, off offset:2048
	v_lshrrev_b32_e32 v84, 3, v84
	v_and_b32_e32 v85, 28, v119
	v_and_or_b32 v84, v84, s77, v85
	v_add_u32_e32 v84, v84, v103
	v_cvt_pk_bf16_f32 v86, v88, v89
	v_cvt_pk_bf16_f32 v87, v90, v91
	v_ashrrev_i32_e32 v85, 31, v84
	v_and_b32_e32 v88, 19, v118
	v_lshlrev_b32_e32 v89, 1, v118
	v_lshrrev_b32_e32 v90, 1, v176
	v_lshlrev_b64 v[84:85], 6, v[84:85]
	v_and_b32_e32 v89, 8, v89
	v_and_or_b32 v88, v90, 4, v88
	v_or3_b32 v84, v88, v89, v84
	v_or_b32_e32 v84, v84, v102
	v_lshl_add_u64 v[84:85], v[84:85], 4, s[24:25]
	v_lshlrev_b32_e32 v88, 1, v177
	v_mov_b32_e32 v89, v133
	v_lshl_add_u64 v[84:85], v[84:85], 0, v[88:89]
	global_store_dwordx2 v[84:85], v[86:87], off

; DI unsigned cvt_pk(float lo, float hi) { f32x2 v = {lo, hi}; bf16x2v b = __builtin_convertvector(v, bf16x2v); return __builtin_bit_cast(unsigned, b); }
; DI bf16_t f2bf(float x) { return (bf16_t)(cvt_pk(x, 0.f) & 0xffffu); }
; DI size_t kf_off(int item, int dk, int j) { return ((size_t)((item * 8 + (dk >> 5)) * 4 + (j >> 4)) * 64 + ((j >> 3) & 1) * 32 + perm23(dk & 31)) * 8 + (j & 7); }
;     ...
;         } else if (col < 2048) {
;             const int c = col - 1024, hd = c >> 8, item = (ch * 4 + b) * 4 + hd;
;             bf16_t* d = (bf16_t*)(p.ws + OFF_KHAT) + (size_t)row0 * 1024 + c;
; #pragma unroll
;             for (int e = 0; e < 4; ++e) { v[e] *= rs[e][1]; d[(size_t)e * 1024] = f2bf(v[e]); }
;             u32x2 wv; wv[0] = cvt_pk(v[0], v[1]); wv[1] = cvt_pk(v[2], v[3]);
;             *(u32x2*)((bf16_t*)(p.ws + OFF_KHATT) + kf_off(item, c & 255, idx)) = wv;
.LBB0_1316:
	s_andn2_saveexec_b64 s[68:69], s[68:69]
	s_cbranch_execz .LBB0_1318
	v_add_u32_e32 v76, 0xfffffc10, v176
	v_lshl_add_u64 v[78:79], s[36:37], 0, v[84:85]
	v_mov_b32_e32 v77, v133
	v_mul_f32_e64 v96, v72, v82
	v_mul_f32_e64 v97, v73, v83
	v_lshl_add_u64 v[78:79], v[76:77], 1, v[78:79]
	v_cvt_pk_bf16_f32 v77, v96, s0
	global_store_short v[78:79], v77, off
	v_cvt_pk_bf16_f32 v77, v97, s0
	global_store_short v[78:79], v77, off offset:2048
	v_mul_f32_e64 v98, v74, v80
	v_mul_f32_e64 v99, v75, v81
	v_add_co_u32_e32 v78, vcc, s35, v78
	v_cvt_pk_bf16_f32 v77, v98, s0
	s_nop 0
	v_addc_co_u32_e32 v79, vcc, 0, v79, vcc
	global_store_short v[78:79], v77, off
	v_cvt_pk_bf16_f32 v77, v99, s0
	global_store_short v[78:79], v77, off offset:2048
	v_lshrrev_b32_e32 v76, 3, v76
	v_and_b32_e32 v77, 28, v125
	v_and_or_b32 v76, v76, s77, v77
	v_add_u32_e32 v76, v76, v87
	v_cvt_pk_bf16_f32 v78, v96, v97
	v_ashrrev_i32_e32 v77, 31, v76
	v_and_b32_e32 v95, 19, v124
	v_lshlrev_b32_e32 v96, 1, v124
	v_lshrrev_b32_e32 v97, 1, v176
	v_lshlrev_b64 v[76:77], 6, v[76:77]
	v_and_b32_e32 v96, 8, v96
	v_and_or_b32 v95, v97, 4, v95
	v_or3_b32 v76, v95, v96, v76
	v_or_b32_e32 v76, v76, v86
	v_lshl_add_u64 v[76:77], v[76:77], 4, s[24:25]
	v_lshlrev_b32_e32 v96, 1, v177
	v_mov_b32_e32 v97, v133
	v_cvt_pk_bf16_f32 v79, v98, v99
	v_lshl_add_u64 v[76:77], v[76:77], 0, v[96:97]
	global_store_dwordx2 v[76:77], v[78:79], off

; DI unsigned cvt_pk(float lo, float hi) { f32x2 v = {lo, hi}; bf16x2v b = __builtin_convertvector(v, bf16x2v); return __builtin_bit_cast(unsigned, b); }
; DI bf16_t f2bf(float x) { return (bf16_t)(cvt_pk(x, 0.f) & 0xffffu); }
; DI size_t kf_off(int item, int dk, int j) { return ((size_t)((item * 8 + (dk >> 5)) * 4 + (j >> 4)) * 64 + ((j >> 3) & 1) * 32 + perm23(dk & 31)) * 8 + (j & 7); }
;     ...
;         } else if (col < 2048) {
;             const int c = col - 1024, hd = c >> 8, item = (ch * 4 + b) * 4 + hd;
;             bf16_t* d = (bf16_t*)(p.ws + OFF_KHAT) + (size_t)row0 * 1024 + c;
; #pragma unroll
;             for (int e = 0; e < 4; ++e) { v[e] *= rs[e][1]; d[(size_t)e * 1024] = f2bf(v[e]); }
;             u32x2 wv; wv[0] = cvt_pk(v[0], v[1]); wv[1] = cvt_pk(v[2], v[3]);
;             *(u32x2*)((bf16_t*)(p.ws + OFF_KHATT) + kf_off(item, c & 255, idx)) = wv;
.LBB0_1322:
	s_andn2_saveexec_b64 s[68:69], s[68:69]
	s_cbranch_execz .LBB0_1324
	v_add_u32_e32 v72, 0xfffffc80, v176
	v_lshl_add_u64 v[74:75], s[36:37], 0, v[84:85]
	v_mov_b32_e32 v73, v133
	v_mul_f32_e64 v76, v68, v82
	v_mul_f32_e64 v77, v69, v83
	v_lshl_add_u64 v[74:75], v[72:73], 1, v[74:75]
	v_cvt_pk_bf16_f32 v73, v76, s0
	global_store_short v[74:75], v73, off
	v_cvt_pk_bf16_f32 v73, v77, s0
	global_store_short v[74:75], v73, off offset:2048
	v_mul_f32_e64 v78, v70, v80
	v_mul_f32_e64 v79, v71, v81
	v_add_co_u32_e32 v74, vcc, s35, v74
	v_cvt_pk_bf16_f32 v73, v78, s0
	s_nop 0
	v_addc_co_u32_e32 v75, vcc, 0, v75, vcc
	global_store_short v[74:75], v73, off
	v_cvt_pk_bf16_f32 v73, v79, s0
	global_store_short v[74:75], v73, off offset:2048
	v_lshrrev_b32_e32 v72, 3, v72
	v_and_b32_e32 v73, 28, v121
	v_and_or_b32 v72, v72, s77, v73
	v_add_u32_e32 v72, v72, v87
	v_cvt_pk_bf16_f32 v74, v76, v77
	v_cvt_pk_bf16_f32 v75, v78, v79
	v_ashrrev_i32_e32 v73, 31, v72
	v_and_b32_e32 v76, 19, v176
	v_lshlrev_b32_e32 v77, 1, v120
	v_lshrrev_b32_e32 v78, 1, v176
	v_lshlrev_b64 v[72:73], 6, v[72:73]
	v_and_b32_e32 v77, 8, v77
	v_and_or_b32 v76, v78, 4, v76
	v_or3_b32 v72, v76, v77, v72
	v_or_b32_e32 v72, v72, v86
	v_lshl_add_u64 v[72:73], v[72:73], 4, s[24:25]
	v_lshlrev_b32_e32 v76, 1, v177
	v_mov_b32_e32 v77, v133
	v_lshl_add_u64 v[72:73], v[72:73], 0, v[76:77]
	global_store_dwordx2 v[72:73], v[74:75], off

; DI unsigned cvt_pk(float lo, float hi) { f32x2 v = {lo, hi}; bf16x2v b = __builtin_convertvector(v, bf16x2v); return __builtin_bit_cast(unsigned, b); }
; DI bf16_t f2bf(float x) { return (bf16_t)(cvt_pk(x, 0.f) & 0xffffu); }
; DI size_t kf_off(int item, int dk, int j) { return ((size_t)((item * 8 + (dk >> 5)) * 4 + (j >> 4)) * 64 + ((j >> 3) & 1) * 32 + perm23(dk & 31)) * 8 + (j & 7); }
;     ...
;         } else if (col < 2048) {
;             const int c = col - 1024, hd = c >> 8, item = (ch * 4 + b) * 4 + hd;
;             bf16_t* d = (bf16_t*)(p.ws + OFF_KHAT) + (size_t)row0 * 1024 + c;
; #pragma unroll
;             for (int e = 0; e < 4; ++e) { v[e] *= rs[e][1]; d[(size_t)e * 1024] = f2bf(v[e]); }
;             u32x2 wv; wv[0] = cvt_pk(v[0], v[1]); wv[1] = cvt_pk(v[2], v[3]);
;             *(u32x2*)((bf16_t*)(p.ws + OFF_KHATT) + kf_off(item, c & 255, idx)) = wv;
.LBB0_1328:
	s_andn2_saveexec_b64 s[68:69], s[68:69]
	s_cbranch_execz .LBB0_1330
	v_add_u32_e32 v68, 0xfffffc90, v176
	v_lshl_add_u64 v[70:71], s[36:37], 0, v[84:85]
	v_mov_b32_e32 v69, v133
	v_mul_f32_e64 v72, v64, v82
	v_mul_f32_e64 v73, v65, v83
	v_lshl_add_u64 v[70:71], v[68:69], 1, v[70:71]
	v_cvt_pk_bf16_f32 v69, v72, s0
	global_store_short v[70:71], v69, off
	v_cvt_pk_bf16_f32 v69, v73, s0
	global_store_short v[70:71], v69, off offset:2048
	v_mul_f32_e64 v74, v66, v80
	v_mul_f32_e64 v75, v67, v81
	v_add_co_u32_e32 v70, vcc, s35, v70
	v_cvt_pk_bf16_f32 v69, v74, s0
	s_nop 0
	v_addc_co_u32_e32 v71, vcc, 0, v71, vcc
	global_store_short v[70:71], v69, off
	v_cvt_pk_bf16_f32 v69, v75, s0
	global_store_short v[70:71], v69, off offset:2048
	v_lshrrev_b32_e32 v68, 3, v68
	v_and_b32_e32 v69, 28, v119
	v_and_or_b32 v68, v68, s77, v69
	v_add_u32_e32 v68, v68, v87
	v_cvt_pk_bf16_f32 v70, v72, v73
	v_cvt_pk_bf16_f32 v71, v74, v75
	v_ashrrev_i32_e32 v69, 31, v68
	v_and_b32_e32 v72, 19, v118
	v_lshlrev_b32_e32 v73, 1, v118
	v_lshrrev_b32_e32 v74, 1, v176
	v_lshlrev_b64 v[68:69], 6, v[68:69]
	v_and_b32_e32 v73, 8, v73
	v_and_or_b32 v72, v74, 4, v72
	v_or3_b32 v68, v72, v73, v68
	v_or_b32_e32 v68, v68, v86
	v_lshl_add_u64 v[68:69], v[68:69], 4, s[24:25]
	v_lshlrev_b32_e32 v72, 1, v177
	v_mov_b32_e32 v73, v133
	v_lshl_add_u64 v[68:69], v[68:69], 0, v[72:73]
	global_store_dwordx2 v[68:69], v[70:71], off

; DI unsigned cvt_pk(float lo, float hi) { f32x2 v = {lo, hi}; bf16x2v b = __builtin_convertvector(v, bf16x2v); return __builtin_bit_cast(unsigned, b); }
; DI bf16_t f2bf(float x) { return (bf16_t)(cvt_pk(x, 0.f) & 0xffffu); }
; DI size_t kf_off(int item, int dk, int j) { return ((size_t)((item * 8 + (dk >> 5)) * 4 + (j >> 4)) * 64 + ((j >> 3) & 1) * 32 + perm23(dk & 31)) * 8 + (j & 7); }
;     ...
;         } else if (col < 2048) {
;             const int c = col - 1024, hd = c >> 8, item = (ch * 4 + b) * 4 + hd;
;             bf16_t* d = (bf16_t*)(p.ws + OFF_KHAT) + (size_t)row0 * 1024 + c;
; #pragma unroll
;             for (int e = 0; e < 4; ++e) { v[e] *= rs[e][1]; d[(size_t)e * 1024] = f2bf(v[e]); }
;             u32x2 wv; wv[0] = cvt_pk(v[0], v[1]); wv[1] = cvt_pk(v[2], v[3]);
;             *(u32x2*)((bf16_t*)(p.ws + OFF_KHATT) + kf_off(item, c & 255, idx)) = wv;
.LBB0_1334:
	s_andn2_saveexec_b64 s[68:69], s[68:69]
	s_cbranch_execz .LBB0_1336
	v_add_u32_e32 v60, 0xfffffc10, v176
	v_lshl_add_u64 v[62:63], s[36:37], 0, v[70:71]
	v_mov_b32_e32 v61, v133
	v_mul_f32_e64 v80, v56, v68
	v_mul_f32_e64 v81, v57, v69
	v_lshl_add_u64 v[62:63], v[60:61], 1, v[62:63]
	v_cvt_pk_bf16_f32 v61, v80, s0
	global_store_short v[62:63], v61, off
	v_cvt_pk_bf16_f32 v61, v81, s0
	global_store_short v[62:63], v61, off offset:2048
	v_mul_f32_e64 v82, v58, v66
	v_mul_f32_e64 v83, v59, v67
	v_add_co_u32_e32 v62, vcc, s35, v62
	v_cvt_pk_bf16_f32 v61, v82, s0
	s_nop 0
	v_addc_co_u32_e32 v63, vcc, 0, v63, vcc
	global_store_short v[62:63], v61, off
	v_cvt_pk_bf16_f32 v61, v83, s0
	global_store_short v[62:63], v61, off offset:2048
	v_lshrrev_b32_e32 v60, 3, v60
	v_and_b32_e32 v61, 28, v125
	v_and_or_b32 v60, v60, s77, v61
	v_add_u32_e32 v60, v60, v72
	v_cvt_pk_bf16_f32 v62, v80, v81
	v_cvt_pk_bf16_f32 v63, v82, v83
	v_ashrrev_i32_e32 v61, 31, v60
	v_and_b32_e32 v80, 19, v124
	v_lshlrev_b32_e32 v81, 1, v124
	v_lshrrev_b32_e32 v82, 1, v176
	v_lshlrev_b64 v[60:61], 6, v[60:61]
	v_and_b32_e32 v81, 8, v81
	v_and_or_b32 v80, v82, 4, v80
	v_or3_b32 v60, v80, v81, v60
	v_or_b32_e32 v60, v60, v65
	v_lshl_add_u64 v[60:61], v[60:61], 4, s[24:25]
	v_lshlrev_b32_e32 v80, 1, v177
	v_mov_b32_e32 v81, v133
	v_lshl_add_u64 v[60:61], v[60:61], 0, v[80:81]
	global_store_dwordx2 v[60:61], v[62:63], off

; DI unsigned cvt_pk(float lo, float hi) { f32x2 v = {lo, hi}; bf16x2v b = __builtin_convertvector(v, bf16x2v); return __builtin_bit_cast(unsigned, b); }
; DI bf16_t f2bf(float x) { return (bf16_t)(cvt_pk(x, 0.f) & 0xffffu); }
; DI size_t kf_off(int item, int dk, int j) { return ((size_t)((item * 8 + (dk >> 5)) * 4 + (j >> 4)) * 64 + ((j >> 3) & 1) * 32 + perm23(dk & 31)) * 8 + (j & 7); }
;     ...
;         } else if (col < 2048) {
;             const int c = col - 1024, hd = c >> 8, item = (ch * 4 + b) * 4 + hd;
;             bf16_t* d = (bf16_t*)(p.ws + OFF_KHAT) + (size_t)row0 * 1024 + c;
; #pragma unroll
;             for (int e = 0; e < 4; ++e) { v[e] *= rs[e][1]; d[(size_t)e * 1024] = f2bf(v[e]); }
;             u32x2 wv; wv[0] = cvt_pk(v[0], v[1]); wv[1] = cvt_pk(v[2], v[3]);
;             *(u32x2*)((bf16_t*)(p.ws + OFF_KHATT) + kf_off(item, c & 255, idx)) = wv;
.LBB0_1340:
	s_andn2_saveexec_b64 s[68:69], s[68:69]
	s_cbranch_execz .LBB0_1342
	v_add_u32_e32 v56, 0xfffffc80, v176
	v_lshl_add_u64 v[58:59], s[36:37], 0, v[70:71]
	v_mov_b32_e32 v57, v133
	v_mul_f32_e64 v60, v52, v68
	v_mul_f32_e64 v61, v53, v69
	v_lshl_add_u64 v[58:59], v[56:57], 1, v[58:59]
	v_cvt_pk_bf16_f32 v57, v60, s0
	global_store_short v[58:59], v57, off
	v_cvt_pk_bf16_f32 v57, v61, s0
	global_store_short v[58:59], v57, off offset:2048
	v_mul_f32_e64 v62, v54, v66
	v_mul_f32_e64 v63, v55, v67
	v_add_co_u32_e32 v58, vcc, s35, v58
	v_cvt_pk_bf16_f32 v57, v62, s0
	s_nop 0
	v_addc_co_u32_e32 v59, vcc, 0, v59, vcc
	global_store_short v[58:59], v57, off
	v_cvt_pk_bf16_f32 v57, v63, s0
	global_store_short v[58:59], v57, off offset:2048
	v_lshrrev_b32_e32 v56, 3, v56
	v_and_b32_e32 v57, 28, v121
	v_and_or_b32 v56, v56, s77, v57
	v_add_u32_e32 v56, v56, v72
	v_cvt_pk_bf16_f32 v58, v60, v61
	v_cvt_pk_bf16_f32 v59, v62, v63
	v_ashrrev_i32_e32 v57, 31, v56
	v_and_b32_e32 v60, 19, v176
	v_lshlrev_b32_e32 v61, 1, v120
	v_lshrrev_b32_e32 v62, 1, v176
	v_lshlrev_b64 v[56:57], 6, v[56:57]
	v_and_b32_e32 v61, 8, v61
	v_and_or_b32 v60, v62, 4, v60
	v_or3_b32 v56, v60, v61, v56
	v_or_b32_e32 v56, v56, v65
	v_lshl_add_u64 v[56:57], v[56:57], 4, s[24:25]
	v_lshlrev_b32_e32 v60, 1, v177
	v_mov_b32_e32 v61, v133
	v_lshl_add_u64 v[56:57], v[56:57], 0, v[60:61]
	global_store_dwordx2 v[56:57], v[58:59], off

; DI unsigned cvt_pk(float lo, float hi) { f32x2 v = {lo, hi}; bf16x2v b = __builtin_convertvector(v, bf16x2v); return __builtin_bit_cast(unsigned, b); }
; DI bf16_t f2bf(float x) { return (bf16_t)(cvt_pk(x, 0.f) & 0xffffu); }
; DI size_t kf_off(int item, int dk, int j) { return ((size_t)((item * 8 + (dk >> 5)) * 4 + (j >> 4)) * 64 + ((j >> 3) & 1) * 32 + perm23(dk & 31)) * 8 + (j & 7); }
;     ...
;         } else if (col < 2048) {
;             const int c = col - 1024, hd = c >> 8, item = (ch * 4 + b) * 4 + hd;
;             bf16_t* d = (bf16_t*)(p.ws + OFF_KHAT) + (size_t)row0 * 1024 + c;
; #pragma unroll
;             for (int e = 0; e < 4; ++e) { v[e] *= rs[e][1]; d[(size_t)e * 1024] = f2bf(v[e]); }
;             u32x2 wv; wv[0] = cvt_pk(v[0], v[1]); wv[1] = cvt_pk(v[2], v[3]);
;             *(u32x2*)((bf16_t*)(p.ws + OFF_KHATT) + kf_off(item, c & 255, idx)) = wv;
.LBB0_1346:
	s_andn2_saveexec_b64 s[68:69], s[68:69]
	s_cbranch_execz .LBB0_1348
	v_add_u32_e32 v52, 0xfffffc90, v176
	v_lshl_add_u64 v[54:55], s[36:37], 0, v[70:71]
	v_mov_b32_e32 v53, v133
	v_mul_f32_e64 v56, v48, v68
	v_mul_f32_e64 v57, v49, v69
	v_lshl_add_u64 v[54:55], v[52:53], 1, v[54:55]
	v_cvt_pk_bf16_f32 v53, v56, s0
	global_store_short v[54:55], v53, off
	v_cvt_pk_bf16_f32 v53, v57, s0
	global_store_short v[54:55], v53, off offset:2048
	v_mul_f32_e64 v58, v50, v66
	v_mul_f32_e64 v59, v51, v67
	v_add_co_u32_e32 v54, vcc, s35, v54
	v_cvt_pk_bf16_f32 v53, v58, s0
	s_nop 0
	v_addc_co_u32_e32 v55, vcc, 0, v55, vcc
	global_store_short v[54:55], v53, off
	v_cvt_pk_bf16_f32 v53, v59, s0
	global_store_short v[54:55], v53, off offset:2048
	v_lshrrev_b32_e32 v52, 3, v52
	v_and_b32_e32 v53, 28, v119
	v_and_or_b32 v52, v52, s77, v53
	v_add_u32_e32 v52, v52, v72
	v_cvt_pk_bf16_f32 v54, v56, v57
	v_cvt_pk_bf16_f32 v55, v58, v59
	v_ashrrev_i32_e32 v53, 31, v52
	v_and_b32_e32 v56, 19, v118
	v_lshlrev_b32_e32 v57, 1, v118
	v_lshrrev_b32_e32 v58, 1, v176
	v_lshlrev_b64 v[52:53], 6, v[52:53]
	v_and_b32_e32 v57, 8, v57
	v_and_or_b32 v56, v58, 4, v56
	v_or3_b32 v52, v56, v57, v52
	v_or_b32_e32 v52, v52, v65
	v_lshl_add_u64 v[52:53], v[52:53], 4, s[24:25]
	v_lshlrev_b32_e32 v56, 1, v177
	v_mov_b32_e32 v57, v133
	v_lshl_add_u64 v[52:53], v[52:53], 0, v[56:57]
	global_store_dwordx2 v[52:53], v[54:55], off

; DI unsigned cvt_pk(float lo, float hi) { f32x2 v = {lo, hi}; bf16x2v b = __builtin_convertvector(v, bf16x2v); return __builtin_bit_cast(unsigned, b); }
; DI bf16_t f2bf(float x) { return (bf16_t)(cvt_pk(x, 0.f) & 0xffffu); }
; DI size_t kf_off(int item, int dk, int j) { return ((size_t)((item * 8 + (dk >> 5)) * 4 + (j >> 4)) * 64 + ((j >> 3) & 1) * 32 + perm23(dk & 31)) * 8 + (j & 7); }
;     ...
;         } else if (col < 2048) {
;             const int c = col - 1024, hd = c >> 8, item = (ch * 4 + b) * 4 + hd;
;             bf16_t* d = (bf16_t*)(p.ws + OFF_KHAT) + (size_t)row0 * 1024 + c;
; #pragma unroll
;             for (int e = 0; e < 4; ++e) { v[e] *= rs[e][1]; d[(size_t)e * 1024] = f2bf(v[e]); }
;             u32x2 wv; wv[0] = cvt_pk(v[0], v[1]); wv[1] = cvt_pk(v[2], v[3]);
;             *(u32x2*)((bf16_t*)(p.ws + OFF_KHATT) + kf_off(item, c & 255, idx)) = wv;
.LBB0_1352:
	s_andn2_saveexec_b64 s[68:69], s[68:69]
	s_cbranch_execz .LBB0_1354
	v_add_u32_e32 v44, 0xfffffc10, v176
	v_lshl_add_u64 v[46:47], s[36:37], 0, v[52:53]
	v_mov_b32_e32 v45, v133
	v_mul_f32_e64 v66, v40, v50
	v_mul_f32_e64 v67, v41, v51
	v_lshl_add_u64 v[46:47], v[44:45], 1, v[46:47]
	v_cvt_pk_bf16_f32 v45, v66, s0
	global_store_short v[46:47], v45, off
	v_cvt_pk_bf16_f32 v45, v67, s0
	global_store_short v[46:47], v45, off offset:2048
	v_mul_f32_e64 v68, v42, v48
	v_mul_f32_e64 v69, v43, v49
	v_add_co_u32_e32 v46, vcc, s35, v46
	v_cvt_pk_bf16_f32 v45, v68, s0
	s_nop 0
	v_addc_co_u32_e32 v47, vcc, 0, v47, vcc
	global_store_short v[46:47], v45, off
	v_cvt_pk_bf16_f32 v45, v69, s0
	global_store_short v[46:47], v45, off offset:2048
	v_lshrrev_b32_e32 v44, 3, v44
	v_and_b32_e32 v45, 28, v125
	v_and_or_b32 v44, v44, s77, v45
	v_add_u32_e32 v44, v44, v55
	v_cvt_pk_bf16_f32 v46, v66, v67
	v_ashrrev_i32_e32 v45, 31, v44
	v_and_b32_e32 v63, 19, v124
	v_lshlrev_b32_e32 v65, 1, v124
	v_lshrrev_b32_e32 v66, 1, v176
	v_lshlrev_b64 v[44:45], 6, v[44:45]
	v_and_b32_e32 v65, 8, v65
	v_and_or_b32 v63, v66, 4, v63
	v_or3_b32 v44, v63, v65, v44
	v_or_b32_e32 v44, v44, v54
	v_lshl_add_u64 v[44:45], v[44:45], 4, s[24:25]
	v_lshlrev_b32_e32 v66, 1, v177
	v_mov_b32_e32 v67, v133
	v_cvt_pk_bf16_f32 v47, v68, v69
	v_lshl_add_u64 v[44:45], v[44:45], 0, v[66:67]
	global_store_dwordx2 v[44:45], v[46:47], off

; DI unsigned cvt_pk(float lo, float hi) { f32x2 v = {lo, hi}; bf16x2v b = __builtin_convertvector(v, bf16x2v); return __builtin_bit_cast(unsigned, b); }
; DI bf16_t f2bf(float x) { return (bf16_t)(cvt_pk(x, 0.f) & 0xffffu); }
; DI size_t kf_off(int item, int dk, int j) { return ((size_t)((item * 8 + (dk >> 5)) * 4 + (j >> 4)) * 64 + ((j >> 3) & 1) * 32 + perm23(dk & 31)) * 8 + (j & 7); }
;     ...
;         } else if (col < 2048) {
;             const int c = col - 1024, hd = c >> 8, item = (ch * 4 + b) * 4 + hd;
;             bf16_t* d = (bf16_t*)(p.ws + OFF_KHAT) + (size_t)row0 * 1024 + c;
; #pragma unroll
;             for (int e = 0; e < 4; ++e) { v[e] *= rs[e][1]; d[(size_t)e * 1024] = f2bf(v[e]); }
;             u32x2 wv; wv[0] = cvt_pk(v[0], v[1]); wv[1] = cvt_pk(v[2], v[3]);
;             *(u32x2*)((bf16_t*)(p.ws + OFF_KHATT) + kf_off(item, c & 255, idx)) = wv;
.LBB0_1358:
	s_andn2_saveexec_b64 s[68:69], s[68:69]
	s_cbranch_execz .LBB0_1360
	v_add_u32_e32 v40, 0xfffffc80, v176
	v_lshl_add_u64 v[42:43], s[36:37], 0, v[52:53]
	v_mov_b32_e32 v41, v133
	v_mul_f32_e64 v44, v36, v50
	v_mul_f32_e64 v45, v37, v51
	v_lshl_add_u64 v[42:43], v[40:41], 1, v[42:43]
	v_cvt_pk_bf16_f32 v41, v44, s0
	global_store_short v[42:43], v41, off
	v_cvt_pk_bf16_f32 v41, v45, s0
	global_store_short v[42:43], v41, off offset:2048
	v_mul_f32_e64 v46, v38, v48
	v_mul_f32_e64 v47, v39, v49
	v_add_co_u32_e32 v42, vcc, s35, v42
	v_cvt_pk_bf16_f32 v41, v46, s0
	s_nop 0
	v_addc_co_u32_e32 v43, vcc, 0, v43, vcc
	global_store_short v[42:43], v41, off
	v_cvt_pk_bf16_f32 v41, v47, s0
	global_store_short v[42:43], v41, off offset:2048
	v_lshrrev_b32_e32 v40, 3, v40
	v_and_b32_e32 v41, 28, v121
	v_and_or_b32 v40, v40, s77, v41
	v_add_u32_e32 v40, v40, v55
	v_cvt_pk_bf16_f32 v42, v44, v45
	v_cvt_pk_bf16_f32 v43, v46, v47
	v_ashrrev_i32_e32 v41, 31, v40
	v_and_b32_e32 v44, 19, v176
	v_lshlrev_b32_e32 v45, 1, v120
	v_lshrrev_b32_e32 v46, 1, v176
	v_lshlrev_b64 v[40:41], 6, v[40:41]
	v_and_b32_e32 v45, 8, v45
	v_and_or_b32 v44, v46, 4, v44
	v_or3_b32 v40, v44, v45, v40
	v_or_b32_e32 v40, v40, v54
	v_lshl_add_u64 v[40:41], v[40:41], 4, s[24:25]
	v_lshlrev_b32_e32 v44, 1, v177
	v_mov_b32_e32 v45, v133
	v_lshl_add_u64 v[40:41], v[40:41], 0, v[44:45]
	global_store_dwordx2 v[40:41], v[42:43], off

; DI unsigned cvt_pk(float lo, float hi) { f32x2 v = {lo, hi}; bf16x2v b = __builtin_convertvector(v, bf16x2v); return __builtin_bit_cast(unsigned, b); }
; DI bf16_t f2bf(float x) { return (bf16_t)(cvt_pk(x, 0.f) & 0xffffu); }
; DI size_t kf_off(int item, int dk, int j) { return ((size_t)((item * 8 + (dk >> 5)) * 4 + (j >> 4)) * 64 + ((j >> 3) & 1) * 32 + perm23(dk & 31)) * 8 + (j & 7); }
;     ...
;         } else if (col < 2048) {
;             const int c = col - 1024, hd = c >> 8, item = (ch * 4 + b) * 4 + hd;
;             bf16_t* d = (bf16_t*)(p.ws + OFF_KHAT) + (size_t)row0 * 1024 + c;
; #pragma unroll
;             for (int e = 0; e < 4; ++e) { v[e] *= rs[e][1]; d[(size_t)e * 1024] = f2bf(v[e]); }
;             u32x2 wv; wv[0] = cvt_pk(v[0], v[1]); wv[1] = cvt_pk(v[2], v[3]);
;             *(u32x2*)((bf16_t*)(p.ws + OFF_KHATT) + kf_off(item, c & 255, idx)) = wv;
.LBB0_1364:
	s_andn2_saveexec_b64 s[68:69], s[68:69]
	s_cbranch_execz .LBB0_1366
	v_add_u32_e32 v36, 0xfffffc90, v176
	v_lshl_add_u64 v[38:39], s[36:37], 0, v[52:53]
	v_mov_b32_e32 v37, v133
	v_mul_f32_e64 v40, v32, v50
	v_mul_f32_e64 v41, v33, v51
	v_lshl_add_u64 v[38:39], v[36:37], 1, v[38:39]
	v_cvt_pk_bf16_f32 v37, v40, s0
	global_store_short v[38:39], v37, off
	v_cvt_pk_bf16_f32 v37, v41, s0
	global_store_short v[38:39], v37, off offset:2048
	v_mul_f32_e64 v42, v34, v48
	v_mul_f32_e64 v43, v35, v49
	v_add_co_u32_e32 v38, vcc, s35, v38
	v_cvt_pk_bf16_f32 v37, v42, s0
	s_nop 0
	v_addc_co_u32_e32 v39, vcc, 0, v39, vcc
	global_store_short v[38:39], v37, off
	v_cvt_pk_bf16_f32 v37, v43, s0
	global_store_short v[38:39], v37, off offset:2048
	v_lshrrev_b32_e32 v36, 3, v36
	v_and_b32_e32 v37, 28, v119
	v_and_or_b32 v36, v36, s77, v37
	v_add_u32_e32 v36, v36, v55
	v_cvt_pk_bf16_f32 v38, v40, v41
	v_cvt_pk_bf16_f32 v39, v42, v43
	v_ashrrev_i32_e32 v37, 31, v36
	v_and_b32_e32 v40, 19, v118
	v_lshlrev_b32_e32 v41, 1, v118
	v_lshrrev_b32_e32 v42, 1, v176
	v_lshlrev_b64 v[36:37], 6, v[36:37]
	v_and_b32_e32 v41, 8, v41
	v_and_or_b32 v40, v42, 4, v40
	v_or3_b32 v36, v40, v41, v36
	v_or_b32_e32 v36, v36, v54
	v_lshl_add_u64 v[36:37], v[36:37], 4, s[24:25]
	v_lshlrev_b32_e32 v40, 1, v177
	v_mov_b32_e32 v41, v133
	v_lshl_add_u64 v[36:37], v[36:37], 0, v[40:41]
	global_store_dwordx2 v[36:37], v[38:39], off

; DI unsigned cvt_pk(float lo, float hi) { f32x2 v = {lo, hi}; bf16x2v b = __builtin_convertvector(v, bf16x2v); return __builtin_bit_cast(unsigned, b); }
; DI bf16_t f2bf(float x) { return (bf16_t)(cvt_pk(x, 0.f) & 0xffffu); }
; DI size_t kf_off(int item, int dk, int j) { return ((size_t)((item * 8 + (dk >> 5)) * 4 + (j >> 4)) * 64 + ((j >> 3) & 1) * 32 + perm23(dk & 31)) * 8 + (j & 7); }
;     ...
;         } else if (col < 2048) {
;             const int c = col - 1024, hd = c >> 8, item = (ch * 4 + b) * 4 + hd;
;             bf16_t* d = (bf16_t*)(p.ws + OFF_KHAT) + (size_t)row0 * 1024 + c;
; #pragma unroll
;             for (int e = 0; e < 4; ++e) { v[e] *= rs[e][1]; d[(size_t)e * 1024] = f2bf(v[e]); }
;             u32x2 wv; wv[0] = cvt_pk(v[0], v[1]); wv[1] = cvt_pk(v[2], v[3]);
;             *(u32x2*)((bf16_t*)(p.ws + OFF_KHATT) + kf_off(item, c & 255, idx)) = wv;
.LBB0_1370:
	s_andn2_saveexec_b64 s[68:69], s[68:69]
	s_cbranch_execz .LBB0_1372
	v_add_u32_e32 v28, 0xfffffc10, v176
	v_lshl_add_u64 v[30:31], s[36:37], 0, v[36:37]
	v_mov_b32_e32 v29, v133
	v_mul_f32_e64 v48, v24, v34
	v_mul_f32_e64 v49, v25, v35
	v_lshl_add_u64 v[30:31], v[28:29], 1, v[30:31]
	v_cvt_pk_bf16_f32 v29, v48, s0
	global_store_short v[30:31], v29, off
	v_cvt_pk_bf16_f32 v29, v49, s0
	global_store_short v[30:31], v29, off offset:2048
	v_mul_f32_e64 v50, v26, v32
	v_mul_f32_e64 v51, v27, v33
	v_add_co_u32_e32 v30, vcc, s35, v30
	v_cvt_pk_bf16_f32 v29, v50, s0
	s_nop 0
	v_addc_co_u32_e32 v31, vcc, 0, v31, vcc
	global_store_short v[30:31], v29, off
	v_cvt_pk_bf16_f32 v29, v51, s0
	global_store_short v[30:31], v29, off offset:2048
	v_lshrrev_b32_e32 v28, 3, v28
	v_and_b32_e32 v29, 28, v125
	v_and_or_b32 v28, v28, s77, v29
	v_add_u32_e32 v28, v28, v39
	v_cvt_pk_bf16_f32 v30, v48, v49
	v_ashrrev_i32_e32 v29, 31, v28
	v_and_b32_e32 v47, 19, v124
	v_lshlrev_b32_e32 v48, 1, v124
	v_lshrrev_b32_e32 v49, 1, v176
	v_lshlrev_b64 v[28:29], 6, v[28:29]
	v_and_b32_e32 v48, 8, v48
	v_and_or_b32 v47, v49, 4, v47
	v_or3_b32 v28, v47, v48, v28
	v_or_b32_e32 v28, v28, v38
	v_lshl_add_u64 v[28:29], v[28:29], 4, s[24:25]
	v_lshlrev_b32_e32 v48, 1, v177
	v_mov_b32_e32 v49, v133
	v_cvt_pk_bf16_f32 v31, v50, v51
	v_lshl_add_u64 v[28:29], v[28:29], 0, v[48:49]
	global_store_dwordx2 v[28:29], v[30:31], off

; DI unsigned cvt_pk(float lo, float hi) { f32x2 v = {lo, hi}; bf16x2v b = __builtin_convertvector(v, bf16x2v); return __builtin_bit_cast(unsigned, b); }
; DI bf16_t f2bf(float x) { return (bf16_t)(cvt_pk(x, 0.f) & 0xffffu); }
; DI size_t kf_off(int item, int dk, int j) { return ((size_t)((item * 8 + (dk >> 5)) * 4 + (j >> 4)) * 64 + ((j >> 3) & 1) * 32 + perm23(dk & 31)) * 8 + (j & 7); }
;     ...
;         } else if (col < 2048) {
;             const int c = col - 1024, hd = c >> 8, item = (ch * 4 + b) * 4 + hd;
;             bf16_t* d = (bf16_t*)(p.ws + OFF_KHAT) + (size_t)row0 * 1024 + c;
; #pragma unroll
;             for (int e = 0; e < 4; ++e) { v[e] *= rs[e][1]; d[(size_t)e * 1024] = f2bf(v[e]); }
;             u32x2 wv; wv[0] = cvt_pk(v[0], v[1]); wv[1] = cvt_pk(v[2], v[3]);
;             *(u32x2*)((bf16_t*)(p.ws + OFF_KHATT) + kf_off(item, c & 255, idx)) = wv;
.LBB0_1376:
	s_andn2_saveexec_b64 s[68:69], s[68:69]
	s_cbranch_execz .LBB0_1378
	v_add_u32_e32 v24, 0xfffffc80, v176
	v_lshl_add_u64 v[26:27], s[36:37], 0, v[36:37]
	v_mov_b32_e32 v25, v133
	v_mul_f32_e64 v28, v20, v34
	v_mul_f32_e64 v29, v21, v35
	v_lshl_add_u64 v[26:27], v[24:25], 1, v[26:27]
	v_cvt_pk_bf16_f32 v25, v28, s0
	global_store_short v[26:27], v25, off
	v_cvt_pk_bf16_f32 v25, v29, s0
	global_store_short v[26:27], v25, off offset:2048
	v_mul_f32_e64 v30, v22, v32
	v_mul_f32_e64 v31, v23, v33
	v_add_co_u32_e32 v26, vcc, s35, v26
	v_cvt_pk_bf16_f32 v25, v30, s0
	s_nop 0
	v_addc_co_u32_e32 v27, vcc, 0, v27, vcc
	global_store_short v[26:27], v25, off
	v_cvt_pk_bf16_f32 v25, v31, s0
	global_store_short v[26:27], v25, off offset:2048
	v_lshrrev_b32_e32 v24, 3, v24
	v_and_b32_e32 v25, 28, v121
	v_and_or_b32 v24, v24, s77, v25
	v_add_u32_e32 v24, v24, v39
	v_cvt_pk_bf16_f32 v26, v28, v29
	v_cvt_pk_bf16_f32 v27, v30, v31
	v_ashrrev_i32_e32 v25, 31, v24
	v_and_b32_e32 v28, 19, v176
	v_lshlrev_b32_e32 v29, 1, v120
	v_lshrrev_b32_e32 v30, 1, v176
	v_lshlrev_b64 v[24:25], 6, v[24:25]
	v_and_b32_e32 v29, 8, v29
	v_and_or_b32 v28, v30, 4, v28
	v_or3_b32 v24, v28, v29, v24
	v_or_b32_e32 v24, v24, v38
	v_lshl_add_u64 v[24:25], v[24:25], 4, s[24:25]
	v_lshlrev_b32_e32 v28, 1, v177
	v_mov_b32_e32 v29, v133
	v_lshl_add_u64 v[24:25], v[24:25], 0, v[28:29]
	global_store_dwordx2 v[24:25], v[26:27], off

; DI unsigned cvt_pk(float lo, float hi) { f32x2 v = {lo, hi}; bf16x2v b = __builtin_convertvector(v, bf16x2v); return __builtin_bit_cast(unsigned, b); }
; DI bf16_t f2bf(float x) { return (bf16_t)(cvt_pk(x, 0.f) & 0xffffu); }
; DI size_t kf_off(int item, int dk, int j) { return ((size_t)((item * 8 + (dk >> 5)) * 4 + (j >> 4)) * 64 + ((j >> 3) & 1) * 32 + perm23(dk & 31)) * 8 + (j & 7); }
;     ...
;         } else if (col < 2048) {
;             const int c = col - 1024, hd = c >> 8, item = (ch * 4 + b) * 4 + hd;
;             bf16_t* d = (bf16_t*)(p.ws + OFF_KHAT) + (size_t)row0 * 1024 + c;
; #pragma unroll
;             for (int e = 0; e < 4; ++e) { v[e] *= rs[e][1]; d[(size_t)e * 1024] = f2bf(v[e]); }
;             u32x2 wv; wv[0] = cvt_pk(v[0], v[1]); wv[1] = cvt_pk(v[2], v[3]);
;             *(u32x2*)((bf16_t*)(p.ws + OFF_KHATT) + kf_off(item, c & 255, idx)) = wv;
.LBB0_1382:
	s_andn2_saveexec_b64 s[68:69], s[68:69]
	s_cbranch_execz .LBB0_1384
	v_add_u32_e32 v20, 0xfffffc90, v176
	v_lshl_add_u64 v[22:23], s[36:37], 0, v[36:37]
	v_mov_b32_e32 v21, v133
	v_mul_f32_e64 v24, v16, v34
	v_mul_f32_e64 v25, v17, v35
	v_lshl_add_u64 v[22:23], v[20:21], 1, v[22:23]
	v_cvt_pk_bf16_f32 v21, v24, s0
	global_store_short v[22:23], v21, off
	v_cvt_pk_bf16_f32 v21, v25, s0
	global_store_short v[22:23], v21, off offset:2048
	v_mul_f32_e64 v26, v18, v32
	v_mul_f32_e64 v27, v19, v33
	v_add_co_u32_e32 v22, vcc, s35, v22
	v_cvt_pk_bf16_f32 v21, v26, s0
	s_nop 0
	v_addc_co_u32_e32 v23, vcc, 0, v23, vcc
	global_store_short v[22:23], v21, off
	v_cvt_pk_bf16_f32 v21, v27, s0
	global_store_short v[22:23], v21, off offset:2048
	v_lshrrev_b32_e32 v20, 3, v20
	v_and_b32_e32 v21, 28, v119
	v_and_or_b32 v20, v20, s77, v21
	v_add_u32_e32 v20, v20, v39
	v_cvt_pk_bf16_f32 v22, v24, v25
	v_cvt_pk_bf16_f32 v23, v26, v27
	v_ashrrev_i32_e32 v21, 31, v20
	v_and_b32_e32 v24, 19, v118
	v_lshlrev_b32_e32 v25, 1, v118
	v_lshrrev_b32_e32 v26, 1, v176
	v_lshlrev_b64 v[20:21], 6, v[20:21]
	v_and_b32_e32 v25, 8, v25
	v_and_or_b32 v24, v26, 4, v24
	v_or3_b32 v20, v24, v25, v20
	v_or_b32_e32 v20, v20, v38
	v_lshl_add_u64 v[20:21], v[20:21], 4, s[24:25]
	v_lshlrev_b32_e32 v24, 1, v177
	v_mov_b32_e32 v25, v133
	v_lshl_add_u64 v[20:21], v[20:21], 0, v[24:25]
	global_store_dwordx2 v[20:21], v[22:23], off

; DI unsigned cvt_pk(float lo, float hi) { f32x2 v = {lo, hi}; bf16x2v b = __builtin_convertvector(v, bf16x2v); return __builtin_bit_cast(unsigned, b); }
; DI bf16_t f2bf(float x) { return (bf16_t)(cvt_pk(x, 0.f) & 0xffffu); }
; DI size_t kf_off(int item, int dk, int j) { return ((size_t)((item * 8 + (dk >> 5)) * 4 + (j >> 4)) * 64 + ((j >> 3) & 1) * 32 + perm23(dk & 31)) * 8 + (j & 7); }
;     ...
;         } else if (col < 2048) {
;             const int c = col - 1024, hd = c >> 8, item = (ch * 4 + b) * 4 + hd;
;             bf16_t* d = (bf16_t*)(p.ws + OFF_KHAT) + (size_t)row0 * 1024 + c;
; #pragma unroll
;             for (int e = 0; e < 4; ++e) { v[e] *= rs[e][1]; d[(size_t)e * 1024] = f2bf(v[e]); }
;             u32x2 wv; wv[0] = cvt_pk(v[0], v[1]); wv[1] = cvt_pk(v[2], v[3]);
;             *(u32x2*)((bf16_t*)(p.ws + OFF_KHATT) + kf_off(item, c & 255, idx)) = wv;
.LBB0_1388:
	s_andn2_saveexec_b64 s[14:15], s[14:15]
	s_cbranch_execz .LBB0_1390
	v_add_u32_e32 v12, 0xfffffc10, v176
	v_lshl_add_u64 v[14:15], s[36:37], 0, v[20:21]
	v_mov_b32_e32 v13, v133
	v_mul_f32_e64 v32, v8, v18
	v_mul_f32_e64 v33, v9, v19
	v_lshl_add_u64 v[14:15], v[12:13], 1, v[14:15]
	v_cvt_pk_bf16_f32 v13, v32, s0
	global_store_short v[14:15], v13, off
	v_cvt_pk_bf16_f32 v13, v33, s0
	global_store_short v[14:15], v13, off offset:2048
	v_mul_f32_e64 v34, v10, v16
	v_mul_f32_e64 v35, v11, v17
	v_add_co_u32_e32 v14, vcc, s35, v14
	v_cvt_pk_bf16_f32 v13, v34, s0
	s_nop 0
	v_addc_co_u32_e32 v15, vcc, 0, v15, vcc
	global_store_short v[14:15], v13, off
	v_cvt_pk_bf16_f32 v13, v35, s0
	global_store_short v[14:15], v13, off offset:2048
	v_lshrrev_b32_e32 v12, 3, v12
	v_and_b32_e32 v13, 28, v125
	v_and_or_b32 v12, v12, s77, v13
	v_add_u32_e32 v12, v12, v23
	v_cvt_pk_bf16_f32 v14, v32, v33
	v_ashrrev_i32_e32 v13, 31, v12
	v_and_b32_e32 v31, 19, v124
	v_lshlrev_b32_e32 v32, 1, v124
	v_lshrrev_b32_e32 v33, 1, v176
	v_lshlrev_b64 v[12:13], 6, v[12:13]
	v_and_b32_e32 v32, 8, v32
	v_and_or_b32 v31, v33, 4, v31
	v_or3_b32 v12, v31, v32, v12
	v_or_b32_e32 v12, v12, v22
	v_lshl_add_u64 v[12:13], v[12:13], 4, s[24:25]
	v_lshlrev_b32_e32 v32, 1, v177
	v_mov_b32_e32 v33, v133
	v_cvt_pk_bf16_f32 v15, v34, v35
	v_lshl_add_u64 v[12:13], v[12:13], 0, v[32:33]
	global_store_dwordx2 v[12:13], v[14:15], off

; DI unsigned cvt_pk(float lo, float hi) { f32x2 v = {lo, hi}; bf16x2v b = __builtin_convertvector(v, bf16x2v); return __builtin_bit_cast(unsigned, b); }
; DI bf16_t f2bf(float x) { return (bf16_t)(cvt_pk(x, 0.f) & 0xffffu); }
; DI size_t kf_off(int item, int dk, int j) { return ((size_t)((item * 8 + (dk >> 5)) * 4 + (j >> 4)) * 64 + ((j >> 3) & 1) * 32 + perm23(dk & 31)) * 8 + (j & 7); }
;     ...
;         } else if (col < 2048) {
;             const int c = col - 1024, hd = c >> 8, item = (ch * 4 + b) * 4 + hd;
;             bf16_t* d = (bf16_t*)(p.ws + OFF_KHAT) + (size_t)row0 * 1024 + c;
; #pragma unroll
;             for (int e = 0; e < 4; ++e) { v[e] *= rs[e][1]; d[(size_t)e * 1024] = f2bf(v[e]); }
;             u32x2 wv; wv[0] = cvt_pk(v[0], v[1]); wv[1] = cvt_pk(v[2], v[3]);
;             *(u32x2*)((bf16_t*)(p.ws + OFF_KHATT) + kf_off(item, c & 255, idx)) = wv;
.LBB0_1394:
	s_andn2_saveexec_b64 s[12:13], s[12:13]
	s_cbranch_execz .LBB0_1396
	v_add_u32_e32 v8, 0xfffffc80, v176
	v_lshl_add_u64 v[10:11], s[36:37], 0, v[20:21]
	v_mov_b32_e32 v9, v133
	v_mul_f32_e64 v12, v4, v18
	v_mul_f32_e64 v13, v5, v19
	v_lshl_add_u64 v[10:11], v[8:9], 1, v[10:11]
	v_cvt_pk_bf16_f32 v9, v12, s0
	global_store_short v[10:11], v9, off
	v_cvt_pk_bf16_f32 v9, v13, s0
	global_store_short v[10:11], v9, off offset:2048
	v_mul_f32_e64 v14, v6, v16
	v_mul_f32_e64 v15, v7, v17
	v_add_co_u32_e32 v10, vcc, s35, v10
	v_cvt_pk_bf16_f32 v9, v14, s0
	s_nop 0
	v_addc_co_u32_e32 v11, vcc, 0, v11, vcc
	global_store_short v[10:11], v9, off
	v_cvt_pk_bf16_f32 v9, v15, s0
	global_store_short v[10:11], v9, off offset:2048
	v_lshrrev_b32_e32 v8, 3, v8
	v_and_b32_e32 v9, 28, v121
	v_and_or_b32 v8, v8, s77, v9
	v_add_u32_e32 v8, v8, v23
	v_cvt_pk_bf16_f32 v10, v12, v13
	v_cvt_pk_bf16_f32 v11, v14, v15
	v_ashrrev_i32_e32 v9, 31, v8
	v_and_b32_e32 v12, 19, v176
	v_lshlrev_b32_e32 v13, 1, v120
	v_lshrrev_b32_e32 v14, 1, v176
	v_lshlrev_b64 v[8:9], 6, v[8:9]
	v_and_b32_e32 v13, 8, v13
	v_and_or_b32 v12, v14, 4, v12
	v_or3_b32 v8, v12, v13, v8
	v_or_b32_e32 v8, v8, v22
	v_lshl_add_u64 v[8:9], v[8:9], 4, s[24:25]
	v_lshlrev_b32_e32 v12, 1, v177
	v_mov_b32_e32 v13, v133
	v_lshl_add_u64 v[8:9], v[8:9], 0, v[12:13]
	global_store_dwordx2 v[8:9], v[10:11], off

; DI unsigned cvt_pk(float lo, float hi) { f32x2 v = {lo, hi}; bf16x2v b = __builtin_convertvector(v, bf16x2v); return __builtin_bit_cast(unsigned, b); }
; DI bf16_t f2bf(float x) { return (bf16_t)(cvt_pk(x, 0.f) & 0xffffu); }
; DI size_t kf_off(int item, int dk, int j) { return ((size_t)((item * 8 + (dk >> 5)) * 4 + (j >> 4)) * 64 + ((j >> 3) & 1) * 32 + perm23(dk & 31)) * 8 + (j & 7); }
;     ...
;         } else if (col < 2048) {
;             const int c = col - 1024, hd = c >> 8, item = (ch * 4 + b) * 4 + hd;
;             bf16_t* d = (bf16_t*)(p.ws + OFF_KHAT) + (size_t)row0 * 1024 + c;
; #pragma unroll
;             for (int e = 0; e < 4; ++e) { v[e] *= rs[e][1]; d[(size_t)e * 1024] = f2bf(v[e]); }
;             u32x2 wv; wv[0] = cvt_pk(v[0], v[1]); wv[1] = cvt_pk(v[2], v[3]);
;             *(u32x2*)((bf16_t*)(p.ws + OFF_KHATT) + kf_off(item, c & 255, idx)) = wv;
.LBB0_1400:
	s_andn2_saveexec_b64 s[10:11], s[10:11]
	s_cbranch_execz .LBB0_1402
	v_add_u32_e32 v132, 0xfffffc90, v176
	v_lshl_add_u64 v[4:5], s[36:37], 0, v[20:21]
	v_mul_f32_e64 v6, v0, v18
	v_mul_f32_e64 v7, v1, v19
	v_lshl_add_u64 v[4:5], v[132:133], 1, v[4:5]
	v_cvt_pk_bf16_f32 v8, v6, s0
	global_store_short v[4:5], v8, off
	v_cvt_pk_bf16_f32 v8, v7, s0
	global_store_short v[4:5], v8, off offset:2048
	v_mul_f32_e64 v8, v2, v16
	v_mul_f32_e64 v9, v3, v17
	v_add_co_u32_e32 v4, vcc, s35, v4
	v_cvt_pk_bf16_f32 v10, v8, s0
	s_nop 0
	v_addc_co_u32_e32 v5, vcc, 0, v5, vcc
	global_store_short v[4:5], v10, off
	v_cvt_pk_bf16_f32 v10, v9, s0
	global_store_short v[4:5], v10, off offset:2048
	v_cvt_pk_bf16_f32 v4, v6, v7
	v_lshrrev_b32_e32 v6, 3, v132
	v_and_b32_e32 v7, 28, v119
	v_and_or_b32 v6, v6, s77, v7
	v_add_u32_e32 v6, v6, v23
	v_cvt_pk_bf16_f32 v5, v8, v9
	v_ashrrev_i32_e32 v7, 31, v6
	v_and_b32_e32 v8, 19, v118
	v_lshlrev_b32_e32 v9, 1, v118
	v_lshrrev_b32_e32 v10, 1, v176
	v_lshlrev_b64 v[6:7], 6, v[6:7]
	v_and_b32_e32 v9, 8, v9
	v_and_or_b32 v8, v10, 4, v8
	v_or3_b32 v6, v8, v9, v6
	v_or_b32_e32 v6, v6, v22
	v_lshl_add_u64 v[6:7], v[6:7], 4, s[24:25]
	v_lshlrev_b32_e32 v132, 1, v177
	v_lshl_add_u64 v[6:7], v[6:7], 0, v[132:133]
	global_store_dwordx2 v[6:7], v[4:5], off

; DI f32x16 zero16() { f32x16 z; for (int i = 0; i < 16; ++i) z[i] = 0.f; return z; }
; template <int EPI, int K, int LNI>
; DI void gemm_tail_unit(const Params& p, const bf16_t* __restrict__ A, const bf16_t* __restrict__ Bt, const int un, float* s_aux) {
;     ...
;     f32x16 acc[2][2];
;     acc[0][0] = zero16(); acc[0][1] = zero16(); acc[1][0] = zero16(); acc[1][1] = zero16();
;     const bf16_t* ap = A + (size_t)(ROW0 + r) * K + w * KS + h * 8;
;     const bf16_t* bp = Bt + (size_t)(col0 + r) * K + w * KS + h * 8;
; #pragma unroll 8
;     for (int s = 0; s < KS / 16; ++s) {
;         const bf16x8 a0 = *(const bf16x8*)(ap + s * 16), a1 = *(const bf16x8*)(ap + (size_t)32 * K + s * 16);
;         const bf16x8 b0 = *(const bf16x8*)(bp + s * 16), b1 = *(const bf16x8*)(bp + (size_t)32 * K + s * 16);
.LBB0_1409:
	v_mov_b32_e32 v69, v210
	s_bfe_u32 s6, s50, 0x20002
	v_ashrrev_i32_e32 v116, 6, v69
	v_and_b32_e32 v68, 31, v69
	v_lshlrev_b32_e32 v2, 7, v116
	v_lshlrev_b32_e32 v64, 11, v68
	v_ashrrev_i32_e32 v3, 31, v2
	v_bfe_u32 v117, v69, 5, 1
	v_lshl_add_u64 v[0:1], s[40:41], 0, v[64:65]
	v_lshlrev_b64 v[4:5], 1, v[2:3]
	v_lshl_add_u64 v[0:1], v[0:1], 0, v[4:5]
	v_lshlrev_b32_e32 v64, 4, v117
	v_add_u32_e32 v108, s3, v68
	v_lshl_add_u64 v[12:13], v[0:1], 0, v[64:65]
	v_ashrrev_i32_e32 v109, 31, v108
	v_lshlrev_b64 v[6:7], 11, v[108:109]
	v_add_co_u32_e32 v0, vcc, s28, v12
	v_lshl_add_u64 v[6:7], s[26:27], 0, v[6:7]
	s_nop 0
	v_addc_co_u32_e32 v1, vcc, 0, v13, vcc
	s_nop 0
	v_readfirstlane_b32 s88, v0
	v_readfirstlane_b32 s89, v1
	v_lshl_add_u64 v[4:5], v[6:7], 0, v[4:5]
	v_lshl_add_u64 v[70:71], v[4:5], 0, v[64:65]
	v_add_co_u32_e32 v112, vcc, s35, v70
	v_lshl_add_u64 v[110:111], v[12:13], 0, s[8:9]
	s_nop 0
	v_addc_co_u32_e32 v113, vcc, 0, v71, vcc
	s_nop 0
	v_readfirstlane_b32 s90, v70
	v_readfirstlane_b32 s91, v71
	v_add_co_u32_e32 v114, vcc, s29, v12
	v_and_b32_e32 v64, 63, v69
	s_nop 0
	v_addc_co_u32_e32 v115, vcc, 0, v13, vcc
	v_lshl_add_u32 v70, v64, 2, 0
	v_lshl_add_u32 v64, v116, 14, v70
	s_nop 11
	s_nop 6
	s_nop 5
	v_and_b32_e32 v244, 63, v210
	v_lshrrev_b32_e32 v245, 3, v244
	v_and_b32_e32 v249, 7, v244
	v_lshlrev_b32_e32 v247, 11, v245
	v_lshl_add_u32 v247, v249, 4, v247
	v_lshrrev_b32_e32 v248, 6, v210
	v_lshlrev_b32_e32 v248, 14, v248
	v_mul_u32_u24_e32 v245, 0x90, v245
	v_lshl_add_u32 v245, v249, 4, v245
	v_add_u32_e32 v245, v245, v248
	v_and_b32_e32 v246, 31, v210
	v_mul_u32_u24_e32 v246, 0x90, v246
	v_bfe_u32 v249, v210, 5, 1
	v_lshl_add_u32 v246, v249, 4, v246
	v_add_u32_e32 v246, v246, v248
	global_load_dwordx4 v[72:75], v247, s[88:89]
	s_add_u32 s92, s88, 0x4000
	s_addc_u32 s93, s89, 0
	s_nop 0
	global_load_dwordx4 v[76:79], v247, s[92:93]
	s_add_u32 s94, s88, 0x8000
	s_addc_u32 s95, s89, 0
	s_nop 0
	global_load_dwordx4 v[80:83], v247, s[94:95]
	s_add_u32 s92, s88, 0xc000
	s_addc_u32 s93, s89, 0
	s_nop 0
	global_load_dwordx4 v[84:87], v247, s[92:93]
	s_add_u32 s94, s88, 0x10000
	s_addc_u32 s95, s89, 0
	s_nop 0
	global_load_dwordx4 v[88:91], v247, s[94:95]
	s_add_u32 s92, s88, 0x14000
	s_addc_u32 s93, s89, 0
	s_nop 0
	global_load_dwordx4 v[92:95], v247, s[92:93]
	s_add_u32 s94, s88, 0x18000
	s_addc_u32 s95, s89, 0
	s_nop 0
	global_load_dwordx4 v[96:99], v247, s[94:95]
	s_add_u32 s92, s88, 0x1c000
	s_addc_u32 s93, s89, 0
	s_nop 0
	global_load_dwordx4 v[100:103], v247, s[92:93]
	global_load_dwordx4 v[104:107], v247, s[90:91]
	s_add_u32 s94, s90, 0x4000
	s_addc_u32 s95, s91, 0
	s_nop 0
	global_load_dwordx4 v[120:123], v247, s[94:95]
	s_add_u32 s92, s90, 0x8000
	s_addc_u32 s93, s91, 0
	s_nop 0
	global_load_dwordx4 v[124:127], v247, s[92:93]
	s_add_u32 s94, s90, 0xc000
	s_addc_u32 s95, s91, 0
	s_nop 0
	global_load_dwordx4 v[128:131], v247, s[94:95]
	s_add_u32 s92, s90, 0x10000
	s_addc_u32 s93, s91, 0
	s_nop 0
	global_load_dwordx4 v[132:135], v247, s[92:93]
	s_add_u32 s94, s90, 0x14000
	s_addc_u32 s95, s91, 0
	s_nop 0
	global_load_dwordx4 v[136:139], v247, s[94:95]
	s_add_u32 s92, s90, 0x18000
	s_addc_u32 s93, s91, 0
	s_nop 0
	global_load_dwordx4 v[140:143], v247, s[92:93]
	s_add_u32 s94, s90, 0x1c000
	s_addc_u32 s95, s91, 0
	s_nop 0
	global_load_dwordx4 v[144:147], v247, s[94:95]
	global_load_dwordx4 v[148:151], v247, s[88:89] offset:128
	s_add_u32 s92, s88, 0x4000
	s_addc_u32 s93, s89, 0
	s_nop 0
	global_load_dwordx4 v[152:155], v247, s[92:93] offset:128
	s_add_u32 s94, s88, 0x8000
	s_addc_u32 s95, s89, 0
	s_nop 0
	global_load_dwordx4 v[156:159], v247, s[94:95] offset:128
	s_add_u32 s92, s88, 0xc000
	s_addc_u32 s93, s89, 0
	s_nop 0
	global_load_dwordx4 v[160:163], v247, s[92:93] offset:128
	s_add_u32 s94, s88, 0x10000
	s_addc_u32 s95, s89, 0
	s_nop 0
	global_load_dwordx4 v[164:167], v247, s[94:95] offset:128
	s_add_u32 s92, s88, 0x14000
	s_addc_u32 s93, s89, 0
	s_nop 0
	global_load_dwordx4 v[168:171], v247, s[92:93] offset:128
	s_add_u32 s94, s88, 0x18000
	s_addc_u32 s95, s89, 0
	s_nop 0
	global_load_dwordx4 v[172:175], v247, s[94:95] offset:128
	s_add_u32 s92, s88, 0x1c000
	s_addc_u32 s93, s89, 0
	s_nop 0
	global_load_dwordx4 v[176:179], v247, s[92:93] offset:128
	global_load_dwordx4 v[180:183], v247, s[90:91] offset:128
	s_add_u32 s94, s90, 0x4000
	s_addc_u32 s95, s91, 0
	s_nop 0
	global_load_dwordx4 v[184:187], v247, s[94:95] offset:128
	s_add_u32 s92, s90, 0x8000
	s_addc_u32 s93, s91, 0
	s_nop 0
	global_load_dwordx4 v[188:191], v247, s[92:93] offset:128
	s_add_u32 s94, s90, 0xc000
	s_addc_u32 s95, s91, 0
	s_nop 0
	global_load_dwordx4 v[192:195], v247, s[94:95] offset:128
	s_add_u32 s92, s90, 0x10000
	s_addc_u32 s93, s91, 0
	s_nop 0
	global_load_dwordx4 v[196:199], v247, s[92:93] offset:128
	s_add_u32 s94, s90, 0x14000
	s_addc_u32 s95, s91, 0
	s_nop 0
	global_load_dwordx4 v[200:203], v247, s[94:95] offset:128
	s_add_u32 s92, s90, 0x18000
	s_addc_u32 s93, s91, 0
	s_nop 0
	global_load_dwordx4 v[204:207], v247, s[92:93] offset:128
	s_add_u32 s94, s90, 0x1c000
	s_addc_u32 s95, s91, 0
	s_nop 0
	global_load_dwordx4 v[212:215], v247, s[94:95] offset:128
	s_waitcnt vmcnt(24) lgkmcnt(0)
	ds_write_b128 v245, v[72:75]
	ds_write_b128 v245, v[76:79] offset:1152
	ds_write_b128 v245, v[80:83] offset:2304
	ds_write_b128 v245, v[84:87] offset:3456
	ds_write_b128 v245, v[88:91] offset:4608
	ds_write_b128 v245, v[92:95] offset:5760
	ds_write_b128 v245, v[96:99] offset:6912
	ds_write_b128 v245, v[100:103] offset:8064
	s_waitcnt lgkmcnt(0)
; DI f32x16 mfma32(bf16x8 a, bf16x8 b, f32x16 c) { return __builtin_amdgcn_mfma_f32_32x32x16_bf16(a, b, c, 0, 0, 0); }
; template <int EPI, int K, int LNI>
; DI void gemm_tail_unit(const Params& p, const bf16_t* __restrict__ A, const bf16_t* __restrict__ Bt, const int un, float* s_aux) {
;     ...
;     for (int s = 0; s < KS / 16; ++s) {
;         const bf16x8 a0 = *(const bf16x8*)(ap + s * 16), a1 = *(const bf16x8*)(ap + (size_t)32 * K + s * 16);
;         const bf16x8 b0 = *(const bf16x8*)(bp + s * 16), b1 = *(const bf16x8*)(bp + (size_t)32 * K + s * 16);
;         acc[0][0] = mfma32(a0, b0, acc[0][0]); acc[0][1] = mfma32(a0, b1, acc[0][1]);
;         acc[1][0] = mfma32(a1, b0, acc[1][0]); acc[1][1] = mfma32(a1, b1, acc[1][1]);
;     }
;     float* red = (float*)dsm;
; #pragma unroll
;     for (int i = 0; i < 2; ++i)
; #pragma unroll
;         for (int j = 0; j < 2; ++j)
; #pragma unroll
;             for (int reg = 0; reg < 16; ++reg) red[((w * 4 + i * 2 + j) * 16 + reg) * 64 + lane] = acc[i][j][reg];
	ds_read_b128 v[72:75], v246
	ds_read_b128 v[76:79], v246 offset:32
	ds_read_b128 v[80:83], v246 offset:64
	ds_read_b128 v[84:87], v246 offset:96
	ds_read_b128 v[88:91], v246 offset:4608
	ds_read_b128 v[92:95], v246 offset:4640
	ds_read_b128 v[96:99], v246 offset:4672
	ds_read_b128 v[100:103], v246 offset:4704
	s_waitcnt vmcnt(16) lgkmcnt(0)
	ds_write_b128 v245, v[104:107]
	ds_write_b128 v245, v[120:123] offset:1152
	ds_write_b128 v245, v[124:127] offset:2304
	ds_write_b128 v245, v[128:131] offset:3456
	ds_write_b128 v245, v[132:135] offset:4608
	ds_write_b128 v245, v[136:139] offset:5760
	ds_write_b128 v245, v[140:143] offset:6912
	ds_write_b128 v245, v[144:147] offset:8064
	s_waitcnt lgkmcnt(0)
	ds_read_b128 v[104:107], v246
	ds_read_b128 v[120:123], v246 offset:32
	ds_read_b128 v[124:127], v246 offset:64
	ds_read_b128 v[128:131], v246 offset:96
	ds_read_b128 v[132:135], v246 offset:4608
	ds_read_b128 v[136:139], v246 offset:4640
	ds_read_b128 v[140:143], v246 offset:4672
	ds_read_b128 v[144:147], v246 offset:4704
	s_waitcnt lgkmcnt(0)
	v_mfma_f32_32x32x16_bf16 v[48:63], v[72:75], v[104:107], 0
	v_mfma_f32_32x32x16_bf16 v[32:47], v[72:75], v[132:135], 0
	v_mfma_f32_32x32x16_bf16 v[16:31], v[88:91], v[104:107], 0
	v_mfma_f32_32x32x16_bf16 v[0:15], v[88:91], v[132:135], 0
	v_mfma_f32_32x32x16_bf16 v[48:63], v[76:79], v[120:123], v[48:63]
	v_mfma_f32_32x32x16_bf16 v[32:47], v[76:79], v[136:139], v[32:47]
	v_mfma_f32_32x32x16_bf16 v[16:31], v[92:95], v[120:123], v[16:31]
	v_mfma_f32_32x32x16_bf16 v[0:15], v[92:95], v[136:139], v[0:15]
	v_mfma_f32_32x32x16_bf16 v[48:63], v[80:83], v[124:127], v[48:63]
	v_mfma_f32_32x32x16_bf16 v[32:47], v[80:83], v[140:143], v[32:47]
	v_mfma_f32_32x32x16_bf16 v[16:31], v[96:99], v[124:127], v[16:31]
	v_mfma_f32_32x32x16_bf16 v[0:15], v[96:99], v[140:143], v[0:15]
	v_mfma_f32_32x32x16_bf16 v[48:63], v[84:87], v[128:131], v[48:63]
	v_mfma_f32_32x32x16_bf16 v[32:47], v[84:87], v[144:147], v[32:47]
	v_mfma_f32_32x32x16_bf16 v[16:31], v[100:103], v[128:131], v[16:31]
	v_mfma_f32_32x32x16_bf16 v[0:15], v[100:103], v[144:147], v[0:15]
	s_waitcnt vmcnt(8) lgkmcnt(0)
	ds_write_b128 v245, v[148:151]
	ds_write_b128 v245, v[152:155] offset:1152
	ds_write_b128 v245, v[156:159] offset:2304
	ds_write_b128 v245, v[160:163] offset:3456
	ds_write_b128 v245, v[164:167] offset:4608
	ds_write_b128 v245, v[168:171] offset:5760
	ds_write_b128 v245, v[172:175] offset:6912
	ds_write_b128 v245, v[176:179] offset:8064
	s_waitcnt lgkmcnt(0)
	ds_read_b128 v[148:151], v246
	ds_read_b128 v[152:155], v246 offset:32
	ds_read_b128 v[156:159], v246 offset:64
	ds_read_b128 v[160:163], v246 offset:96
	ds_read_b128 v[164:167], v246 offset:4608
	ds_read_b128 v[168:171], v246 offset:4640
	ds_read_b128 v[172:175], v246 offset:4672
	ds_read_b128 v[176:179], v246 offset:4704
	s_waitcnt vmcnt(0) lgkmcnt(0)
	ds_write_b128 v245, v[180:183]
	ds_write_b128 v245, v[184:187] offset:1152
	ds_write_b128 v245, v[188:191] offset:2304
	ds_write_b128 v245, v[192:195] offset:3456
	ds_write_b128 v245, v[196:199] offset:4608
	ds_write_b128 v245, v[200:203] offset:5760
	ds_write_b128 v245, v[204:207] offset:6912
	ds_write_b128 v245, v[212:215] offset:8064
	s_waitcnt lgkmcnt(0)
	ds_read_b128 v[180:183], v246
	ds_read_b128 v[184:187], v246 offset:32
	ds_read_b128 v[188:191], v246 offset:64
	ds_read_b128 v[192:195], v246 offset:96
	ds_read_b128 v[196:199], v246 offset:4608
	ds_read_b128 v[200:203], v246 offset:4640
	ds_read_b128 v[204:207], v246 offset:4672
	ds_read_b128 v[212:215], v246 offset:4704
	s_waitcnt lgkmcnt(0)
	v_mfma_f32_32x32x16_bf16 v[48:63], v[148:151], v[180:183], v[48:63]
	v_mfma_f32_32x32x16_bf16 v[32:47], v[148:151], v[196:199], v[32:47]
	v_mfma_f32_32x32x16_bf16 v[16:31], v[164:167], v[180:183], v[16:31]
	v_mfma_f32_32x32x16_bf16 v[0:15], v[164:167], v[196:199], v[0:15]
	v_mfma_f32_32x32x16_bf16 v[48:63], v[152:155], v[184:187], v[48:63]
	v_mfma_f32_32x32x16_bf16 v[32:47], v[152:155], v[200:203], v[32:47]
	v_mfma_f32_32x32x16_bf16 v[16:31], v[168:171], v[184:187], v[16:31]
	v_mfma_f32_32x32x16_bf16 v[0:15], v[168:171], v[200:203], v[0:15]
	v_mfma_f32_32x32x16_bf16 v[48:63], v[156:159], v[188:191], v[48:63]
	v_mfma_f32_32x32x16_bf16 v[32:47], v[156:159], v[204:207], v[32:47]
	v_mfma_f32_32x32x16_bf16 v[16:31], v[172:175], v[188:191], v[16:31]
	v_mfma_f32_32x32x16_bf16 v[0:15], v[172:175], v[204:207], v[0:15]
	v_mfma_f32_32x32x16_bf16 v[48:63], v[160:163], v[192:195], v[48:63]
	v_mfma_f32_32x32x16_bf16 v[32:47], v[160:163], v[212:215], v[32:47]
	v_mfma_f32_32x32x16_bf16 v[16:31], v[176:179], v[192:195], v[16:31]
	v_mfma_f32_32x32x16_bf16 v[0:15], v[176:179], v[212:215], v[0:15]
	s_nop 7
	s_nop 3
	ds_write2st64_b32 v64, v48, v49 offset1:1
	ds_write2st64_b32 v64, v50, v51 offset0:2 offset1:3
	ds_write2st64_b32 v64, v52, v53 offset0:4 offset1:5
	ds_write2st64_b32 v64, v54, v55 offset0:6 offset1:7
	ds_write2st64_b32 v64, v56, v57 offset0:8 offset1:9
	ds_write2st64_b32 v64, v58, v59 offset0:10 offset1:11
	ds_write2st64_b32 v64, v60, v61 offset0:12 offset1:13
	ds_write2st64_b32 v64, v62, v63 offset0:14 offset1:15
	ds_write2st64_b32 v64, v32, v33 offset0:16 offset1:17
	ds_write2st64_b32 v64, v34, v35 offset0:18 offset1:19
	ds_write2st64_b32 v64, v36, v37 offset0:20 offset1:21
	ds_write2st64_b32 v64, v38, v39 offset0:22 offset1:23
	ds_write2st64_b32 v64, v40, v41 offset0:24 offset1:25
	ds_write2st64_b32 v64, v42, v43 offset0:26 offset1:27
	ds_write2st64_b32 v64, v44, v45 offset0:28 offset1:29
	ds_write2st64_b32 v64, v46, v47 offset0:30 offset1:31
	ds_write2st64_b32 v64, v16, v17 offset0:32 offset1:33
	ds_write2st64_b32 v64, v18, v19 offset0:34 offset1:35
; DI unsigned cvt_pk(float lo, float hi) { f32x2 v = {lo, hi}; bf16x2v b = __builtin_convertvector(v, bf16x2v); return __builtin_bit_cast(unsigned, b); }
; DI float ex2(float x) { return __builtin_amdgcn_exp2f(x); }
; DI size_t vf_off(int item, int dvh, int j) { return ((size_t)((item * 16 + (dvh >> 5)) * 4 + (j >> 4)) * 64 + ((j >> 3) & 1) * 32 + (dvh & 31)) * 8 + (j & 7); }
;     ...
;             const int c = col - 2048, hd = c >> 9, item = (ch * 4 + b) * 4 + hd;
;             u32x2 wv; wv[0] = cvt_pk(v[0], v[1]); wv[1] = cvt_pk(v[2], v[3]);
;             *(u32x2*)((bf16_t*)(p.ws + OFF_VT1) + vf_off(item, c & 511, idx)) = wv;
; template <int EPI, int K, int LNI>
; DI void gemm_tail_unit(const Params& p, const bf16_t* __restrict__ A, const bf16_t* __restrict__ Bt, const int un, float* s_aux) {
;     ...
;             for (int reg = 0; reg < 16; ++reg) red[((w * 4 + i * 2 + j) * 16 + reg) * 64 + lane] = acc[i][j][reg];
;     __syncthreads();
;     {
;         const int tile = w >> 1, i = tile >> 1, j = tile & 1;
; #pragma unroll
;         for (int gg = 0; gg < 2; ++gg) {
;             const int g = 2 * (w & 1) + gg;
;             float v[4];
; #pragma unroll
;             for (int e = 0; e < 4; ++e) {
;                 float sacc = 0.f;
; #pragma unroll
;                 for (int wv = 0; wv < 8; ++wv) sacc += red[((wv * 4 + tile) * 16 + 4 * g + e) * 64 + lane];
;                 v[e] = sacc;
;             }
;             const int lrow0 = i * 32 + 8 * g + 4 * h;
;             f32x2 rs[4]; float lng = 1.f, lnb = 0.f;
;             if (EPI == EPI_E5) {
;                 lng = log2f(1.f - ex2(-5.f - (float)((col0 >> 8) & 3)));
;                 const int idx_ = (((ROW0 + lrow0) % LT) + 48) & 63;
; #pragma unroll
;                 for (int e = 0; e < 4; ++e) rs[e] = (f32x2){ex2(lng * (float)(idx_ + e + 1)), 0.0625f * ex2(lng * (float)(63 - idx_ - e))};
;             }
	ds_write2st64_b32 v64, v20, v21 offset0:36 offset1:37
	ds_write2st64_b32 v64, v22, v23 offset0:38 offset1:39
	ds_write2st64_b32 v64, v24, v25 offset0:40 offset1:41
	ds_write2st64_b32 v64, v26, v27 offset0:42 offset1:43
	ds_write2st64_b32 v64, v28, v29 offset0:44 offset1:45
	ds_write2st64_b32 v64, v30, v31 offset0:46 offset1:47
	s_nop 11
	ds_write2st64_b32 v64, v0, v1 offset0:48 offset1:49
	ds_write2st64_b32 v64, v2, v3 offset0:50 offset1:51
	ds_write2st64_b32 v64, v4, v5 offset0:52 offset1:53
	ds_write2st64_b32 v64, v6, v7 offset0:54 offset1:55
	ds_write2st64_b32 v64, v8, v9 offset0:56 offset1:57
	ds_write2st64_b32 v64, v10, v11 offset0:58 offset1:59
	ds_write2st64_b32 v64, v12, v13 offset0:60 offset1:61
	ds_write2st64_b32 v64, v14, v15 offset0:62 offset1:63
	v_cvt_f32_ubyte0_e32 v1, s6
	v_sub_f32_e32 v1, 0xc0a00000, v1
	v_exp_f32_e32 v1, v1
	v_ashrrev_i32_e32 v0, 7, v69
	v_lshlrev_b32_e32 v2, 1, v116
	v_lshlrev_b32_e32 v17, 12, v0
	v_sub_f32_e32 v1, 1.0, v1
	v_cmp_gt_f32_e32 vcc, s43, v1
	s_and_b64 s[6:7], vcc, exec
	s_cselect_b32 s6, 32, 0
	v_ldexp_f32 v1, v1, s6
	v_log_f32_e32 v1, v1
	v_lshlrev_b32_e32 v0, 5, v0
	v_and_b32_e32 v16, 2, v2
	v_cndmask_b32_e32 v2, 0, v66, vcc
	v_and_b32_e32 v0, 32, v0
	v_sub_f32_e32 v7, v1, v2
	v_add_u32_e32 v1, s3, v0
	v_add_u32_e32 v18, v108, v0
	v_sub_co_u32_e32 v0, vcc, s3, v67
	v_lshrrev_b32_e32 v0, 3, v0
	v_and_b32_e32 v0, 0x1fffffc0, v0
	v_lshrrev_b32_e32 v1, 3, v1
	v_add_u32_e32 v64, 0xfffffc00, v18
	v_and_or_b32 v10, v1, 60, v0
	v_lshrrev_b32_e32 v0, 3, v64
	v_and_b32_e32 v1, 28, v1
	v_and_or_b32 v9, v0, s45, v1
	v_lshlrev_b32_e32 v1, 1, v69
	v_lshrrev_b32_e32 v2, 1, v69
	v_lshl_or_b32 v19, v16, 10, v17
	v_ashrrev_i32_e32 v3, 3, v69
	v_lshlrev_b32_e32 v6, 2, v117
	v_and_b32_e32 v0, 19, v69
	v_and_b32_e32 v1, 8, v1
	v_and_b32_e32 v2, 4, v2
	v_add_u32_e32 v34, v70, v19
	s_waitcnt lgkmcnt(0)
	s_barrier
	v_and_or_b32 v11, v3, s42, v6
	v_or3_b32 v8, v2, v0, v1
	ds_read2st64_b32 v[0:1], v34 offset1:1
	ds_read2st64_b32 v[2:3], v34 offset0:64 offset1:65
	ds_read2st64_b32 v[4:5], v34 offset0:128 offset1:129
	ds_read2st64_b32 v[20:21], v34 offset0:192 offset1:193
	v_add_u32_e32 v12, 0x10000, v70
	v_add_u32_e32 v13, 0x14000, v70
	v_add_u32_e32 v14, 0x18000, v70
	v_add_u32_e32 v15, 0x1c000, v70
	v_or_b32_e32 v24, 0x100, v19
	s_waitcnt lgkmcnt(3)
	v_pk_add_f32 v[0:1], v[0:1], 0 op_sel_hi:[1,0]
	v_add_u32_e32 v22, v12, v19
	v_add_u32_e32 v23, v13, v19
	v_add_u32_e32 v25, v14, v19
	v_add_u32_e32 v27, v15, v19
	v_add_u32_e32 v29, v12, v24
	v_add_u32_e32 v30, v13, v24
	v_add_u32_e32 v31, v14, v24
	v_add_u32_e32 v32, v15, v24
	s_waitcnt lgkmcnt(2)
	v_add_f32_e64 v0, v0, v2
	v_add_f32_e64 v1, v1, v3
	ds_read_b32 v22, v22
	ds_read_b32 v24, v23
	ds_read_b32 v26, v25
	ds_read_b32 v28, v27
	ds_read_b32 v23, v29
	ds_read_b32 v25, v30
	ds_read_b32 v27, v31
	ds_read_b32 v29, v32
	ds_read2st64_b32 v[30:31], v34 offset0:66 offset1:67
	ds_read2st64_b32 v[32:33], v34 offset0:2 offset1:3
	s_waitcnt lgkmcnt(11)
	v_add_f32_e64 v0, v0, v4
	v_add_f32_e64 v1, v1, v5
	ds_read2st64_b32 v[2:3], v34 offset0:194 offset1:195
	ds_read2st64_b32 v[34:35], v34 offset0:130 offset1:131
	s_waitcnt lgkmcnt(12)
	v_add_f32_e64 v0, v0, v20
	v_add_f32_e64 v1, v1, v21
	v_or_b32_e32 v4, 0x200, v19
	s_waitcnt lgkmcnt(7)
	v_add_f32_e64 v0, v0, v22
	v_add_f32_e64 v1, v1, v23
	v_add_u32_e32 v5, v12, v4
	s_waitcnt lgkmcnt(6)
	v_add_f32_e64 v0, v0, v24
	v_add_f32_e64 v1, v1, v25
	v_add_u32_e32 v20, v13, v4
	v_add_u32_e32 v21, v14, v4
	v_add_u32_e32 v23, v15, v4
	v_or_b32_e32 v4, 0x300, v19
	s_waitcnt lgkmcnt(5)
	v_add_f32_e64 v0, v0, v26
	v_add_f32_e64 v1, v1, v27
	v_add_u32_e32 v25, v13, v4
	v_add_u32_e32 v26, v14, v4
	v_add_u32_e32 v27, v15, v4
	v_add_u32_e32 v19, v12, v4
	ds_read_b32 v4, v5
	ds_read_b32 v20, v20
	ds_read_b32 v22, v21
	ds_read_b32 v24, v23
	ds_read_b32 v5, v19
	ds_read_b32 v21, v25
	ds_read_b32 v23, v26
	ds_read_b32 v25, v27
	s_waitcnt lgkmcnt(10)
	v_pk_add_f32 v[26:27], v[32:33], 0 op_sel_hi:[1,0]
	v_cmp_lt_i32_e64 s[6:7], s44, v18
	v_add_f32_e64 v26, v26, v30
	v_add_f32_e64 v27, v27, v31
	s_xor_b64 s[12:13], vcc, -1
	s_waitcnt lgkmcnt(8)
	v_add_f32_e64 v26, v26, v34
	v_add_f32_e64 v27, v27, v35
	v_add_f32_e64 v0, v0, v28
	v_add_f32_e64 v1, v1, v29
	v_add_f32_e64 v2, v26, v2
	v_add_f32_e64 v3, v27, v3
	s_waitcnt lgkmcnt(3)
	v_add_f32_e64 v2, v2, v4
	v_add_f32_e64 v3, v3, v5
	v_lshl_or_b32 v5, v16, 3, v11
	v_add_u32_e32 v4, 0x8000, v5
	v_mul_hi_i32 v19, v4, s46
	s_waitcnt lgkmcnt(2)
	v_add_f32_e64 v2, v2, v20
	v_add_f32_e64 v3, v3, v21
	v_lshrrev_b32_e32 v20, 31, v19
	v_ashrrev_i32_e32 v19, 12, v19
	v_add_u32_e32 v21, v19, v20
	v_mul_i32_i24_e32 v19, 0x2010, v21
	v_sub_u32_e32 v19, v4, v19
	v_add_u32_e32 v19, 48, v19
	s_waitcnt lgkmcnt(1)
	v_add_f32_e64 v2, v2, v22
	v_add_f32_e64 v3, v3, v23
	v_and_b32_e32 v23, 63, v19
	v_mul_i32_i24_e32 v19, 0xffffdff0, v21
	s_waitcnt lgkmcnt(0)
	v_add_f32_e64 v2, v2, v24
	v_add_f32_e64 v3, v3, v25
	v_add3_u32 v24, v5, v19, s47
	v_and_b32_e32 v20, 60, v24
	v_ashrrev_i32_e32 v22, 6, v24
	s_and_saveexec_b64 s[14:15], s[6:7]
	s_xor_b64 s[14:15], exec, s[14:15]
	s_cbranch_execz .LBB0_1414
	s_mov_b64 s[22:23], -1
	s_and_b64 vcc, exec, s[12:13]
	s_cbranch_vccz .LBB0_1412
	v_lshlrev_b32_e32 v5, 10, v22
	v_lshlrev_b32_e32 v19, 8, v21
	v_lshrrev_b32_e32 v26, 4, v20
	v_add3_u32 v5, v19, v10, v5
	v_or_b32_e32 v26, v5, v26
	v_ashrrev_i32_e32 v27, 31, v26
	v_lshlrev_b64 v[26:27], 6, v[26:27]
	v_lshlrev_b32_e32 v5, 2, v20
	v_and_or_b32 v5, v5, 32, v26
	v_or_b32_e32 v26, v5, v68
	v_lshl_add_u64 v[26:27], v[26:27], 4, s[20:21]
	v_lshlrev_b32_e32 v28, 1, v6
	v_mov_b32_e32 v29, v65
	v_cvt_pk_bf16_f32 v24, v0, v1
	v_cvt_pk_bf16_f32 v25, v2, v3
	v_lshl_add_u64 v[26:27], v[26:27], 0, v[28:29]
	global_store_dwordx2 v[26:27], v[24:25], off
	s_mov_b64 s[22:23], 0
; DI unsigned cvt_pk(float lo, float hi) { f32x2 v = {lo, hi}; bf16x2v b = __builtin_convertvector(v, bf16x2v); return __builtin_bit_cast(unsigned, b); }
; DI bf16_t f2bf(float x) { return (bf16_t)(cvt_pk(x, 0.f) & 0xffffu); }
; DI float ex2(float x) { return __builtin_amdgcn_exp2f(x); }
; DI size_t kf_off(int item, int dk, int j) { return ((size_t)((item * 8 + (dk >> 5)) * 4 + (j >> 4)) * 64 + ((j >> 3) & 1) * 32 + perm23(dk & 31)) * 8 + (j & 7); }
;     ...
;         } else if (col < 2048) {
;             const int c = col - 1024, hd = c >> 8, item = (ch * 4 + b) * 4 + hd;
;             bf16_t* d = (bf16_t*)(p.ws + OFF_KHAT) + (size_t)row0 * 1024 + c;
; #pragma unroll
;             for (int e = 0; e < 4; ++e) { v[e] *= rs[e][1]; d[(size_t)e * 1024] = f2bf(v[e]); }
;             u32x2 wv; wv[0] = cvt_pk(v[0], v[1]); wv[1] = cvt_pk(v[2], v[3]);
;             *(u32x2*)((bf16_t*)(p.ws + OFF_KHATT) + kf_off(item, c & 255, idx)) = wv;
; template <int EPI, int K, int LNI>
; DI void gemm_tail_unit(const Params& p, const bf16_t* __restrict__ A, const bf16_t* __restrict__ Bt, const int un, float* s_aux) {
;     ...
;             if (EPI == EPI_E5) {
;                 lng = log2f(1.f - ex2(-5.f - (float)((col0 >> 8) & 3)));
;                 const int idx_ = (((ROW0 + lrow0) % LT) + 48) & 63;
; #pragma unroll
;                 for (int e = 0; e < 4; ++e) rs[e] = (f32x2){ex2(lng * (float)(idx_ + e + 1)), 0.0625f * ex2(lng * (float)(63 - idx_ - e))};
;             }
.LBB0_1412:
	s_andn2_b64 vcc, exec, s[22:23]
	s_cbranch_vccnz .LBB0_1414
	v_sub_u32_e32 v19, 62, v23
	v_cvt_f32_u32_e32 v19, v19
	v_xor_b32_e32 v5, 63, v23
	v_cvt_f32_ubyte0_e32 v5, v5
	v_mul_f32_e32 v5, v7, v5
	v_exp_f32_e32 v24, v5
	v_mul_f32_e32 v5, v7, v19
	v_sub_u32_e32 v19, 61, v23
	v_cvt_f32_u32_e32 v19, v19
	v_sub_u32_e32 v23, 60, v23
	v_cvt_f32_u32_e32 v23, v23
	v_exp_f32_e32 v25, v5
	v_mul_f32_e32 v5, v7, v19
	v_exp_f32_e32 v26, v5
	v_mul_f32_e32 v5, v7, v23
	v_exp_f32_e32 v27, v5
	v_ashrrev_i32_e32 v5, 31, v4
	v_mul_f32_e64 v24, v24, s10
	v_mul_f32_e64 v25, v25, s10
	v_lshlrev_b64 v[4:5], 11, v[4:5]
	v_lshl_add_u64 v[4:5], s[36:37], 0, v[4:5]
	v_mul_f32_e64 v0, v24, v0
	v_mul_f32_e64 v1, v25, v1
	v_lshl_add_u64 v[4:5], v[64:65], 1, v[4:5]
	v_cvt_pk_bf16_f32 v19, v0, s0
	v_mul_f32_e64 v26, v26, s10
	v_mul_f32_e64 v27, v27, s10
	global_store_short v[4:5], v19, off
	v_cvt_pk_bf16_f32 v19, v1, s0
	global_store_short v[4:5], v19, off offset:2048
	v_mul_f32_e64 v2, v26, v2
	v_mul_f32_e64 v3, v27, v3
	v_add_co_u32_e32 v4, vcc, s48, v4
	v_cvt_pk_bf16_f32 v19, v2, s0
	s_nop 0
	v_addc_co_u32_e32 v5, vcc, 0, v5, vcc
	global_store_short v[4:5], v19, off
	v_cvt_pk_bf16_f32 v19, v3, s0
	v_cvt_pk_bf16_f32 v0, v0, v1
	v_cvt_pk_bf16_f32 v1, v2, v3
	v_lshlrev_b32_e32 v2, 9, v22
	v_lshlrev_b32_e32 v3, 7, v21
	global_store_short v[4:5], v19, off offset:2048
	v_lshrrev_b32_e32 v4, 4, v20
	v_add3_u32 v2, v9, v3, v2
	v_or_b32_e32 v2, v2, v4
	v_ashrrev_i32_e32 v3, 31, v2
	v_lshlrev_b64 v[2:3], 6, v[2:3]
	v_lshlrev_b32_e32 v4, 2, v20
	v_and_or_b32 v2, v4, 32, v2
	v_or_b32_e32 v2, v2, v8
	v_lshl_add_u64 v[2:3], v[2:3], 4, s[24:25]
	v_lshlrev_b32_e32 v4, 1, v6
	v_mov_b32_e32 v5, v65
	v_lshl_add_u64 v[2:3], v[2:3], 0, v[4:5]
	global_store_dwordx2 v[2:3], v[0:1], off

;     ...
;         } else if (col < 2048) {
;             const int c = col - 1024, hd = c >> 8, item = (ch * 4 + b) * 4 + hd;
;             bf16_t* d = (bf16_t*)(p.ws + OFF_KHAT) + (size_t)row0 * 1024 + c;
; #pragma unroll
;             for (int e = 0; e < 4; ++e) { v[e] *= rs[e][1]; d[(size_t)e * 1024] = f2bf(v[e]); }
;             u32x2 wv; wv[0] = cvt_pk(v[0], v[1]); wv[1] = cvt_pk(v[2], v[3]);
;             *(u32x2*)((bf16_t*)(p.ws + OFF_KHATT) + kf_off(item, c & 255, idx)) = wv;
;         } else {
;             const int c = col - 2048, hd = c >> 9, item = (ch * 4 + b) * 4 + hd;
;             u32x2 wv; wv[0] = cvt_pk(v[0], v[1]); wv[1] = cvt_pk(v[2], v[3]);
;             *(u32x2*)((bf16_t*)(p.ws + OFF_VT1) + vf_off(item, c & 511, idx)) = wv;
; template <int EPI, int K, int LNI>
; DI void gemm_tail_unit(const Params& p, const bf16_t* __restrict__ A, const bf16_t* __restrict__ Bt, const int un, float* s_aux) {
;     ...
;     {
;         const int tile = w >> 1, i = tile >> 1, j = tile & 1;
; #pragma unroll
;         for (int gg = 0; gg < 2; ++gg) {
;             const int g = 2 * (w & 1) + gg;
;             float v[4];
; #pragma unroll
;             for (int e = 0; e < 4; ++e) {
;                 float sacc = 0.f;
; #pragma unroll
;                 for (int wv = 0; wv < 8; ++wv) sacc += red[((wv * 4 + tile) * 16 + 4 * g + e) * 64 + lane];
;                 v[e] = sacc;
;             }
;             const int lrow0 = i * 32 + 8 * g + 4 * h;
;             f32x2 rs[4]; float lng = 1.f, lnb = 0.f;
;             if (EPI == EPI_E5) {
;                 lng = log2f(1.f - ex2(-5.f - (float)((col0 >> 8) & 3)));
;                 const int idx_ = (((ROW0 + lrow0) % LT) + 48) & 63;
; #pragma unroll
;                 for (int e = 0; e < 4; ++e) rs[e] = (f32x2){ex2(lng * (float)(idx_ + e + 1)), 0.0625f * ex2(lng * (float)(63 - idx_ - e))};
;             }
;             if (EPI == EPI_RESID && LNI >= 0) {
;                 const f32x2* st_ = (const f32x2*)((unsigned char*)p.out + OFFO_STATS) + ROW0 + lrow0;
; #pragma unroll
;                 for (int e = 0; e < 4; ++e) rs[e] = st_[e];
;                 lng = p.ln_g[(LNI < 0 ? 0 : LNI) * 1024 + col0 + j * 32 + r]; lnb = p.ln_b[(LNI < 0 ? 0 : LNI) * 1024 + col0 + j * 32 + r];
;             }
;             epi_store<EPI, LNI>(p, ROW0 + lrow0, col0 + j * 32 + r, lrow0, v, s_aux, rs, lng, lnb);
.LBB0_1416:
	s_or_b64 exec, exec, s[14:15]
	v_or_b32_e32 v4, 1, v16
	v_lshl_or_b32 v36, v4, 10, v17
	v_add_u32_e32 v34, v70, v36
	ds_read2st64_b32 v[0:1], v34 offset1:1
	ds_read2st64_b32 v[2:3], v34 offset0:64 offset1:65
	ds_read2st64_b32 v[16:17], v34 offset0:128 offset1:129
	ds_read2st64_b32 v[20:21], v34 offset0:192 offset1:193
	v_or_b32_e32 v24, 0x100, v36
	v_add_u32_e32 v22, v12, v36
	v_add_u32_e32 v23, v13, v36
	v_add_u32_e32 v25, v14, v36
	v_add_u32_e32 v27, v15, v36
	v_add_u32_e32 v29, v12, v24
	v_add_u32_e32 v30, v13, v24
	v_add_u32_e32 v31, v14, v24
	v_add_u32_e32 v32, v15, v24
	s_waitcnt lgkmcnt(3)
	v_pk_add_f32 v[0:1], v[0:1], 0 op_sel_hi:[1,0]
	ds_read_b32 v22, v22
	ds_read_b32 v24, v23
	ds_read_b32 v26, v25
	ds_read_b32 v28, v27
	ds_read_b32 v23, v29
	ds_read_b32 v25, v30
	ds_read_b32 v27, v31
	ds_read_b32 v29, v32
	ds_read2st64_b32 v[30:31], v34 offset0:66 offset1:67
	ds_read2st64_b32 v[32:33], v34 offset0:2 offset1:3
	s_waitcnt lgkmcnt(12)
	v_add_f32_e64 v0, v0, v2
	v_add_f32_e64 v1, v1, v3
	ds_read2st64_b32 v[2:3], v34 offset0:194 offset1:195
	ds_read2st64_b32 v[34:35], v34 offset0:130 offset1:131
	s_waitcnt lgkmcnt(13)
	v_add_f32_e64 v0, v0, v16
	v_add_f32_e64 v1, v1, v17
	v_or_b32_e32 v16, 0x200, v36
	s_waitcnt lgkmcnt(12)
	v_add_f32_e64 v0, v0, v20
	v_add_f32_e64 v1, v1, v21
	v_add_u32_e32 v17, v12, v16
	s_waitcnt lgkmcnt(7)
	v_add_f32_e64 v0, v0, v22
	v_add_f32_e64 v1, v1, v23
	v_add_u32_e32 v20, v13, v16
	v_add_u32_e32 v21, v14, v16
	v_add_u32_e32 v22, v15, v16
	v_or_b32_e32 v16, 0x300, v36
	s_waitcnt lgkmcnt(6)
	v_add_f32_e64 v0, v0, v24
	v_add_f32_e64 v1, v1, v25
	v_add_u32_e32 v23, v12, v16
	s_waitcnt lgkmcnt(5)
	v_add_f32_e64 v0, v0, v26
	v_add_f32_e64 v1, v1, v27
	v_add_u32_e32 v24, v13, v16
	v_add_u32_e32 v25, v14, v16
	v_add_u32_e32 v26, v15, v16
	ds_read_b32 v12, v17
	ds_read_b32 v14, v20
	ds_read_b32 v16, v21
	ds_read_b32 v20, v22
	ds_read_b32 v13, v23
	ds_read_b32 v15, v24
	ds_read_b32 v17, v25
	ds_read_b32 v21, v26
	s_waitcnt lgkmcnt(10)
	v_pk_add_f32 v[22:23], v[32:33], 0 op_sel_hi:[1,0]
	v_add_f32_e64 v0, v0, v28
	v_add_f32_e64 v1, v1, v29
	v_add_f32_e64 v22, v22, v30
	v_add_f32_e64 v23, v23, v31
	s_waitcnt lgkmcnt(8)
	v_add_f32_e64 v22, v22, v34
	v_add_f32_e64 v23, v23, v35
	s_nop 0
	v_add_f32_e64 v2, v22, v2
	v_add_f32_e64 v3, v23, v3
	s_waitcnt lgkmcnt(3)
	v_add_f32_e64 v2, v2, v12
	v_add_f32_e64 v3, v3, v13
	v_lshl_or_b32 v12, v4, 3, v11
	v_add_u32_e32 v4, 0x8000, v12
	v_mul_hi_i32 v11, v4, s46
	v_lshrrev_b32_e32 v13, 31, v11
	v_ashrrev_i32_e32 v11, 12, v11
	v_add_u32_e32 v11, v11, v13
	v_mul_i32_i24_e32 v13, 0x2010, v11
	v_sub_u32_e32 v13, v4, v13
	v_add_u32_e32 v13, 48, v13
	s_waitcnt lgkmcnt(2)
	v_add_f32_e64 v2, v2, v14
	v_add_f32_e64 v3, v3, v15
	v_and_b32_e32 v14, 63, v13
	v_mul_i32_i24_e32 v13, 0xffffdff0, v11
	s_waitcnt lgkmcnt(1)
	v_add_f32_e64 v2, v2, v16
	v_add_f32_e64 v3, v3, v17
	v_add3_u32 v15, v12, v13, s47
	s_waitcnt lgkmcnt(0)
	v_add_f32_e64 v2, v2, v20
	v_add_f32_e64 v3, v3, v21
	v_and_b32_e32 v12, 60, v15
	v_ashrrev_i32_e32 v13, 6, v15
	s_and_saveexec_b64 s[14:15], s[6:7]
	s_xor_b64 s[6:7], exec, s[14:15]
	s_cbranch_execz .LBB0_1421
	s_andn2_b64 vcc, exec, s[12:13]
	s_mov_b64 s[12:13], -1
	s_cbranch_vccnz .LBB0_1419
	v_lshlrev_b32_e32 v5, 10, v13
	v_lshlrev_b32_e32 v15, 8, v11
	v_lshrrev_b32_e32 v18, 4, v12
	v_add3_u32 v5, v15, v10, v5
	v_or_b32_e32 v18, v5, v18
	v_ashrrev_i32_e32 v19, 31, v18
	v_lshlrev_b64 v[18:19], 6, v[18:19]
	v_lshlrev_b32_e32 v5, 2, v12
	v_and_or_b32 v5, v5, 32, v18
	v_or_b32_e32 v18, v5, v68
	v_lshl_add_u64 v[18:19], v[18:19], 4, s[20:21]
	v_lshlrev_b32_e32 v20, 1, v6
	v_mov_b32_e32 v21, v65
	v_cvt_pk_bf16_f32 v16, v0, v1
	v_cvt_pk_bf16_f32 v17, v2, v3
	v_lshl_add_u64 v[18:19], v[18:19], 0, v[20:21]
	s_mov_b64 s[12:13], 0
	global_store_dwordx2 v[18:19], v[16:17], off
.LBB0_1419:
	s_andn2_b64 vcc, exec, s[12:13]
	s_cbranch_vccnz .LBB0_1421
	v_sub_u32_e32 v10, 62, v14
	v_cvt_f32_u32_e32 v10, v10
	v_xor_b32_e32 v5, 63, v14
	v_cvt_f32_ubyte0_e32 v5, v5
	v_mul_f32_e32 v5, v7, v5
	v_exp_f32_e32 v16, v5
	v_mul_f32_e32 v5, v7, v10
	v_sub_u32_e32 v10, 61, v14
	v_cvt_f32_u32_e32 v10, v10
	v_sub_u32_e32 v14, 60, v14
	v_cvt_f32_u32_e32 v15, v14
	v_exp_f32_e32 v17, v5
	v_mul_f32_e32 v5, v7, v10
	v_exp_f32_e32 v14, v5
	v_mul_f32_e32 v5, v7, v15
	v_exp_f32_e32 v15, v5
	v_ashrrev_i32_e32 v5, 31, v4
	v_mul_f32_e64 v16, v16, s10
	v_mul_f32_e64 v17, v17, s10
	v_lshlrev_b64 v[4:5], 11, v[4:5]
	v_lshl_add_u64 v[4:5], s[36:37], 0, v[4:5]
	v_mul_f32_e64 v0, v16, v0
	v_mul_f32_e64 v1, v17, v1
	v_lshl_add_u64 v[4:5], v[64:65], 1, v[4:5]
	v_cvt_pk_bf16_f32 v7, v0, s0
	v_mul_f32_e64 v14, v14, s10
	v_mul_f32_e64 v15, v15, s10
	global_store_short v[4:5], v7, off
	v_cvt_pk_bf16_f32 v7, v1, s0
	global_store_short v[4:5], v7, off offset:2048
	v_mul_f32_e64 v2, v14, v2
	v_mul_f32_e64 v3, v15, v3
	v_add_co_u32_e32 v4, vcc, s48, v4
	v_cvt_pk_bf16_f32 v7, v2, s0
	s_nop 0
	v_addc_co_u32_e32 v5, vcc, 0, v5, vcc
	global_store_short v[4:5], v7, off
	v_cvt_pk_bf16_f32 v7, v3, s0
	v_cvt_pk_bf16_f32 v0, v0, v1
	v_cvt_pk_bf16_f32 v1, v2, v3
	v_lshlrev_b32_e32 v2, 9, v13
	v_lshlrev_b32_e32 v3, 7, v11
	global_store_short v[4:5], v7, off offset:2048
	v_lshrrev_b32_e32 v4, 4, v12
	v_add3_u32 v2, v9, v3, v2
	v_or_b32_e32 v2, v2, v4
	v_ashrrev_i32_e32 v3, 31, v2
	v_lshlrev_b64 v[2:3], 6, v[2:3]
	v_lshlrev_b32_e32 v4, 2, v12
	v_and_or_b32 v2, v4, 32, v2
	v_or_b32_e32 v2, v2, v8
	v_lshl_add_u64 v[2:3], v[2:3], 4, s[24:25]
	v_lshlrev_b32_e32 v64, 1, v6
	v_lshl_add_u64 v[2:3], v[2:3], 0, v[64:65]
	global_store_dwordx2 v[2:3], v[0:1], off

.LBB0_1546:
	s_waitcnt vmcnt(10)
	v_cvt_pk_bf16_f32 v124, v0, v1
	v_cvt_pk_bf16_f32 v125, v2, v3
	v_cvt_pk_bf16_f32 v126, v4, v5
	v_cvt_pk_bf16_f32 v127, v6, v7
	s_waitcnt lgkmcnt(0)
	v_cvt_pk_bf16_f32 v180, v8, v9
	v_cvt_pk_bf16_f32 v181, v10, v11
	v_mfma_f32_32x32x16_bf16 v[32:47], v[124:127], v[104:107], v[32:47]
	v_cvt_pk_bf16_f32 v182, v12, v13
	v_cvt_pk_bf16_f32 v183, v14, v15
	v_mov_b32_e32 v191, v190
	v_mul_f32_e64 v14, v190, v14
	v_mul_f32_e64 v15, v191, v15
	v_mul_f32_e64 v12, v190, v12
	v_mul_f32_e64 v13, v191, v13
	v_mul_f32_e64 v10, v190, v10
	v_mul_f32_e64 v11, v191, v11
	v_mul_f32_e64 v8, v190, v8
	v_mul_f32_e64 v9, v191, v9
	v_mfma_f32_32x32x16_bf16 v[16:31], v[124:127], v[100:103], v[16:31]
	v_mul_f32_e64 v6, v190, v6
	v_mul_f32_e64 v7, v191, v7
	v_mul_f32_e64 v4, v190, v4
	v_mul_f32_e64 v5, v191, v5
	v_mul_f32_e64 v2, v190, v2
	v_mul_f32_e64 v3, v191, v3
	v_mul_f32_e64 v0, v196, v0
	v_mul_f32_e64 v1, v197, v1
	s_lshl_b32 s12, s12, 16
	v_add_u32_e32 v213, s12, v209
	v_add_u32_e32 v212, s12, v211
	v_mfma_f32_32x32x16_bf16 v[32:47], v[180:183], v[108:111], v[32:47]
	v_lshl_add_u64 v[204:205], s[56:57], 0, v[198:199]
	v_mfma_f32_32x32x16_bf16 v[16:31], v[180:183], v[96:99], v[16:31]
	s_nop 9
	ds_write_b128 v213, v[32:35]
	s_nop 0
	ds_write_b128 v213, v[16:19] offset:4096
	ds_write_b128 v213, v[36:39] offset:1024
	ds_write_b128 v213, v[20:23] offset:5120
	ds_write_b128 v213, v[40:43] offset:2048
	ds_write_b128 v213, v[24:27] offset:6144
	ds_write_b128 v213, v[44:47] offset:3072
	ds_write_b128 v213, v[28:31] offset:7168
	v_mfma_f32_32x32x16_bf16 v[0:15], v[72:75], v[176:179], v[0:15]
	s_waitcnt lgkmcnt(0)
	s_barrier
	ds_read_b128 v[16:19], v212
	ds_read_b128 v[20:23], v212 offset:8192
	ds_read_b128 v[24:27], v212 offset:16384
	s_waitcnt lgkmcnt(1)
	v_add_f32_e32 v20, v16, v20
	v_mfma_f32_32x32x16_bf16 v[0:15], v[60:63], v[172:175], v[0:15]
	v_add_f32_e32 v21, v17, v21
	v_add_f32_e32 v22, v18, v22
	v_add_f32_e32 v23, v19, v23
	ds_read_b128 v[16:19], v212 offset:24576
	s_waitcnt lgkmcnt(1)
	v_add_f32_e32 v20, v20, v24
	v_add_f32_e32 v21, v21, v25
	v_add_f32_e32 v24, v22, v26
	v_add_f32_e32 v25, v23, v27
	s_waitcnt lgkmcnt(0)
	v_add_f32_e32 v26, v20, v16
	v_add_f32_e32 v27, v21, v17
	ds_read_b128 v[20:23], v212 offset:32768
	v_add_f32_e32 v24, v24, v18
	v_add_f32_e32 v25, v25, v19
	ds_read_b128 v[16:19], v212 offset:40960
	v_mfma_f32_32x32x16_bf16 v[0:15], v[56:59], v[168:171], v[0:15]
	s_waitcnt lgkmcnt(1)
	v_add_f32_e32 v20, v26, v20
	v_add_f32_e32 v26, v27, v21
	v_add_f32_e32 v24, v24, v22
	v_add_f32_e32 v25, v25, v23
	s_waitcnt lgkmcnt(0)
	v_add_f32_e32 v27, v20, v16
	ds_read_b128 v[20:23], v212 offset:49152
	v_add_f32_e32 v26, v26, v17
	v_add_f32_e32 v24, v24, v18
	v_add_f32_e32 v25, v25, v19
	ds_read_b128 v[16:19], v212 offset:57344
	v_mfma_f32_32x32x16_bf16 v[0:15], v[48:51], v[116:119], v[0:15]
	s_waitcnt lgkmcnt(1)
	v_add_f32_e32 v21, v26, v21
	v_add_f32_e32 v23, v25, v23
	v_add_f32_e32 v20, v27, v20
	v_add_f32_e32 v22, v24, v22
	s_waitcnt lgkmcnt(0)
	v_add_f32_e32 v21, v21, v17
	v_add_f32_e32 v23, v23, v19
	v_add_f32_e32 v20, v20, v16
	v_add_f32_e32 v22, v22, v18
	v_mul_f32_e32 v16, v21, v21
	v_mul_f32_e32 v17, v23, v23
	v_add_co_u32_e32 v18, vcc, 0x17b10000, v204
	v_fmac_f32_e32 v16, v20, v20
	v_fmac_f32_e32 v17, v22, v22
	v_cvt_pk_bf16_f32 v20, v20, s0
	v_addc_co_u32_e32 v19, vcc, 0, v205, vcc
	v_add_f32_e32 v16, v16, v17
	global_store_short v[18:19], v20, off
	v_cvt_pk_bf16_f32 v20, v21, s0
	v_mov_b32_e32 v17, v16
	global_store_short v[18:19], v20, off offset:16
	v_cvt_pk_bf16_f32 v20, v22, s0
	v_cmp_lt_i32_e32 vcc, 47, v184
	v_permlane32_swap_b32_e32 v16, v17
	global_store_short v[18:19], v20, off offset:32
	v_cvt_pk_bf16_f32 v20, v23, s0
	s_and_b64 s[76:77], s[6:7], vcc
	global_store_short v[18:19], v20, off offset:48
	s_and_saveexec_b64 s[48:49], s[76:77]
	s_cbranch_execz .LBB0_1548
	v_add_f32_e32 v18, v16, v17
	v_lshl_add_u64 v[16:17], s[46:47], 0, v[184:185]
	v_lshlrev_b64 v[16:17], 10, v[16:17]
	v_lshl_add_u64 v[16:17], s[10:11], 0, v[16:17]
	s_lshl_b32 s12, s71, 2
	v_lshl_add_u64 v[16:17], v[16:17], 0, s[12:13]
	s_lshl_b32 s12, s72, 2
	v_lshl_add_u64 v[16:17], v[16:17], 0, s[12:13]
	s_lshl_b32 s12, s69, 2
	v_lshl_add_u64 v[16:17], v[16:17], 0, s[12:13]
	v_add_co_u32_e32 v16, vcc, 0xffff4000, v16
	s_nop 1
	v_addc_co_u32_e32 v17, vcc, -1, v17, vcc
	global_store_dword v[16:17], v18, off

.LBB0_1555:
	s_waitcnt vmcnt(23)
	v_cvt_pk_bf16_f32 v120, v0, v1
	v_cvt_pk_bf16_f32 v121, v2, v3
	v_cvt_pk_bf16_f32 v122, v4, v5
	v_cvt_pk_bf16_f32 v123, v6, v7
	s_waitcnt lgkmcnt(0)
	v_cvt_pk_bf16_f32 v180, v8, v9
	v_cvt_pk_bf16_f32 v181, v10, v11
	v_mfma_f32_32x32x16_bf16 v[32:47], v[120:123], v[88:91], v[32:47]
	v_cvt_pk_bf16_f32 v182, v12, v13
	v_cvt_pk_bf16_f32 v183, v14, v15
	v_mov_b32_e32 v191, v190
	v_mul_f32_e64 v14, v190, v14
	v_mul_f32_e64 v15, v191, v15
	v_mul_f32_e64 v12, v190, v12
	v_mul_f32_e64 v13, v191, v13
	v_mul_f32_e64 v10, v190, v10
	v_mul_f32_e64 v11, v191, v11
	v_mul_f32_e64 v8, v190, v8
	v_mul_f32_e64 v9, v191, v9
	v_mfma_f32_32x32x16_bf16 v[16:31], v[120:123], v[84:87], v[16:31]
	v_mul_f32_e64 v6, v190, v6
	v_mul_f32_e64 v7, v191, v7
	v_mul_f32_e64 v4, v190, v4
	v_mul_f32_e64 v5, v191, v5
	v_mul_f32_e64 v2, v190, v2
	v_mul_f32_e64 v3, v191, v3
	v_mul_f32_e64 v0, v196, v0
	v_mul_f32_e64 v1, v197, v1
	s_lshl_b32 s12, s12, 16
	v_add_u32_e32 v84, s12, v209
	v_mfma_f32_32x32x16_bf16 v[32:47], v[180:183], v[92:95], v[32:47]
	v_mfma_f32_32x32x16_bf16 v[16:31], v[180:183], v[80:83], v[16:31]
	s_nop 10
	ds_write_b128 v84, v[32:35]
	ds_write_b128 v84, v[16:19] offset:4096
	ds_write_b128 v84, v[36:39] offset:1024
	ds_write_b128 v84, v[20:23] offset:5120
	ds_write_b128 v84, v[40:43] offset:2048
	ds_write_b128 v84, v[24:27] offset:6144
	ds_write_b128 v84, v[44:47] offset:3072
	ds_write_b128 v84, v[28:31] offset:7168
	v_mfma_f32_32x32x16_bf16 v[0:15], v[76:79], v[176:179], v[0:15]
	v_add_u32_e32 v28, s12, v211
	s_waitcnt lgkmcnt(0)
	s_barrier
	ds_read_b128 v[16:19], v28
	ds_read_b128 v[20:23], v28 offset:8192
	ds_read_b128 v[24:27], v28 offset:16384
	s_waitcnt lgkmcnt(1)
	v_add_f32_e32 v20, v16, v20
	v_mfma_f32_32x32x16_bf16 v[0:15], v[68:71], v[172:175], v[0:15]
	v_add_f32_e32 v21, v17, v21
	v_add_f32_e32 v22, v18, v22
	v_add_f32_e32 v23, v19, v23
	ds_read_b128 v[16:19], v28 offset:24576
	s_waitcnt lgkmcnt(1)
	v_add_f32_e32 v20, v20, v24
	v_add_f32_e32 v21, v21, v25
	v_add_f32_e32 v24, v22, v26
	v_add_f32_e32 v25, v23, v27
	s_waitcnt lgkmcnt(0)
	v_add_f32_e32 v26, v20, v16
	v_add_f32_e32 v27, v21, v17
	ds_read_b128 v[20:23], v28 offset:32768
	v_add_f32_e32 v24, v24, v18
	v_add_f32_e32 v25, v25, v19
	ds_read_b128 v[16:19], v28 offset:40960
	v_mfma_f32_32x32x16_bf16 v[0:15], v[64:67], v[168:171], v[0:15]
	s_waitcnt lgkmcnt(1)
	v_add_f32_e32 v20, v26, v20
	v_add_f32_e32 v26, v27, v21
	v_add_f32_e32 v24, v24, v22
	v_add_f32_e32 v25, v25, v23
	s_waitcnt lgkmcnt(0)
	v_add_f32_e32 v27, v20, v16
	ds_read_b128 v[20:23], v28 offset:49152
	v_add_f32_e32 v26, v26, v17
	v_add_f32_e32 v24, v24, v18
	v_add_f32_e32 v25, v25, v19
	ds_read_b128 v[16:19], v28 offset:57344
	v_mfma_f32_32x32x16_bf16 v[0:15], v[52:55], v[112:115], v[0:15]
	s_waitcnt lgkmcnt(1)
	v_add_f32_e32 v21, v26, v21
	v_add_f32_e32 v23, v25, v23
	v_add_f32_e32 v20, v27, v20
	v_add_f32_e32 v22, v24, v22
	s_waitcnt lgkmcnt(0)
	v_add_f32_e32 v24, v21, v17
	v_add_f32_e32 v19, v23, v19
	v_add_f32_e32 v20, v20, v16
	v_add_f32_e32 v22, v22, v18
	v_mul_f32_e32 v17, v24, v24
	v_mul_f32_e32 v18, v19, v19
	v_fmac_f32_e32 v17, v20, v20
	v_fmac_f32_e32 v18, v22, v22
	v_cvt_pk_bf16_f32 v23, v20, s0
	v_add_co_u32_e32 v20, vcc, 0x17c10000, v204
	v_add_u32_e32 v16, 64, v184
	v_add_f32_e32 v17, v17, v18
	v_addc_co_u32_e32 v21, vcc, 0, v205, vcc
	v_mov_b32_e32 v18, v17
	v_cmp_lt_i32_e32 vcc, 47, v16
	s_nop 0
	v_permlane32_swap_b32_e32 v17, v18
	global_store_short v[20:21], v23, off
	v_cvt_pk_bf16_f32 v23, v24, s0
	v_cvt_pk_bf16_f32 v22, v22, s0
	v_cvt_pk_bf16_f32 v19, v19, s0
	s_and_b64 s[76:77], s[6:7], vcc
	global_store_short v[20:21], v23, off offset:16
	global_store_short v[20:21], v22, off offset:32
	global_store_short v[20:21], v19, off offset:48
	s_and_saveexec_b64 s[48:49], s[76:77]
	s_cbranch_execz .LBB0_1557
	v_add_f32_e32 v18, v17, v18
	v_mov_b32_e32 v17, v185
	v_lshl_add_u64 v[16:17], s[46:47], 0, v[16:17]
	v_lshlrev_b64 v[16:17], 10, v[16:17]
	v_lshl_add_u64 v[16:17], s[10:11], 0, v[16:17]
	s_lshl_b32 s12, s71, 2
	v_lshl_add_u64 v[16:17], v[16:17], 0, s[12:13]
	s_lshl_b32 s12, s72, 2
	v_lshl_add_u64 v[16:17], v[16:17], 0, s[12:13]
	s_lshl_b32 s12, s69, 2
	v_lshl_add_u64 v[16:17], v[16:17], 0, s[12:13]
	v_add_co_u32_e32 v16, vcc, 0xffff4000, v16
	s_nop 1
	v_addc_co_u32_e32 v17, vcc, -1, v17, vcc
	global_store_dword v[16:17], v18, off

; DI void scan_block(const Params& p, const int u) {
;     ...
;     for (int c3 = 0; c3 < NCH; c3 += 3) {
;         SCAN_STEP(c3, kaA, qA, sA, kaC, qC, sC);
;         SCAN_STEP(c3 + 1, kaB, qB, sB, kaA, qA, sA);
;         SCAN_STEP(c3 + 2, kaC, qC, sC, kaB, qB, sB);
;     }
.LBB0_1564:
	s_waitcnt vmcnt(27)
	v_cvt_pk_bf16_f32 v160, v0, v1
	v_cvt_pk_bf16_f32 v161, v2, v3
	v_cvt_pk_bf16_f32 v162, v4, v5
	v_cvt_pk_bf16_f32 v163, v6, v7
	s_waitcnt lgkmcnt(0)
	v_cvt_pk_bf16_f32 v180, v8, v9
	v_cvt_pk_bf16_f32 v181, v10, v11
	v_mfma_f32_32x32x16_bf16 v[32:47], v[160:163], v[156:159], v[32:47]
	v_cvt_pk_bf16_f32 v182, v12, v13
	v_cvt_pk_bf16_f32 v183, v14, v15
	v_mov_b32_e32 v191, v190
	v_mul_f32_e64 v14, v190, v14
	v_mul_f32_e64 v15, v191, v15
	v_mul_f32_e64 v12, v190, v12
	v_mul_f32_e64 v13, v191, v13
	v_mul_f32_e64 v10, v190, v10
	v_mul_f32_e64 v11, v191, v11
	v_mul_f32_e64 v8, v190, v8
	v_mul_f32_e64 v9, v191, v9
	v_mfma_f32_32x32x16_bf16 v[16:31], v[160:163], v[148:151], v[16:31]
	v_mul_f32_e64 v6, v190, v6
	v_mul_f32_e64 v7, v191, v7
	v_mul_f32_e64 v4, v190, v4
	v_mul_f32_e64 v5, v191, v5
	v_mul_f32_e64 v2, v190, v2
	v_mul_f32_e64 v3, v191, v3
	v_mul_f32_e64 v0, v196, v0
	v_mul_f32_e64 v1, v197, v1
	v_mfma_f32_32x32x16_bf16 v[32:47], v[180:183], v[152:155], v[32:47]
	v_mfma_f32_32x32x16_bf16 v[16:31], v[180:183], v[144:147], v[16:31]
	s_nop 10
	ds_write_b128 v213, v[32:35]
	ds_write_b128 v213, v[16:19] offset:4096
	ds_write_b128 v213, v[36:39] offset:1024
	ds_write_b128 v213, v[20:23] offset:5120
	ds_write_b128 v213, v[40:43] offset:2048
	ds_write_b128 v213, v[24:27] offset:6144
	ds_write_b128 v213, v[44:47] offset:3072
	ds_write_b128 v213, v[28:31] offset:7168
	v_mfma_f32_32x32x16_bf16 v[0:15], v[140:143], v[176:179], v[0:15]
	s_waitcnt lgkmcnt(0)
	s_barrier
	ds_read_b128 v[16:19], v212
	ds_read_b128 v[20:23], v212 offset:8192
	ds_read_b128 v[24:27], v212 offset:16384
	s_waitcnt lgkmcnt(1)
	v_add_f32_e32 v20, v16, v20
	v_mfma_f32_32x32x16_bf16 v[0:15], v[136:139], v[172:175], v[0:15]
	v_add_f32_e32 v21, v17, v21
	v_add_f32_e32 v22, v18, v22
	v_add_f32_e32 v23, v19, v23
	ds_read_b128 v[16:19], v212 offset:24576
	s_waitcnt lgkmcnt(1)
	v_add_f32_e32 v20, v20, v24
	v_add_f32_e32 v24, v21, v25
	v_add_f32_e32 v25, v22, v26
	v_add_f32_e32 v26, v23, v27
	s_waitcnt lgkmcnt(0)
	v_add_f32_e32 v27, v20, v16
	ds_read_b128 v[20:23], v212 offset:32768
	v_add_f32_e32 v24, v24, v17
	v_add_f32_e32 v25, v25, v18
	v_add_f32_e32 v26, v26, v19
	ds_read_b128 v[16:19], v212 offset:40960
	v_mfma_f32_32x32x16_bf16 v[0:15], v[132:135], v[168:171], v[0:15]
	s_waitcnt lgkmcnt(1)
	v_add_f32_e32 v20, v27, v20
	v_add_f32_e32 v24, v24, v21
	v_add_f32_e32 v25, v25, v22
	v_add_f32_e32 v26, v26, v23
	s_waitcnt lgkmcnt(0)
	v_add_f32_e32 v27, v20, v16
	ds_read_b128 v[20:23], v212 offset:49152
	v_add_f32_e32 v24, v24, v17
	v_add_f32_e32 v25, v25, v18
	v_add_f32_e32 v26, v26, v19
	ds_read_b128 v[16:19], v212 offset:57344
	v_mfma_f32_32x32x16_bf16 v[0:15], v[128:131], v[164:167], v[0:15]
	s_waitcnt lgkmcnt(1)
	v_add_f32_e32 v21, v24, v21
	v_add_f32_e32 v23, v26, v23
	v_add_f32_e32 v20, v27, v20
	v_add_f32_e32 v22, v25, v22
	s_waitcnt lgkmcnt(0)
	v_add_f32_e32 v24, v21, v17
	v_add_f32_e32 v19, v23, v19
	v_add_f32_e32 v20, v20, v16
	v_add_f32_e32 v22, v22, v18
	v_mul_f32_e32 v17, v24, v24
	v_mul_f32_e32 v18, v19, v19
	v_fmac_f32_e32 v17, v20, v20
	v_fmac_f32_e32 v18, v22, v22
	v_cvt_pk_bf16_f32 v23, v20, s0
	v_add_co_u32_e32 v20, vcc, 0x17d10000, v204
	v_add_u32_e32 v16, 0x80, v184
	v_add_f32_e32 v17, v17, v18
	v_addc_co_u32_e32 v21, vcc, 0, v205, vcc
	v_mov_b32_e32 v18, v17
	v_cmp_lt_i32_e32 vcc, 47, v16
	s_nop 0
	v_permlane32_swap_b32_e32 v17, v18
	global_store_short v[20:21], v23, off
	v_cvt_pk_bf16_f32 v23, v24, s0
	v_cvt_pk_bf16_f32 v22, v22, s0
	v_cvt_pk_bf16_f32 v19, v19, s0
	s_and_b64 s[48:49], s[6:7], vcc
	global_store_short v[20:21], v23, off offset:16
	global_store_short v[20:21], v22, off offset:32
	global_store_short v[20:21], v19, off offset:48
	s_and_saveexec_b64 s[8:9], s[48:49]
	s_cbranch_execz .LBB0_1538
	v_add_f32_e32 v18, v17, v18
	v_mov_b32_e32 v17, v185
	v_lshl_add_u64 v[16:17], s[46:47], 0, v[16:17]
	v_lshlrev_b64 v[16:17], 10, v[16:17]
	v_lshl_add_u64 v[16:17], s[10:11], 0, v[16:17]
	s_lshl_b32 s12, s71, 2
	v_lshl_add_u64 v[16:17], v[16:17], 0, s[12:13]
	s_lshl_b32 s12, s72, 2
	v_lshl_add_u64 v[16:17], v[16:17], 0, s[12:13]
	s_lshl_b32 s12, s69, 2
	v_lshl_add_u64 v[16:17], v[16:17], 0, s[12:13]
	v_add_co_u32_e32 v16, vcc, 0xffff4000, v16
	s_nop 1
	v_addc_co_u32_e32 v17, vcc, -1, v17, vcc
	global_store_dword v[16:17], v18, off
	s_branch .LBB0_1538

; DI int opaque_tid() { int t = threadIdx.x; asm volatile("" : "+v"(t)); return t; }
; template <int EPI, int K, int LNI = -1>
; DI void ph_gemm(const Params& p, const bf16_t* __restrict__ A, const bf16_t* __restrict__ Bt, int N, float* s_aux) {
;     ...
;         if (EPI == EPI_E5B) {
;             if (opaque_tid() < 256) {
;                 const int row = brow + (int)opaque_tid(); const int hd = bcol >> 9;
;                 const float* pp = (const float*)((unsigned char*)p.out + OFFO_PART) + (size_t)row * 256 + hd * 64;
;                 float sacc = 0.f;
; #pragma unroll
;                 for (int i = 0; i < 16; ++i) { const f32x4 v = *(const f32x4*)(pp + i * 4); sacc += (v[0] + v[1]) + (v[2] + v[3]); }
;                 sa[opaque_tid()] = __frsqrt_rn(sacc * (1.0f / 512.0f) + 1e-6f);
;             }
.LBB0_1633:
	s_lshl_b32 s11, s35, 11
	s_and_b32 s11, s11, 0x800
	s_add_i32 s11, s11, 0
	v_mov_b32_e32 v0, v210
	s_lshl_b32 s42, s52, 8
	s_add_i32 s11, s11, 0x20000
	s_nop 0
	v_cmp_gt_i32_e32 vcc, s60, v0
	s_and_saveexec_b64 s[48:49], vcc
	s_cbranch_execz .LBB0_1635
	v_mov_b32_e32 v0, v210
	s_lshl_b32 s43, s10, 5
	v_add_u32_e32 v0, s42, v0
	v_ashrrev_i32_e32 v1, 31, v0
	v_lshlrev_b64 v[0:1], 10, v[0:1]
	s_and_b32 s50, s43, 0xffffffc0
	v_lshl_add_u64 v[0:1], s[24:25], 0, v[0:1]
	s_ashr_i32 s51, s50, 31
	s_waitcnt vmcnt(0)
	v_lshl_add_u64 v[60:61], s[50:51], 2, v[0:1]
	global_load_dwordx4 v[0:3], v[60:61], off
	global_load_dwordx4 v[4:7], v[60:61], off offset:16
	global_load_dwordx4 v[8:11], v[60:61], off offset:32
	global_load_dwordx4 v[12:15], v[60:61], off offset:48
	global_load_dwordx4 v[16:19], v[60:61], off offset:64
	global_load_dwordx4 v[20:23], v[60:61], off offset:80
	global_load_dwordx4 v[24:27], v[60:61], off offset:96
	global_load_dwordx4 v[28:31], v[60:61], off offset:112
	global_load_dwordx4 v[32:35], v[60:61], off offset:128
	global_load_dwordx4 v[36:39], v[60:61], off offset:144
	global_load_dwordx4 v[40:43], v[60:61], off offset:160
	global_load_dwordx4 v[44:47], v[60:61], off offset:176
	global_load_dwordx4 v[48:51], v[60:61], off offset:192
	global_load_dwordx4 v[52:55], v[60:61], off offset:208
	global_load_dwordx4 v[56:59], v[60:61], off offset:224
	s_nop 0
	global_load_dwordx4 v[60:63], v[60:61], off offset:240
	s_waitcnt vmcnt(0)
	v_mov_b32_e32 v64, v1
	v_mov_b32_e32 v65, v2
	v_mov_b32_e32 v1, v3
	v_mov_b32_e32 v2, v5
	v_mov_b32_e32 v3, v6
	v_mov_b32_e32 v5, v7
	v_add_f32_e64 v0, v64, v0
	v_add_f32_e64 v1, v65, v1
	v_add_f32_e64 v2, v2, v4
	v_add_f32_e64 v3, v3, v5
	v_add_f32_e32 v6, v8, v9
	v_add_f32_e32 v8, v10, v11
	v_add_f32_e32 v10, v0, v1
	v_add_f32_e64 v0, v2, v3
	v_add_f32_e64 v1, v3, v2
	v_mov_b32_e32 v11, v12
	v_mov_b32_e32 v7, v14
	v_mov_b32_e32 v9, v15
	v_add_f32_e32 v10, 0, v10
	v_mov_b32_e32 v1, v13
	v_mov_b32_e32 v14, v17
	v_mov_b32_e32 v15, v18
	v_mov_b32_e32 v17, v19
	v_add_f32_e64 v4, v6, v8
	v_add_f32_e64 v5, v7, v9
	v_add_f32_e64 v0, v10, v0
	v_add_f32_e64 v1, v11, v1
	v_add_f32_e64 v6, v14, v16
	v_add_f32_e64 v7, v15, v17
	v_add_f32_e64 v0, v0, v4
	v_add_f32_e64 v1, v1, v5
	v_add_f32_e64 v2, v6, v7
	v_add_f32_e64 v3, v7, v6
	v_pk_add_f32 v[0:1], v[0:1], v[0:1] op_sel:[0,1] op_sel_hi:[1,0]
	v_add_f32_e32 v18, v20, v21
	v_add_f32_e32 v20, v22, v23
	v_mov_b32_e32 v19, v26
	v_mov_b32_e32 v21, v27
	v_mov_b32_e32 v3, v25
	v_mov_b32_e32 v1, v24
	v_mov_b32_e32 v22, v29
	v_mov_b32_e32 v23, v30
	v_mov_b32_e32 v29, v31
	v_add_f32_e64 v8, v18, v20
	v_add_f32_e64 v9, v19, v21
	v_add_f32_e64 v0, v0, v2
	v_add_f32_e64 v1, v1, v3
	v_add_f32_e64 v14, v22, v28
	v_add_f32_e64 v15, v23, v29
	v_add_f32_e64 v0, v0, v8
	v_add_f32_e64 v1, v1, v9
	v_add_f32_e64 v6, v14, v15
	v_add_f32_e64 v7, v15, v14
	v_pk_add_f32 v[0:1], v[0:1], v[0:1] op_sel:[0,1] op_sel_hi:[1,0]
	v_add_f32_e32 v26, v32, v33
	v_add_f32_e32 v30, v34, v35
	v_mov_b32_e32 v27, v38
	v_mov_b32_e32 v31, v39
	v_mov_b32_e32 v7, v37
	v_mov_b32_e32 v1, v36
	v_mov_b32_e32 v32, v41
	v_mov_b32_e32 v33, v42
	v_mov_b32_e32 v41, v43
	v_add_f32_e64 v16, v26, v30
	v_add_f32_e64 v17, v27, v31
	v_add_f32_e64 v0, v0, v6
	v_add_f32_e64 v1, v1, v7
	v_add_f32_e64 v18, v32, v40
	v_add_f32_e64 v19, v33, v41
	v_add_f32_e64 v0, v0, v16
	v_add_f32_e64 v1, v1, v17
	v_add_f32_e64 v14, v18, v19
	v_add_f32_e64 v15, v19, v18
	v_pk_add_f32 v[0:1], v[0:1], v[0:1] op_sel:[0,1] op_sel_hi:[1,0]
	v_add_f32_e32 v34, v44, v45
	v_add_f32_e32 v38, v46, v47
	v_mov_b32_e32 v35, v50
	v_mov_b32_e32 v39, v51
	v_mov_b32_e32 v15, v49
	v_mov_b32_e32 v1, v48
	v_mov_b32_e32 v42, v53
	v_mov_b32_e32 v43, v54
	v_mov_b32_e32 v53, v55
	v_add_f32_e64 v20, v34, v38
	v_add_f32_e64 v21, v35, v39
	v_add_f32_e64 v0, v0, v14
	v_add_f32_e64 v1, v1, v15
	v_add_f32_e64 v22, v42, v52
	v_add_f32_e64 v23, v43, v53
	v_add_f32_e64 v0, v0, v20
	v_add_f32_e64 v1, v1, v21
	v_add_f32_e64 v18, v22, v23
	v_add_f32_e64 v19, v23, v22
	v_pk_add_f32 v[0:1], v[0:1], v[0:1] op_sel:[0,1] op_sel_hi:[1,0]
	v_add_f32_e32 v44, v56, v57
	v_add_f32_e32 v46, v58, v59
	v_mov_b32_e32 v45, v62
	v_mov_b32_e32 v47, v63
	v_mov_b32_e32 v19, v61
	v_mov_b32_e32 v1, v60
	v_add_f32_e64 v0, v0, v18
	v_add_f32_e64 v1, v1, v19
	v_add_f32_e64 v2, v44, v46
	v_add_f32_e64 v3, v45, v47
	s_nop 0
	v_add_f32_e64 v0, v0, v2
	v_add_f32_e64 v1, v1, v3
	s_nop 0
	v_add_f32_e32 v0, v0, v1
	v_fmamk_f32 v0, v0, 0x3b000000, v182
	v_rsq_f32_e32 v0, v0
	v_mov_b32_e32 v1, v210
	s_nop 0
	v_lshl_add_u32 v1, v1, 2, s11
	ds_write_b32 v1, v0

; template <int EPI, int K, int LNI>
; DI void gemm_tail_unit(const Params& p, const bf16_t* __restrict__ A, const bf16_t* __restrict__ Bt, const int un, float* s_aux) {
;     ...
;     if (EPI == EPI_E5B) {
;         if (tid < 64) {
;             const int hd = col0 >> 9;
;             const float* pp = (const float*)((unsigned char*)p.out + OFFO_PART) + (size_t)(ROW0 + tid) * 256 + hd * 64;
;             float sacc = 0.f;
; #pragma unroll
;             for (int i = 0; i < 16; ++i) { const f32x4 v = *(const f32x4*)(pp + i * 4); sacc += (v[0] + v[1]) + (v[2] + v[3]); }
;             s_aux[tid] = __frsqrt_rn(sacc * (1.0f / 512.0f) + 1e-6f);
;         }
.LBB0_1645:
	v_mov_b32_e32 v66, v210
	s_nop 0
	v_cmp_lt_i32_e32 vcc, 63, v66
	s_and_saveexec_b64 s[10:11], vcc
	s_xor_b64 s[10:11], exec, s[10:11]
	s_and_b32 s12, s44, 0xffffffc0
	s_or_saveexec_b64 s[10:11], s[10:11]
	v_mov_b32_e32 v69, s12
	s_xor_b64 exec, exec, s[10:11]
	s_cbranch_execz .LBB0_1644
	v_ashrrev_i32_e32 v67, 31, v66
	v_lshlrev_b64 v[0:1], 10, v[66:67]
	s_and_b32 s12, s44, 0xffffffc0
	v_lshl_add_u64 v[0:1], s[24:25], 0, v[0:1]
	s_ashr_i32 s13, s12, 31
	v_lshl_add_u64 v[56:57], s[12:13], 2, v[0:1]
	v_lshl_add_u64 v[60:61], v[56:57], 0, s[6:7]
	v_add_co_u32_e32 v56, vcc, 0x2000000, v56
	global_load_dwordx4 v[0:3], v[60:61], off offset:16
	global_load_dwordx4 v[4:7], v[60:61], off offset:32
	global_load_dwordx4 v[8:11], v[60:61], off offset:48
	global_load_dwordx4 v[12:15], v[60:61], off offset:64
	global_load_dwordx4 v[16:19], v[60:61], off offset:80
	global_load_dwordx4 v[20:23], v[60:61], off offset:96
	global_load_dwordx4 v[24:27], v[60:61], off offset:112
	global_load_dwordx4 v[28:31], v[60:61], off offset:128
	global_load_dwordx4 v[32:35], v[60:61], off offset:144
	global_load_dwordx4 v[36:39], v[60:61], off offset:160
	global_load_dwordx4 v[40:43], v[60:61], off offset:176
	global_load_dwordx4 v[44:47], v[60:61], off offset:192
	global_load_dwordx4 v[48:51], v[60:61], off offset:224
	global_load_dwordx4 v[52:55], v[60:61], off offset:208
	v_addc_co_u32_e32 v57, vcc, 0, v57, vcc
	global_load_dwordx4 v[56:59], v[56:57], off
	s_nop 0
	global_load_dwordx4 v[60:63], v[60:61], off offset:240
	v_mov_b32_e32 v69, s12
	s_waitcnt vmcnt(15)
	v_mov_b32_e32 v70, v1
	v_mov_b32_e32 v71, v2
	v_mov_b32_e32 v1, v3
	s_waitcnt vmcnt(14)
	v_add_f32_e32 v2, v4, v5
	v_add_f32_e32 v4, v6, v7
	s_waitcnt vmcnt(13)
	v_mov_b32_e32 v3, v10
	v_mov_b32_e32 v5, v11
	s_waitcnt vmcnt(12)
	v_mov_b32_e32 v10, v13
	v_mov_b32_e32 v11, v14
	v_mov_b32_e32 v13, v15
	s_waitcnt vmcnt(11)
	v_add_f32_e32 v14, v16, v17
	v_add_f32_e32 v16, v18, v19
	s_waitcnt vmcnt(9)
	v_mov_b32_e32 v18, v25
	v_mov_b32_e32 v19, v26
	v_mov_b32_e32 v25, v27
	s_waitcnt vmcnt(8)
	v_add_f32_e32 v26, v30, v31
	s_waitcnt vmcnt(7)
	v_mov_b32_e32 v27, v35
	s_waitcnt vmcnt(4)
	v_mov_b32_e32 v31, v46
	v_mov_b32_e32 v35, v47
	s_waitcnt vmcnt(1)
	v_mov_b32_e32 v46, v57
	v_mov_b32_e32 v47, v58
	v_mov_b32_e32 v57, v59
	v_add_f32_e64 v0, v70, v0
	v_add_f32_e64 v1, v71, v1
	v_add_f32_e64 v2, v2, v4
	v_add_f32_e64 v3, v3, v5
	v_add_f32_e64 v4, v10, v12
	v_add_f32_e64 v5, v11, v13
	v_add_f32_e64 v12, v18, v24
	v_add_f32_e64 v13, v19, v25
	v_add_f32_e64 v24, v46, v56
	v_add_f32_e64 v25, v47, v57
	v_pk_add_f32 v[0:1], v[0:1], v[0:1] op_sel:[0,1] op_sel_hi:[1,0]
	v_add_f32_e32 v6, v24, v25
	v_mov_b32_e32 v7, v8
	v_mov_b32_e32 v1, v9
	v_add_f32_e32 v6, 0, v6
	v_add_f32_e64 v0, v6, v0
	v_add_f32_e64 v1, v7, v1
	v_pk_add_f32 v[4:5], v[4:5], v[4:5] op_sel:[0,1] op_sel_hi:[1,0]
	v_add_f32_e64 v0, v0, v2
	v_add_f32_e64 v1, v1, v3
	v_mov_b32_e32 v15, v22
	v_pk_add_f32 v[0:1], v[0:1], v[0:1] op_sel:[0,1] op_sel_hi:[1,0]
	v_mov_b32_e32 v17, v23
	v_mov_b32_e32 v5, v21
	v_mov_b32_e32 v1, v20
	v_add_f32_e64 v10, v14, v16
	v_add_f32_e64 v11, v15, v17
	v_add_f32_e64 v0, v0, v4
	v_add_f32_e64 v1, v1, v5
	v_pk_add_f32 v[12:13], v[12:13], v[12:13] op_sel:[0,1] op_sel_hi:[1,0]
	v_add_f32_e64 v0, v0, v10
	v_add_f32_e64 v1, v1, v11
	v_add_f32_e32 v22, v28, v29
	v_pk_add_f32 v[0:1], v[0:1], v[0:1] op_sel:[0,1] op_sel_hi:[1,0]
	v_mov_b32_e32 v23, v34
	v_mov_b32_e32 v13, v33
	v_mov_b32_e32 v1, v32
	v_mov_b32_e32 v28, v37
	v_mov_b32_e32 v29, v38
	v_mov_b32_e32 v37, v39
	v_add_f32_e64 v14, v22, v26
	v_add_f32_e64 v15, v23, v27
	v_add_f32_e64 v0, v0, v12
	v_add_f32_e64 v1, v1, v13
	v_add_f32_e64 v16, v28, v36
	v_add_f32_e64 v17, v29, v37
	v_add_f32_e64 v0, v0, v14
	v_add_f32_e64 v1, v1, v15
	v_pk_add_f32 v[16:17], v[16:17], v[16:17] op_sel:[0,1] op_sel_hi:[1,0]
	v_pk_add_f32 v[0:1], v[0:1], v[0:1] op_sel:[0,1] op_sel_hi:[1,0]
	v_add_f32_e32 v30, v40, v41
	v_add_f32_e32 v34, v42, v43
	v_mov_b32_e32 v17, v45
	v_mov_b32_e32 v1, v44
	v_mov_b32_e32 v38, v53
	v_mov_b32_e32 v39, v54
	v_mov_b32_e32 v53, v55
	v_add_f32_e64 v18, v30, v34
	v_add_f32_e64 v19, v31, v35
	v_add_f32_e64 v0, v0, v16
	v_add_f32_e64 v1, v1, v17
	v_add_f32_e64 v22, v38, v52
	v_add_f32_e64 v23, v39, v53
	v_add_f32_e64 v0, v0, v18
	v_add_f32_e64 v1, v1, v19
	v_pk_add_f32 v[22:23], v[22:23], v[22:23] op_sel:[0,1] op_sel_hi:[1,0]
	v_pk_add_f32 v[0:1], v[0:1], v[0:1] op_sel:[0,1] op_sel_hi:[1,0]
	v_add_f32_e32 v40, v48, v49
	v_add_f32_e32 v42, v50, v51
	s_waitcnt vmcnt(0)
	v_mov_b32_e32 v41, v62
	v_mov_b32_e32 v43, v63
	v_mov_b32_e32 v23, v61
	v_mov_b32_e32 v1, v60
	v_add_f32_e64 v26, v40, v42
	v_add_f32_e64 v27, v41, v43
	v_add_f32_e64 v0, v0, v22
	v_add_f32_e64 v1, v1, v23
	s_nop 0
	v_add_f32_e64 v0, v0, v26
	v_add_f32_e64 v1, v1, v27
	s_nop 0
	v_add_f32_e32 v0, v0, v1
	v_fmamk_f32 v0, v0, 0x3b000000, v68
	v_rsq_f32_e32 v0, v0
	v_lshl_add_u32 v1, v66, 2, 0
	v_add_u32_e32 v1, 0x20000, v1
	ds_write_b32 v1, v0
	s_branch .LBB0_1644
